# v15 + back-edge rotation in the 8 GEMM K-loops: loop-carried SALU block (counter, base bumps, exit compare) moved in front of the loop-back barrier
# baseline (speedup 1.0000x reference)
; #define PG8_STAGE(bufoff, gbase, voff) do { _Pragma("unroll") for (int _i = 0; _i < 2; ++_i) \
;         __builtin_amdgcn_global_load_lds((const unsigned*)((const char*)(gbase) + (voff)[_i]), (PG8_LAS unsigned*)(lds + (bufoff) + ldsw + _i * 8192), 16, 0, 0); } while (0)
; #define PG8_LDA(dst, b, h) do { _Pragma("unroll") for (int m = 0; m < 4; ++m) _Pragma("unroll") for (int k = 0; k < 2; ++k) dst[m][k] = *(const PG8_LAS bf16x8*)(lds + PG8_SA(b, h) + aoff + m * 2048 + k * 1024); } while (0)
; #define PG8_LDB(dst, b, h) do { _Pragma("unroll") for (int n = 0; n < 2; ++n) _Pragma("unroll") for (int k = 0; k < 2; ++k) dst[n][k] = *(const PG8_LAS bf16x8*)(lds + PG8_SB(b, h) + boff + n * 2048 + k * 1024); } while (0)
; #define PG8_MMA(ai, bj, At, Bt) do { __builtin_amdgcn_s_setprio(1); _Pragma("unroll") for (int m = 0; m < 4; ++m) _Pragma("unroll") for (int n = 0; n < 2; ++n) _Pragma("unroll") for (int k = 0; k < 2; ++k) \
;         acc[ai][bj][m][n] = __builtin_amdgcn_mfma_f32_16x16x32_bf16(Bt[n][k], At[m][k], acc[ai][bj][m][n], 0, 0, 0); __builtin_amdgcn_s_setprio(0); } while (0)
; #define PG8_WAIT_V(n) asm volatile("s_waitcnt vmcnt(" #n ")" ::: "memory")
; #define PG8_WAIT_L(n) asm volatile("s_waitcnt lgkmcnt(" #n ")" ::: "memory")
; #define PG8_BAR __builtin_amdgcn_s_barrier()
; template <class Epi, class Sched, bool ALIGN_EPI = false, bool SP2 = false>
; __device__ __forceinline__ void gemm_phase(PG8_LAS unsigned char* lds, const Gemm g, const Sched& S, const Epi& E, const int wid  ) {
;     ...
;         for (int t = 0; t < nt; t += 2) {
;             const bool last = (t == nt - 2);
;             const char* a1 = cA + (size_t)(t + 1) * kstep;
;             const char* a2 = last ? nA : cA + (size_t)(t + 2) * kstep; const char* b2 = last ? nB : cB + (size_t)(t + 2) * kstep;
;             const char* a3 = a2 + kstep; const char* b3 = b2 + kstep;
;             if (last && has_next) S.a_ready(nxt);
;             if constexpr (SP2) {
;             PG8_LDB(B0, 0, 0); PG8_LDB(B1, 0, 1); PG8_SCHED; PG8_LDA(At, 0, 0); PG8_STAGE(PG8_SA(1, 1), a1 + hstep, voffA);
;             PG8_WAIT_V(8); PG8_WAIT_L(0); PG8_BAR; PG8_MMA(0, 0, At, B0); PG8_MMA(0, 1, At, B1); PG8_BAR; PG8_SCHED;
;             PG8_LDA(At, 0, 1); PG8_STAGE(PG8_SB(0, 0), b2, voffB); PG8_STAGE(PG8_SB(0, 1), b2 + hstep, voffB); PG8_STAGE(PG8_SA(0, 0), a2, voffA);
.LBB0_230:
	s_add_u32 s100, s10, 0xfff80000
	s_addc_u32 s101, s11, -1
	ds_read_b128 v[68:71], v185
	ds_read_b128 v[76:79], v185 offset:1024
	ds_read_b128 v[80:83], v185 offset:2048
	ds_read_b128 v[88:91], v185 offset:3072
	ds_read_b128 v[160:163], v186
	ds_read_b128 v[164:167], v186 offset:1024
	ds_read_b128 v[168:171], v186 offset:2048
	ds_read_b128 v[190:193], v186 offset:3072
	s_add_u32 s47, s10, 0xfff80080
	s_addc_u32 s52, s11, -1
	s_cmp_eq_u32 s45, 28
	s_cselect_b32 s55, s7, s52
	s_cselect_b32 s54, s9, s47
	s_cselect_b32 s53, s30, s35
	s_cselect_b32 s52, s31, s34
	v_lshl_add_u64 v[228:229], s[100:101], 0, v[152:153]
	s_mov_b32 m0, s62
	v_lshl_add_u64 v[230:231], s[100:101], 0, v[154:155]
	global_load_lds_dwordx4 v[228:229], off
	s_mov_b32 m0, s63
	s_nop 0
	global_load_lds_dwordx4 v[230:231], off
	v_lshl_add_u64 v[172:173], s[10:11], 0, v[152:153]
	s_add_i32 m0, s37, 0xc000
	ds_read_b128 v[194:197], v187
	ds_read_b128 v[198:201], v187 offset:1024
	ds_read_b128 v[202:205], v187 offset:2048
	ds_read_b128 v[206:209], v187 offset:3072
	ds_read_b128 v[210:213], v187 offset:4096
	ds_read_b128 v[214:217], v187 offset:5120
	ds_read_b128 v[218:221], v187 offset:6144
	ds_read_b128 v[222:225], v187 offset:7168
	global_load_lds_dwordx4 v[172:173], off
	v_lshl_add_u64 v[172:173], s[10:11], 0, v[154:155]
	s_add_i32 m0, s37, 0xe000
	s_nop 0
	global_load_lds_dwordx4 v[172:173], off
	s_waitcnt vmcnt(8)
	s_waitcnt lgkmcnt(0)
	s_barrier
	s_setprio 1
	s_waitcnt lgkmcnt(0)
	v_mfma_f32_16x16x32_bf16 v[140:143], v[68:71], v[194:197], v[140:143]
	v_mfma_f32_16x16x32_bf16 v[136:139], v[80:83], v[194:197], v[136:139]
	v_mfma_f32_16x16x32_bf16 v[124:127], v[68:71], v[202:205], v[124:127]
	v_mfma_f32_16x16x32_bf16 v[120:123], v[80:83], v[202:205], v[120:123]
	v_mfma_f32_16x16x32_bf16 v[108:111], v[68:71], v[210:213], v[108:111]
	v_mfma_f32_16x16x32_bf16 v[104:107], v[80:83], v[210:213], v[104:107]
	v_mfma_f32_16x16x32_bf16 v[92:95], v[68:71], v[218:221], v[92:95]
	v_mfma_f32_16x16x32_bf16 v[84:87], v[80:83], v[218:221], v[84:87]
	v_mfma_f32_16x16x32_bf16 v[140:143], v[76:79], v[198:201], v[140:143]
	v_mfma_f32_16x16x32_bf16 v[136:139], v[88:91], v[198:201], v[136:139]
	v_mfma_f32_16x16x32_bf16 v[124:127], v[76:79], v[206:209], v[124:127]
	v_mfma_f32_16x16x32_bf16 v[120:123], v[88:91], v[206:209], v[120:123]
	v_mfma_f32_16x16x32_bf16 v[108:111], v[76:79], v[214:217], v[108:111]
	v_mfma_f32_16x16x32_bf16 v[104:107], v[88:91], v[214:217], v[104:107]
	v_mfma_f32_16x16x32_bf16 v[92:95], v[76:79], v[222:225], v[92:95]
	v_mfma_f32_16x16x32_bf16 v[84:87], v[88:91], v[222:225], v[84:87]
	s_setprio 0
	s_setprio 1
	v_mfma_f32_16x16x32_bf16 v[132:135], v[160:163], v[194:197], v[132:135]
	v_mfma_f32_16x16x32_bf16 v[128:131], v[168:171], v[194:197], v[128:131]
	v_mfma_f32_16x16x32_bf16 v[116:119], v[160:163], v[202:205], v[116:119]
	v_mfma_f32_16x16x32_bf16 v[112:115], v[168:171], v[202:205], v[112:115]
	v_mfma_f32_16x16x32_bf16 v[100:103], v[160:163], v[210:213], v[100:103]
	v_mfma_f32_16x16x32_bf16 v[96:99], v[168:171], v[210:213], v[96:99]
	v_mfma_f32_16x16x32_bf16 v[72:75], v[160:163], v[218:221], v[72:75]
	v_mfma_f32_16x16x32_bf16 v[64:67], v[168:171], v[218:221], v[64:67]
	v_mfma_f32_16x16x32_bf16 v[132:135], v[164:167], v[198:201], v[132:135]
	v_mfma_f32_16x16x32_bf16 v[128:131], v[190:193], v[198:201], v[128:131]
	v_mfma_f32_16x16x32_bf16 v[116:119], v[164:167], v[206:209], v[116:119]
	v_mfma_f32_16x16x32_bf16 v[112:115], v[190:193], v[206:209], v[112:115]
	v_mfma_f32_16x16x32_bf16 v[100:103], v[164:167], v[214:217], v[100:103]
	v_mfma_f32_16x16x32_bf16 v[96:99], v[190:193], v[214:217], v[96:99]
	v_mfma_f32_16x16x32_bf16 v[72:75], v[164:167], v[222:225], v[72:75]
	v_mfma_f32_16x16x32_bf16 v[64:67], v[190:193], v[222:225], v[64:67]
	s_setprio 0
	s_barrier
	s_add_i32 s47, s66, s29
	v_lshl_add_u64 v[172:173], s[52:53], 0, v[146:147]
	s_mov_b32 m0, s47
	ds_read_b128 v[194:197], v187 offset:16384
	ds_read_b128 v[198:201], v187 offset:17408
	ds_read_b128 v[202:205], v187 offset:18432
	ds_read_b128 v[206:209], v187 offset:19456
	ds_read_b128 v[210:213], v187 offset:20480
	ds_read_b128 v[214:217], v187 offset:21504
	ds_read_b128 v[218:221], v187 offset:22528
	ds_read_b128 v[222:225], v187 offset:23552
	global_load_lds_dwordx4 v[172:173], off
	s_add_i32 m0, s47, 0x2000
	s_add_u32 s72, s52, 0x80000
	v_lshl_add_u64 v[226:227], s[52:53], 0, v[150:151]
	s_addc_u32 s73, s53, 0
	s_add_i32 s47, s67, s29
	global_load_lds_dwordx4 v[226:227], off
	v_lshl_add_u64 v[228:229], s[72:73], 0, v[146:147]
	s_mov_b32 m0, s47
	s_nop 0
	global_load_lds_dwordx4 v[228:229], off
	v_lshl_add_u64 v[228:229], s[72:73], 0, v[150:151]
	s_add_i32 m0, s47, 0x2000
	s_nop 0
	global_load_lds_dwordx4 v[228:229], off
	s_waitcnt vmcnt(6)
	s_waitcnt lgkmcnt(0)
	s_barrier
; #define PG8_STAGE(bufoff, gbase, voff) do { _Pragma("unroll") for (int _i = 0; _i < 2; ++_i) \
;         __builtin_amdgcn_global_load_lds((const unsigned*)((const char*)(gbase) + (voff)[_i]), (PG8_LAS unsigned*)(lds + (bufoff) + ldsw + _i * 8192), 16, 0, 0); } while (0)
; #define PG8_LDA(dst, b, h) do { _Pragma("unroll") for (int m = 0; m < 4; ++m) _Pragma("unroll") for (int k = 0; k < 2; ++k) dst[m][k] = *(const PG8_LAS bf16x8*)(lds + PG8_SA(b, h) + aoff + m * 2048 + k * 1024); } while (0)
; #define PG8_LDB(dst, b, h) do { _Pragma("unroll") for (int n = 0; n < 2; ++n) _Pragma("unroll") for (int k = 0; k < 2; ++k) dst[n][k] = *(const PG8_LAS bf16x8*)(lds + PG8_SB(b, h) + boff + n * 2048 + k * 1024); } while (0)
; #define PG8_MMA(ai, bj, At, Bt) do { __builtin_amdgcn_s_setprio(1); _Pragma("unroll") for (int m = 0; m < 4; ++m) _Pragma("unroll") for (int n = 0; n < 2; ++n) _Pragma("unroll") for (int k = 0; k < 2; ++k) \
;         acc[ai][bj][m][n] = __builtin_amdgcn_mfma_f32_16x16x32_bf16(Bt[n][k], At[m][k], acc[ai][bj][m][n], 0, 0, 0); __builtin_amdgcn_s_setprio(0); } while (0)
; #define PG8_WAIT_V(n) asm volatile("s_waitcnt vmcnt(" #n ")" ::: "memory")
; #define PG8_WAIT_L(n) asm volatile("s_waitcnt lgkmcnt(" #n ")" ::: "memory")
; #define PG8_BAR __builtin_amdgcn_s_barrier()
; #define PG8_SCHED __builtin_amdgcn_sched_barrier(0)
; template <class Epi, class Sched, bool ALIGN_EPI = false, bool SP2 = false>
; __device__ __forceinline__ void gemm_phase(PG8_LAS unsigned char* lds, const Gemm g, const Sched& S, const Epi& E, const int wid  ) {
;     ...
;             PG8_WAIT_V(8); PG8_WAIT_L(0); PG8_BAR; PG8_MMA(1, 0, At, B0); PG8_MMA(1, 1, At, B1); PG8_BAR; PG8_SCHED;
;             PG8_LDB(B0, 1, 0); PG8_LDB(B1, 1, 1); PG8_SCHED; PG8_LDA(At, 1, 0); PG8_STAGE(PG8_SA(0, 1), a2 + hstep, voffA);
;             PG8_WAIT_V(8); PG8_WAIT_L(0); PG8_BAR; PG8_MMA(0, 0, At, B0); PG8_MMA(0, 1, At, B1); PG8_BAR; PG8_SCHED;
	s_setprio 1
	s_waitcnt lgkmcnt(0)
	v_mfma_f32_16x16x32_bf16 v[60:63], v[68:71], v[194:197], v[60:63]
	v_mfma_f32_16x16x32_bf16 v[56:59], v[80:83], v[194:197], v[56:59]
	v_mfma_f32_16x16x32_bf16 v[44:47], v[68:71], v[202:205], v[44:47]
	v_mfma_f32_16x16x32_bf16 v[40:43], v[80:83], v[202:205], v[40:43]
	v_mfma_f32_16x16x32_bf16 v[28:31], v[68:71], v[210:213], v[28:31]
	v_mfma_f32_16x16x32_bf16 v[24:27], v[80:83], v[210:213], v[24:27]
	v_mfma_f32_16x16x32_bf16 v[12:15], v[68:71], v[218:221], v[12:15]
	v_mfma_f32_16x16x32_bf16 v[8:11], v[80:83], v[218:221], v[8:11]
	v_mfma_f32_16x16x32_bf16 v[60:63], v[76:79], v[198:201], v[60:63]
	v_mfma_f32_16x16x32_bf16 v[56:59], v[88:91], v[198:201], v[56:59]
	v_mfma_f32_16x16x32_bf16 v[44:47], v[76:79], v[206:209], v[44:47]
	v_mfma_f32_16x16x32_bf16 v[40:43], v[88:91], v[206:209], v[40:43]
	v_mfma_f32_16x16x32_bf16 v[28:31], v[76:79], v[214:217], v[28:31]
	v_mfma_f32_16x16x32_bf16 v[24:27], v[88:91], v[214:217], v[24:27]
	v_mfma_f32_16x16x32_bf16 v[12:15], v[76:79], v[222:225], v[12:15]
	v_mfma_f32_16x16x32_bf16 v[8:11], v[88:91], v[222:225], v[8:11]
	s_setprio 0
	s_setprio 1
	v_mfma_f32_16x16x32_bf16 v[52:55], v[160:163], v[194:197], v[52:55]
	v_mfma_f32_16x16x32_bf16 v[48:51], v[168:171], v[194:197], v[48:51]
	v_mfma_f32_16x16x32_bf16 v[36:39], v[160:163], v[202:205], v[36:39]
	v_mfma_f32_16x16x32_bf16 v[32:35], v[168:171], v[202:205], v[32:35]
	v_mfma_f32_16x16x32_bf16 v[20:23], v[160:163], v[210:213], v[20:23]
	v_mfma_f32_16x16x32_bf16 v[16:19], v[168:171], v[210:213], v[16:19]
	v_mfma_f32_16x16x32_bf16 v[4:7], v[160:163], v[218:221], v[4:7]
	v_mfma_f32_16x16x32_bf16 v[0:3], v[168:171], v[218:221], v[0:3]
	v_mfma_f32_16x16x32_bf16 v[52:55], v[164:167], v[198:201], v[52:55]
	v_mfma_f32_16x16x32_bf16 v[48:51], v[190:193], v[198:201], v[48:51]
	v_mfma_f32_16x16x32_bf16 v[36:39], v[164:167], v[206:209], v[36:39]
	v_mfma_f32_16x16x32_bf16 v[32:35], v[190:193], v[206:209], v[32:35]
	v_mfma_f32_16x16x32_bf16 v[20:23], v[164:167], v[214:217], v[20:23]
	v_mfma_f32_16x16x32_bf16 v[16:19], v[190:193], v[214:217], v[16:19]
	v_mfma_f32_16x16x32_bf16 v[4:7], v[164:167], v[222:225], v[4:7]
	v_mfma_f32_16x16x32_bf16 v[0:3], v[190:193], v[222:225], v[0:3]
	s_setprio 0
	s_barrier
	s_add_i32 s47, 0, 0x18000
	s_add_i32 s72, 0, 0x1c000
	v_add_u32_e32 v88, s47, v176
	v_add_u32_e32 v190, s72, v176
	ds_read_b128 v[68:71], v88
	ds_read_b128 v[76:79], v88 offset:1024
	ds_read_b128 v[80:83], v88 offset:2048
	ds_read_b128 v[88:91], v88 offset:3072
	ds_read_b128 v[160:163], v190
	ds_read_b128 v[164:167], v190 offset:1024
	ds_read_b128 v[168:171], v190 offset:2048
	ds_read_b128 v[190:193], v190 offset:3072
	v_lshl_add_u64 v[228:229], s[54:55], 0, v[144:145]
	s_mov_b32 m0, s37
	v_lshl_add_u64 v[230:231], s[54:55], 0, v[148:149]
	global_load_lds_dwordx4 v[228:229], off
	s_mov_b32 m0, s56
	s_nop 0
	global_load_lds_dwordx4 v[230:231], off
	s_add_u32 s54, s54, 0x80000
	s_addc_u32 s55, s55, 0
	s_mov_b32 m0, s57
	v_lshl_add_u64 v[232:233], s[54:55], 0, v[144:145]
	ds_read_b128 v[194:197], v187 offset:32768
	ds_read_b128 v[198:201], v187 offset:33792
	ds_read_b128 v[202:205], v187 offset:34816
	ds_read_b128 v[206:209], v187 offset:35840
	ds_read_b128 v[210:213], v187 offset:36864
	ds_read_b128 v[214:217], v187 offset:37888
	ds_read_b128 v[218:221], v187 offset:38912
	ds_read_b128 v[222:225], v187 offset:39936
	global_load_lds_dwordx4 v[232:233], off
	v_lshl_add_u64 v[232:233], s[54:55], 0, v[148:149]
	s_mov_b32 m0, s58
	s_nop 0
	global_load_lds_dwordx4 v[232:233], off
	s_waitcnt vmcnt(8)
	s_waitcnt lgkmcnt(0)
	s_barrier
; #define PG8_STAGE(bufoff, gbase, voff) do { _Pragma("unroll") for (int _i = 0; _i < 2; ++_i) \
;         __builtin_amdgcn_global_load_lds((const unsigned*)((const char*)(gbase) + (voff)[_i]), (PG8_LAS unsigned*)(lds + (bufoff) + ldsw + _i * 8192), 16, 0, 0); } while (0)
; #define PG8_LDA(dst, b, h) do { _Pragma("unroll") for (int m = 0; m < 4; ++m) _Pragma("unroll") for (int k = 0; k < 2; ++k) dst[m][k] = *(const PG8_LAS bf16x8*)(lds + PG8_SA(b, h) + aoff + m * 2048 + k * 1024); } while (0)
; #define PG8_MMA(ai, bj, At, Bt) do { __builtin_amdgcn_s_setprio(1); _Pragma("unroll") for (int m = 0; m < 4; ++m) _Pragma("unroll") for (int n = 0; n < 2; ++n) _Pragma("unroll") for (int k = 0; k < 2; ++k) \
;         acc[ai][bj][m][n] = __builtin_amdgcn_mfma_f32_16x16x32_bf16(Bt[n][k], At[m][k], acc[ai][bj][m][n], 0, 0, 0); __builtin_amdgcn_s_setprio(0); } while (0)
; #define PG8_WAIT_V(n) asm volatile("s_waitcnt vmcnt(" #n ")" ::: "memory")
; #define PG8_WAIT_L(n) asm volatile("s_waitcnt lgkmcnt(" #n ")" ::: "memory")
; #define PG8_BAR __builtin_amdgcn_s_barrier()
; #define PG8_SCHED __builtin_amdgcn_sched_barrier(0)
; template <class Epi, class Sched, bool ALIGN_EPI = false, bool SP2 = false>
; __device__ __forceinline__ void gemm_phase(PG8_LAS unsigned char* lds, const Gemm g, const Sched& S, const Epi& E, const int wid  ) {
;     ...
;             PG8_WAIT_V(8); PG8_WAIT_L(0); PG8_BAR; PG8_MMA(0, 0, At, B0); PG8_MMA(0, 1, At, B1); PG8_BAR; PG8_SCHED;
;             PG8_LDA(At, 1, 1); PG8_STAGE(PG8_SB(1, 0), b3, voffB); PG8_STAGE(PG8_SB(1, 1), b3 + hstep, voffB); PG8_STAGE(PG8_SA(1, 0), a3, voffA);
;             PG8_WAIT_V(8); PG8_WAIT_L(0); PG8_BAR; PG8_MMA(1, 0, At, B0); PG8_MMA(1, 1, At, B1); PG8_BAR; PG8_SCHED;
	s_setprio 1
	s_waitcnt lgkmcnt(0)
	v_mfma_f32_16x16x32_bf16 v[140:143], v[68:71], v[194:197], v[140:143]
	v_mfma_f32_16x16x32_bf16 v[136:139], v[80:83], v[194:197], v[136:139]
	v_mfma_f32_16x16x32_bf16 v[124:127], v[68:71], v[202:205], v[124:127]
	v_mfma_f32_16x16x32_bf16 v[120:123], v[80:83], v[202:205], v[120:123]
	v_mfma_f32_16x16x32_bf16 v[108:111], v[68:71], v[210:213], v[108:111]
	v_mfma_f32_16x16x32_bf16 v[104:107], v[80:83], v[210:213], v[104:107]
	v_mfma_f32_16x16x32_bf16 v[92:95], v[68:71], v[218:221], v[92:95]
	v_mfma_f32_16x16x32_bf16 v[84:87], v[80:83], v[218:221], v[84:87]
	v_mfma_f32_16x16x32_bf16 v[140:143], v[76:79], v[198:201], v[140:143]
	v_mfma_f32_16x16x32_bf16 v[136:139], v[88:91], v[198:201], v[136:139]
	v_mfma_f32_16x16x32_bf16 v[124:127], v[76:79], v[206:209], v[124:127]
	v_mfma_f32_16x16x32_bf16 v[120:123], v[88:91], v[206:209], v[120:123]
	v_mfma_f32_16x16x32_bf16 v[108:111], v[76:79], v[214:217], v[108:111]
	v_mfma_f32_16x16x32_bf16 v[104:107], v[88:91], v[214:217], v[104:107]
	v_mfma_f32_16x16x32_bf16 v[92:95], v[76:79], v[222:225], v[92:95]
	v_mfma_f32_16x16x32_bf16 v[84:87], v[88:91], v[222:225], v[84:87]
	s_setprio 0
	s_setprio 1
	v_mfma_f32_16x16x32_bf16 v[132:135], v[160:163], v[194:197], v[132:135]
	v_mfma_f32_16x16x32_bf16 v[128:131], v[168:171], v[194:197], v[128:131]
	v_mfma_f32_16x16x32_bf16 v[116:119], v[160:163], v[202:205], v[116:119]
	v_mfma_f32_16x16x32_bf16 v[112:115], v[168:171], v[202:205], v[112:115]
	v_mfma_f32_16x16x32_bf16 v[100:103], v[160:163], v[210:213], v[100:103]
	v_mfma_f32_16x16x32_bf16 v[96:99], v[168:171], v[210:213], v[96:99]
	v_mfma_f32_16x16x32_bf16 v[72:75], v[160:163], v[218:221], v[72:75]
	v_mfma_f32_16x16x32_bf16 v[64:67], v[168:171], v[218:221], v[64:67]
	v_mfma_f32_16x16x32_bf16 v[132:135], v[164:167], v[198:201], v[132:135]
	v_mfma_f32_16x16x32_bf16 v[128:131], v[190:193], v[198:201], v[128:131]
	v_mfma_f32_16x16x32_bf16 v[116:119], v[164:167], v[206:209], v[116:119]
	v_mfma_f32_16x16x32_bf16 v[112:115], v[190:193], v[206:209], v[112:115]
	v_mfma_f32_16x16x32_bf16 v[100:103], v[164:167], v[214:217], v[100:103]
	v_mfma_f32_16x16x32_bf16 v[96:99], v[190:193], v[214:217], v[96:99]
	v_mfma_f32_16x16x32_bf16 v[72:75], v[164:167], v[222:225], v[72:75]
	v_mfma_f32_16x16x32_bf16 v[64:67], v[190:193], v[222:225], v[64:67]
	s_setprio 0
	s_barrier
	s_add_i32 s47, s47, s29
	v_lshl_add_u64 v[172:173], v[172:173], 0, s[38:39]
	s_mov_b32 m0, s47
	ds_read_b128 v[194:197], v187 offset:49152
	ds_read_b128 v[198:201], v187 offset:50176
	ds_read_b128 v[202:205], v187 offset:51200
	ds_read_b128 v[206:209], v187 offset:52224
	ds_read_b128 v[210:213], v187 offset:53248
	ds_read_b128 v[214:217], v187 offset:54272
	ds_read_b128 v[218:221], v187 offset:55296
	ds_read_b128 v[222:225], v187 offset:56320
	global_load_lds_dwordx4 v[172:173], off
	s_add_i32 m0, s47, 0x2000
	s_add_u32 s52, s52, 0x80080
	v_lshl_add_u64 v[172:173], v[226:227], 0, s[38:39]
	s_addc_u32 s53, s53, 0
	s_add_i32 s47, s72, s29
	global_load_lds_dwordx4 v[172:173], off
	v_lshl_add_u64 v[172:173], s[52:53], 0, v[146:147]
	s_mov_b32 m0, s47
	s_nop 0
	global_load_lds_dwordx4 v[172:173], off
	v_lshl_add_u64 v[172:173], s[52:53], 0, v[150:151]
	s_add_i32 m0, s47, 0x2000
	s_nop 0
	global_load_lds_dwordx4 v[172:173], off
	s_waitcnt vmcnt(6)
	s_waitcnt lgkmcnt(0)
	s_barrier
	s_setprio 1
	s_waitcnt lgkmcnt(0)
	v_mfma_f32_16x16x32_bf16 v[60:63], v[68:71], v[194:197], v[60:63]
	v_mfma_f32_16x16x32_bf16 v[56:59], v[80:83], v[194:197], v[56:59]
	v_mfma_f32_16x16x32_bf16 v[44:47], v[68:71], v[202:205], v[44:47]
	v_mfma_f32_16x16x32_bf16 v[40:43], v[80:83], v[202:205], v[40:43]
	v_mfma_f32_16x16x32_bf16 v[28:31], v[68:71], v[210:213], v[28:31]
	v_mfma_f32_16x16x32_bf16 v[24:27], v[80:83], v[210:213], v[24:27]
	v_mfma_f32_16x16x32_bf16 v[12:15], v[68:71], v[218:221], v[12:15]
	v_mfma_f32_16x16x32_bf16 v[8:11], v[80:83], v[218:221], v[8:11]
	v_mfma_f32_16x16x32_bf16 v[60:63], v[76:79], v[198:201], v[60:63]
	v_mfma_f32_16x16x32_bf16 v[56:59], v[88:91], v[198:201], v[56:59]
	v_mfma_f32_16x16x32_bf16 v[44:47], v[76:79], v[206:209], v[44:47]
	v_mfma_f32_16x16x32_bf16 v[40:43], v[88:91], v[206:209], v[40:43]
	v_mfma_f32_16x16x32_bf16 v[28:31], v[76:79], v[214:217], v[28:31]
	v_mfma_f32_16x16x32_bf16 v[24:27], v[88:91], v[214:217], v[24:27]
	v_mfma_f32_16x16x32_bf16 v[12:15], v[76:79], v[222:225], v[12:15]
	v_mfma_f32_16x16x32_bf16 v[8:11], v[88:91], v[222:225], v[8:11]
	s_setprio 0
	s_setprio 1
	v_mfma_f32_16x16x32_bf16 v[52:55], v[160:163], v[194:197], v[52:55]
	v_mfma_f32_16x16x32_bf16 v[48:51], v[168:171], v[194:197], v[48:51]
	v_mfma_f32_16x16x32_bf16 v[36:39], v[160:163], v[202:205], v[36:39]
	v_mfma_f32_16x16x32_bf16 v[32:35], v[168:171], v[202:205], v[32:35]
	v_mfma_f32_16x16x32_bf16 v[20:23], v[160:163], v[210:213], v[20:23]
	v_mfma_f32_16x16x32_bf16 v[16:19], v[168:171], v[210:213], v[16:19]
	v_mfma_f32_16x16x32_bf16 v[4:7], v[160:163], v[218:221], v[4:7]
	v_mfma_f32_16x16x32_bf16 v[0:3], v[168:171], v[218:221], v[0:3]
	v_mfma_f32_16x16x32_bf16 v[52:55], v[164:167], v[198:201], v[52:55]
	v_mfma_f32_16x16x32_bf16 v[48:51], v[190:193], v[198:201], v[48:51]
	v_mfma_f32_16x16x32_bf16 v[36:39], v[164:167], v[206:209], v[36:39]
	v_mfma_f32_16x16x32_bf16 v[32:35], v[190:193], v[206:209], v[32:35]
	v_mfma_f32_16x16x32_bf16 v[20:23], v[164:167], v[214:217], v[20:23]
	v_mfma_f32_16x16x32_bf16 v[16:19], v[190:193], v[214:217], v[16:19]
	v_mfma_f32_16x16x32_bf16 v[4:7], v[164:167], v[222:225], v[4:7]
	v_mfma_f32_16x16x32_bf16 v[0:3], v[190:193], v[222:225], v[0:3]
	s_setprio 0
	s_add_i32 s45, s45, 2
	s_add_u32 s10, s10, 0x100
	s_addc_u32 s11, s11, 0
	s_add_u32 s34, s34, 0x100
	s_addc_u32 s35, s35, 0
	s_cmp_gt_u32 s45, 29
	s_barrier
	s_cbranch_scc0 .LBB0_230
	s_and_b64 vcc, exec, s[40:41]
	s_cbranch_vccz .LBB0_233
	s_barrier

; #define PG8_STAGE(bufoff, gbase, voff) do { _Pragma("unroll") for (int _i = 0; _i < 2; ++_i) \
;         __builtin_amdgcn_global_load_lds((const unsigned*)((const char*)(gbase) + (voff)[_i]), (PG8_LAS unsigned*)(lds + (bufoff) + ldsw + _i * 8192), 16, 0, 0); } while (0)
; #define PG8_LDA(dst, b, h) do { _Pragma("unroll") for (int m = 0; m < 4; ++m) _Pragma("unroll") for (int k = 0; k < 2; ++k) dst[m][k] = *(const PG8_LAS bf16x8*)(lds + PG8_SA(b, h) + aoff + m * 2048 + k * 1024); } while (0)
; #define PG8_LDB(dst, b, h) do { _Pragma("unroll") for (int n = 0; n < 2; ++n) _Pragma("unroll") for (int k = 0; k < 2; ++k) dst[n][k] = *(const PG8_LAS bf16x8*)(lds + PG8_SB(b, h) + boff + n * 2048 + k * 1024); } while (0)
; #define PG8_MMA(ai, bj, At, Bt) do { __builtin_amdgcn_s_setprio(1); _Pragma("unroll") for (int m = 0; m < 4; ++m) _Pragma("unroll") for (int n = 0; n < 2; ++n) _Pragma("unroll") for (int k = 0; k < 2; ++k) \
;         acc[ai][bj][m][n] = __builtin_amdgcn_mfma_f32_16x16x32_bf16(Bt[n][k], At[m][k], acc[ai][bj][m][n], 0, 0, 0); __builtin_amdgcn_s_setprio(0); } while (0)
; #define PG8_WAIT_V(n) asm volatile("s_waitcnt vmcnt(" #n ")" ::: "memory")
; #define PG8_WAIT_L(n) asm volatile("s_waitcnt lgkmcnt(" #n ")" ::: "memory")
; #define PG8_BAR __builtin_amdgcn_s_barrier()
; template <class Epi, class Sched, bool ALIGN_EPI = false, bool SP2 = false>
; __device__ __forceinline__ void gemm_phase(PG8_LAS unsigned char* lds, const Gemm g, const Sched& S, const Epi& E, const int wid  ) {
;     ...
;         for (int t = 0; t < nt; t += 2) {
;             const bool last = (t == nt - 2);
;             const char* a1 = cA + (size_t)(t + 1) * kstep;
;             const char* a2 = last ? nA : cA + (size_t)(t + 2) * kstep; const char* b2 = last ? nB : cB + (size_t)(t + 2) * kstep;
;             const char* a3 = a2 + kstep; const char* b3 = b2 + kstep;
;             if (last && has_next) S.a_ready(nxt);
;             if constexpr (SP2) {
;             PG8_LDB(B0, 0, 0); PG8_LDB(B1, 0, 1); PG8_SCHED; PG8_LDA(At, 0, 0); PG8_STAGE(PG8_SA(1, 1), a1 + hstep, voffA);
;             PG8_WAIT_V(8); PG8_WAIT_L(0); PG8_BAR; PG8_MMA(0, 0, At, B0); PG8_MMA(0, 1, At, B1); PG8_BAR; PG8_SCHED;
;             PG8_LDA(At, 0, 1); PG8_STAGE(PG8_SB(0, 0), b2, voffB); PG8_STAGE(PG8_SB(0, 1), b2 + hstep, voffB); PG8_STAGE(PG8_SA(0, 0), a2, voffA);
.LBB0_549:
	s_add_u32 s100, s56, 0xfff80000
	s_addc_u32 s101, s57, -1
	ds_read_b128 v[64:67], v236
	ds_read_b128 v[68:71], v236 offset:1024
	ds_read_b128 v[80:83], v236 offset:2048
	ds_read_b128 v[84:87], v236 offset:3072
	ds_read_b128 v[144:147], v237
	ds_read_b128 v[148:151], v237 offset:1024
	ds_read_b128 v[152:155], v237 offset:2048
	ds_read_b128 v[156:159], v237 offset:3072
	s_add_u32 s58, s56, 0xfff80080
	s_addc_u32 s59, s57, -1
	s_cmp_eq_u32 s72, 28
	s_cselect_b32 s61, s9, s59
	s_cselect_b32 s60, s49, s58
	s_cselect_b32 s59, s47, s71
	s_cselect_b32 s58, s55, s70
	v_lshl_add_u64 v[196:197], s[100:101], 0, v[208:209]
	s_mov_b32 m0, s64
	v_lshl_add_u64 v[198:199], s[100:101], 0, v[210:211]
	global_load_lds_dwordx4 v[196:197], off
	s_mov_b32 m0, s65
	s_nop 0
	global_load_lds_dwordx4 v[198:199], off
	v_lshl_add_u64 v[192:193], s[56:57], 0, v[208:209]
	s_add_i32 m0, s34, 0xc000
	ds_read_b128 v[160:163], v238
	ds_read_b128 v[164:167], v238 offset:1024
	ds_read_b128 v[168:171], v238 offset:2048
	ds_read_b128 v[172:175], v238 offset:3072
	ds_read_b128 v[176:179], v238 offset:4096
	ds_read_b128 v[180:183], v238 offset:5120
	ds_read_b128 v[184:187], v238 offset:6144
	ds_read_b128 v[188:191], v238 offset:7168
	global_load_lds_dwordx4 v[192:193], off
	v_lshl_add_u64 v[192:193], s[56:57], 0, v[210:211]
	s_add_i32 m0, s34, 0xe000
	s_nop 0
	global_load_lds_dwordx4 v[192:193], off
	s_waitcnt vmcnt(8)
	s_waitcnt lgkmcnt(0)
	s_barrier
	s_setprio 1
	s_waitcnt lgkmcnt(0)
	v_mfma_f32_16x16x32_bf16 v[140:143], v[64:67], v[160:163], v[140:143]
	v_mfma_f32_16x16x32_bf16 v[136:139], v[80:83], v[160:163], v[136:139]
	v_mfma_f32_16x16x32_bf16 v[124:127], v[64:67], v[168:171], v[124:127]
	v_mfma_f32_16x16x32_bf16 v[120:123], v[80:83], v[168:171], v[120:123]
	v_mfma_f32_16x16x32_bf16 v[108:111], v[64:67], v[176:179], v[108:111]
	v_mfma_f32_16x16x32_bf16 v[104:107], v[80:83], v[176:179], v[104:107]
	v_mfma_f32_16x16x32_bf16 v[92:95], v[64:67], v[184:187], v[92:95]
	v_mfma_f32_16x16x32_bf16 v[88:91], v[80:83], v[184:187], v[88:91]
	v_mfma_f32_16x16x32_bf16 v[140:143], v[68:71], v[164:167], v[140:143]
	v_mfma_f32_16x16x32_bf16 v[136:139], v[84:87], v[164:167], v[136:139]
	v_mfma_f32_16x16x32_bf16 v[124:127], v[68:71], v[172:175], v[124:127]
	v_mfma_f32_16x16x32_bf16 v[120:123], v[84:87], v[172:175], v[120:123]
	v_mfma_f32_16x16x32_bf16 v[108:111], v[68:71], v[180:183], v[108:111]
	v_mfma_f32_16x16x32_bf16 v[104:107], v[84:87], v[180:183], v[104:107]
	v_mfma_f32_16x16x32_bf16 v[92:95], v[68:71], v[188:191], v[92:95]
	v_mfma_f32_16x16x32_bf16 v[88:91], v[84:87], v[188:191], v[88:91]
	s_setprio 0
	s_setprio 1
	v_mfma_f32_16x16x32_bf16 v[132:135], v[144:147], v[160:163], v[132:135]
	v_mfma_f32_16x16x32_bf16 v[128:131], v[152:155], v[160:163], v[128:131]
	v_mfma_f32_16x16x32_bf16 v[116:119], v[144:147], v[168:171], v[116:119]
	v_mfma_f32_16x16x32_bf16 v[112:115], v[152:155], v[168:171], v[112:115]
	v_mfma_f32_16x16x32_bf16 v[100:103], v[144:147], v[176:179], v[100:103]
	v_mfma_f32_16x16x32_bf16 v[96:99], v[152:155], v[176:179], v[96:99]
	v_mfma_f32_16x16x32_bf16 v[76:79], v[144:147], v[184:187], v[76:79]
	v_mfma_f32_16x16x32_bf16 v[72:75], v[152:155], v[184:187], v[72:75]
	v_mfma_f32_16x16x32_bf16 v[132:135], v[148:151], v[164:167], v[132:135]
	v_mfma_f32_16x16x32_bf16 v[128:131], v[156:159], v[164:167], v[128:131]
	v_mfma_f32_16x16x32_bf16 v[116:119], v[148:151], v[172:175], v[116:119]
	v_mfma_f32_16x16x32_bf16 v[112:115], v[156:159], v[172:175], v[112:115]
	v_mfma_f32_16x16x32_bf16 v[100:103], v[148:151], v[180:183], v[100:103]
	v_mfma_f32_16x16x32_bf16 v[96:99], v[156:159], v[180:183], v[96:99]
	v_mfma_f32_16x16x32_bf16 v[76:79], v[148:151], v[188:191], v[76:79]
	v_mfma_f32_16x16x32_bf16 v[72:75], v[156:159], v[188:191], v[72:75]
	s_setprio 0
	s_barrier
	s_add_i32 s73, s68, s31
	v_lshl_add_u64 v[192:193], s[58:59], 0, v[202:203]
	s_mov_b32 m0, s73
	ds_read_b128 v[160:163], v238 offset:16384
	ds_read_b128 v[164:167], v238 offset:17408
	ds_read_b128 v[168:171], v238 offset:18432
	ds_read_b128 v[172:175], v238 offset:19456
	ds_read_b128 v[176:179], v238 offset:20480
	ds_read_b128 v[180:183], v238 offset:21504
	ds_read_b128 v[184:187], v238 offset:22528
	ds_read_b128 v[188:191], v238 offset:23552
	global_load_lds_dwordx4 v[192:193], off
	s_add_i32 m0, s73, 0x2000
	s_add_u32 s74, s58, 0x80000
	v_lshl_add_u64 v[194:195], s[58:59], 0, v[206:207]
	s_addc_u32 s75, s59, 0
	s_add_i32 s73, s69, s31
	global_load_lds_dwordx4 v[194:195], off
	v_lshl_add_u64 v[196:197], s[74:75], 0, v[202:203]
	s_mov_b32 m0, s73
	s_nop 0
	global_load_lds_dwordx4 v[196:197], off
	v_lshl_add_u64 v[196:197], s[74:75], 0, v[206:207]
	s_add_i32 m0, s73, 0x2000
	s_nop 0
	global_load_lds_dwordx4 v[196:197], off
	s_waitcnt vmcnt(6)
	s_waitcnt lgkmcnt(0)
	s_barrier
; #define PG8_STAGE(bufoff, gbase, voff) do { _Pragma("unroll") for (int _i = 0; _i < 2; ++_i) \
;         __builtin_amdgcn_global_load_lds((const unsigned*)((const char*)(gbase) + (voff)[_i]), (PG8_LAS unsigned*)(lds + (bufoff) + ldsw + _i * 8192), 16, 0, 0); } while (0)
; #define PG8_LDA(dst, b, h) do { _Pragma("unroll") for (int m = 0; m < 4; ++m) _Pragma("unroll") for (int k = 0; k < 2; ++k) dst[m][k] = *(const PG8_LAS bf16x8*)(lds + PG8_SA(b, h) + aoff + m * 2048 + k * 1024); } while (0)
; #define PG8_LDB(dst, b, h) do { _Pragma("unroll") for (int n = 0; n < 2; ++n) _Pragma("unroll") for (int k = 0; k < 2; ++k) dst[n][k] = *(const PG8_LAS bf16x8*)(lds + PG8_SB(b, h) + boff + n * 2048 + k * 1024); } while (0)
; #define PG8_MMA(ai, bj, At, Bt) do { __builtin_amdgcn_s_setprio(1); _Pragma("unroll") for (int m = 0; m < 4; ++m) _Pragma("unroll") for (int n = 0; n < 2; ++n) _Pragma("unroll") for (int k = 0; k < 2; ++k) \
;         acc[ai][bj][m][n] = __builtin_amdgcn_mfma_f32_16x16x32_bf16(Bt[n][k], At[m][k], acc[ai][bj][m][n], 0, 0, 0); __builtin_amdgcn_s_setprio(0); } while (0)
; #define PG8_WAIT_V(n) asm volatile("s_waitcnt vmcnt(" #n ")" ::: "memory")
; #define PG8_WAIT_L(n) asm volatile("s_waitcnt lgkmcnt(" #n ")" ::: "memory")
; #define PG8_BAR __builtin_amdgcn_s_barrier()
; #define PG8_SCHED __builtin_amdgcn_sched_barrier(0)
; template <class Epi, class Sched, bool ALIGN_EPI = false, bool SP2 = false>
; __device__ __forceinline__ void gemm_phase(PG8_LAS unsigned char* lds, const Gemm g, const Sched& S, const Epi& E, const int wid  ) {
;     ...
;             PG8_WAIT_V(8); PG8_WAIT_L(0); PG8_BAR; PG8_MMA(1, 0, At, B0); PG8_MMA(1, 1, At, B1); PG8_BAR; PG8_SCHED;
;             PG8_LDB(B0, 1, 0); PG8_LDB(B1, 1, 1); PG8_SCHED; PG8_LDA(At, 1, 0); PG8_STAGE(PG8_SA(0, 1), a2 + hstep, voffA);
;             PG8_WAIT_V(8); PG8_WAIT_L(0); PG8_BAR; PG8_MMA(0, 0, At, B0); PG8_MMA(0, 1, At, B1); PG8_BAR; PG8_SCHED;
	s_setprio 1
	s_waitcnt lgkmcnt(0)
	v_mfma_f32_16x16x32_bf16 v[60:63], v[64:67], v[160:163], v[60:63]
	v_mfma_f32_16x16x32_bf16 v[56:59], v[80:83], v[160:163], v[56:59]
	v_mfma_f32_16x16x32_bf16 v[44:47], v[64:67], v[168:171], v[44:47]
	v_mfma_f32_16x16x32_bf16 v[40:43], v[80:83], v[168:171], v[40:43]
	v_mfma_f32_16x16x32_bf16 v[28:31], v[64:67], v[176:179], v[28:31]
	v_mfma_f32_16x16x32_bf16 v[24:27], v[80:83], v[176:179], v[24:27]
	v_mfma_f32_16x16x32_bf16 v[12:15], v[64:67], v[184:187], v[12:15]
	v_mfma_f32_16x16x32_bf16 v[8:11], v[80:83], v[184:187], v[8:11]
	v_mfma_f32_16x16x32_bf16 v[60:63], v[68:71], v[164:167], v[60:63]
	v_mfma_f32_16x16x32_bf16 v[56:59], v[84:87], v[164:167], v[56:59]
	v_mfma_f32_16x16x32_bf16 v[44:47], v[68:71], v[172:175], v[44:47]
	v_mfma_f32_16x16x32_bf16 v[40:43], v[84:87], v[172:175], v[40:43]
	v_mfma_f32_16x16x32_bf16 v[28:31], v[68:71], v[180:183], v[28:31]
	v_mfma_f32_16x16x32_bf16 v[24:27], v[84:87], v[180:183], v[24:27]
	v_mfma_f32_16x16x32_bf16 v[12:15], v[68:71], v[188:191], v[12:15]
	v_mfma_f32_16x16x32_bf16 v[8:11], v[84:87], v[188:191], v[8:11]
	s_setprio 0
	s_setprio 1
	v_mfma_f32_16x16x32_bf16 v[52:55], v[144:147], v[160:163], v[52:55]
	v_mfma_f32_16x16x32_bf16 v[48:51], v[152:155], v[160:163], v[48:51]
	v_mfma_f32_16x16x32_bf16 v[36:39], v[144:147], v[168:171], v[36:39]
	v_mfma_f32_16x16x32_bf16 v[32:35], v[152:155], v[168:171], v[32:35]
	v_mfma_f32_16x16x32_bf16 v[20:23], v[144:147], v[176:179], v[20:23]
	v_mfma_f32_16x16x32_bf16 v[16:19], v[152:155], v[176:179], v[16:19]
	v_mfma_f32_16x16x32_bf16 v[4:7], v[144:147], v[184:187], v[4:7]
	v_mfma_f32_16x16x32_bf16 v[0:3], v[152:155], v[184:187], v[0:3]
	v_mfma_f32_16x16x32_bf16 v[52:55], v[148:151], v[164:167], v[52:55]
	v_mfma_f32_16x16x32_bf16 v[48:51], v[156:159], v[164:167], v[48:51]
	v_mfma_f32_16x16x32_bf16 v[36:39], v[148:151], v[172:175], v[36:39]
	v_mfma_f32_16x16x32_bf16 v[32:35], v[156:159], v[172:175], v[32:35]
	v_mfma_f32_16x16x32_bf16 v[20:23], v[148:151], v[180:183], v[20:23]
	v_mfma_f32_16x16x32_bf16 v[16:19], v[156:159], v[180:183], v[16:19]
	v_mfma_f32_16x16x32_bf16 v[4:7], v[148:151], v[188:191], v[4:7]
	v_mfma_f32_16x16x32_bf16 v[0:3], v[156:159], v[188:191], v[0:3]
	s_setprio 0
	s_barrier
	s_add_i32 s73, 0, 0x18000
	s_add_i32 s74, 0, 0x1c000
	v_add_u32_e32 v84, s73, v234
	v_add_u32_e32 v156, s74, v234
	ds_read_b128 v[64:67], v84
	ds_read_b128 v[68:71], v84 offset:1024
	ds_read_b128 v[80:83], v84 offset:2048
	ds_read_b128 v[84:87], v84 offset:3072
	ds_read_b128 v[144:147], v156
	ds_read_b128 v[148:151], v156 offset:1024
	ds_read_b128 v[152:155], v156 offset:2048
	ds_read_b128 v[156:159], v156 offset:3072
	v_lshl_add_u64 v[196:197], s[60:61], 0, v[200:201]
	s_mov_b32 m0, s34
	v_lshl_add_u64 v[198:199], s[60:61], 0, v[204:205]
	global_load_lds_dwordx4 v[196:197], off
	s_mov_b32 m0, s35
	s_nop 0
	global_load_lds_dwordx4 v[198:199], off
	s_add_u32 s60, s60, 0x80000
	s_addc_u32 s61, s61, 0
	s_mov_b32 m0, s37
	v_lshl_add_u64 v[216:217], s[60:61], 0, v[200:201]
	ds_read_b128 v[160:163], v238 offset:32768
	ds_read_b128 v[164:167], v238 offset:33792
	ds_read_b128 v[168:171], v238 offset:34816
	ds_read_b128 v[172:175], v238 offset:35840
	ds_read_b128 v[176:179], v238 offset:36864
	ds_read_b128 v[180:183], v238 offset:37888
	ds_read_b128 v[184:187], v238 offset:38912
	ds_read_b128 v[188:191], v238 offset:39936
	global_load_lds_dwordx4 v[216:217], off
	v_lshl_add_u64 v[216:217], s[60:61], 0, v[204:205]
	s_mov_b32 m0, s62
	s_nop 0
	global_load_lds_dwordx4 v[216:217], off
	s_waitcnt vmcnt(8)
	s_waitcnt lgkmcnt(0)
	s_barrier
; #define PG8_STAGE(bufoff, gbase, voff) do { _Pragma("unroll") for (int _i = 0; _i < 2; ++_i) \
;         __builtin_amdgcn_global_load_lds((const unsigned*)((const char*)(gbase) + (voff)[_i]), (PG8_LAS unsigned*)(lds + (bufoff) + ldsw + _i * 8192), 16, 0, 0); } while (0)
; #define PG8_LDA(dst, b, h) do { _Pragma("unroll") for (int m = 0; m < 4; ++m) _Pragma("unroll") for (int k = 0; k < 2; ++k) dst[m][k] = *(const PG8_LAS bf16x8*)(lds + PG8_SA(b, h) + aoff + m * 2048 + k * 1024); } while (0)
; #define PG8_MMA(ai, bj, At, Bt) do { __builtin_amdgcn_s_setprio(1); _Pragma("unroll") for (int m = 0; m < 4; ++m) _Pragma("unroll") for (int n = 0; n < 2; ++n) _Pragma("unroll") for (int k = 0; k < 2; ++k) \
;         acc[ai][bj][m][n] = __builtin_amdgcn_mfma_f32_16x16x32_bf16(Bt[n][k], At[m][k], acc[ai][bj][m][n], 0, 0, 0); __builtin_amdgcn_s_setprio(0); } while (0)
; #define PG8_WAIT_V(n) asm volatile("s_waitcnt vmcnt(" #n ")" ::: "memory")
; #define PG8_WAIT_L(n) asm volatile("s_waitcnt lgkmcnt(" #n ")" ::: "memory")
; #define PG8_BAR __builtin_amdgcn_s_barrier()
; #define PG8_SCHED __builtin_amdgcn_sched_barrier(0)
; template <class Epi, class Sched, bool ALIGN_EPI = false, bool SP2 = false>
; __device__ __forceinline__ void gemm_phase(PG8_LAS unsigned char* lds, const Gemm g, const Sched& S, const Epi& E, const int wid  ) {
;     ...
;             PG8_WAIT_V(8); PG8_WAIT_L(0); PG8_BAR; PG8_MMA(0, 0, At, B0); PG8_MMA(0, 1, At, B1); PG8_BAR; PG8_SCHED;
;             PG8_LDA(At, 1, 1); PG8_STAGE(PG8_SB(1, 0), b3, voffB); PG8_STAGE(PG8_SB(1, 1), b3 + hstep, voffB); PG8_STAGE(PG8_SA(1, 0), a3, voffA);
;             PG8_WAIT_V(8); PG8_WAIT_L(0); PG8_BAR; PG8_MMA(1, 0, At, B0); PG8_MMA(1, 1, At, B1); PG8_BAR; PG8_SCHED;
	s_setprio 1
	s_waitcnt lgkmcnt(0)
	v_mfma_f32_16x16x32_bf16 v[140:143], v[64:67], v[160:163], v[140:143]
	v_mfma_f32_16x16x32_bf16 v[136:139], v[80:83], v[160:163], v[136:139]
	v_mfma_f32_16x16x32_bf16 v[124:127], v[64:67], v[168:171], v[124:127]
	v_mfma_f32_16x16x32_bf16 v[120:123], v[80:83], v[168:171], v[120:123]
	v_mfma_f32_16x16x32_bf16 v[108:111], v[64:67], v[176:179], v[108:111]
	v_mfma_f32_16x16x32_bf16 v[104:107], v[80:83], v[176:179], v[104:107]
	v_mfma_f32_16x16x32_bf16 v[92:95], v[64:67], v[184:187], v[92:95]
	v_mfma_f32_16x16x32_bf16 v[88:91], v[80:83], v[184:187], v[88:91]
	v_mfma_f32_16x16x32_bf16 v[140:143], v[68:71], v[164:167], v[140:143]
	v_mfma_f32_16x16x32_bf16 v[136:139], v[84:87], v[164:167], v[136:139]
	v_mfma_f32_16x16x32_bf16 v[124:127], v[68:71], v[172:175], v[124:127]
	v_mfma_f32_16x16x32_bf16 v[120:123], v[84:87], v[172:175], v[120:123]
	v_mfma_f32_16x16x32_bf16 v[108:111], v[68:71], v[180:183], v[108:111]
	v_mfma_f32_16x16x32_bf16 v[104:107], v[84:87], v[180:183], v[104:107]
	v_mfma_f32_16x16x32_bf16 v[92:95], v[68:71], v[188:191], v[92:95]
	v_mfma_f32_16x16x32_bf16 v[88:91], v[84:87], v[188:191], v[88:91]
	s_setprio 0
	s_setprio 1
	v_mfma_f32_16x16x32_bf16 v[132:135], v[144:147], v[160:163], v[132:135]
	v_mfma_f32_16x16x32_bf16 v[128:131], v[152:155], v[160:163], v[128:131]
	v_mfma_f32_16x16x32_bf16 v[116:119], v[144:147], v[168:171], v[116:119]
	v_mfma_f32_16x16x32_bf16 v[112:115], v[152:155], v[168:171], v[112:115]
	v_mfma_f32_16x16x32_bf16 v[100:103], v[144:147], v[176:179], v[100:103]
	v_mfma_f32_16x16x32_bf16 v[96:99], v[152:155], v[176:179], v[96:99]
	v_mfma_f32_16x16x32_bf16 v[76:79], v[144:147], v[184:187], v[76:79]
	v_mfma_f32_16x16x32_bf16 v[72:75], v[152:155], v[184:187], v[72:75]
	v_mfma_f32_16x16x32_bf16 v[132:135], v[148:151], v[164:167], v[132:135]
	v_mfma_f32_16x16x32_bf16 v[128:131], v[156:159], v[164:167], v[128:131]
	v_mfma_f32_16x16x32_bf16 v[116:119], v[148:151], v[172:175], v[116:119]
	v_mfma_f32_16x16x32_bf16 v[112:115], v[156:159], v[172:175], v[112:115]
	v_mfma_f32_16x16x32_bf16 v[100:103], v[148:151], v[180:183], v[100:103]
	v_mfma_f32_16x16x32_bf16 v[96:99], v[156:159], v[180:183], v[96:99]
	v_mfma_f32_16x16x32_bf16 v[76:79], v[148:151], v[188:191], v[76:79]
	v_mfma_f32_16x16x32_bf16 v[72:75], v[156:159], v[188:191], v[72:75]
	s_setprio 0
	s_barrier
	s_add_i32 s60, s73, s31
	v_lshl_add_u64 v[192:193], v[192:193], 0, s[40:41]
	s_mov_b32 m0, s60
	ds_read_b128 v[160:163], v238 offset:49152
	ds_read_b128 v[164:167], v238 offset:50176
	ds_read_b128 v[168:171], v238 offset:51200
	ds_read_b128 v[172:175], v238 offset:52224
	ds_read_b128 v[176:179], v238 offset:53248
	ds_read_b128 v[180:183], v238 offset:54272
	ds_read_b128 v[184:187], v238 offset:55296
	ds_read_b128 v[188:191], v238 offset:56320
	global_load_lds_dwordx4 v[192:193], off
	s_add_i32 m0, s60, 0x2000
	s_add_u32 s58, s58, 0x80080
	v_lshl_add_u64 v[192:193], v[194:195], 0, s[40:41]
	s_addc_u32 s59, s59, 0
	s_add_i32 s60, s74, s31
	global_load_lds_dwordx4 v[192:193], off
	v_lshl_add_u64 v[192:193], s[58:59], 0, v[202:203]
	s_mov_b32 m0, s60
	s_nop 0
	global_load_lds_dwordx4 v[192:193], off
	v_lshl_add_u64 v[192:193], s[58:59], 0, v[206:207]
	s_add_i32 m0, s60, 0x2000
	s_nop 0
	global_load_lds_dwordx4 v[192:193], off
	s_waitcnt vmcnt(6)
	s_waitcnt lgkmcnt(0)
	s_barrier
	s_setprio 1
	s_waitcnt lgkmcnt(0)
	v_mfma_f32_16x16x32_bf16 v[60:63], v[64:67], v[160:163], v[60:63]
	v_mfma_f32_16x16x32_bf16 v[56:59], v[80:83], v[160:163], v[56:59]
	v_mfma_f32_16x16x32_bf16 v[44:47], v[64:67], v[168:171], v[44:47]
	v_mfma_f32_16x16x32_bf16 v[40:43], v[80:83], v[168:171], v[40:43]
	v_mfma_f32_16x16x32_bf16 v[28:31], v[64:67], v[176:179], v[28:31]
	v_mfma_f32_16x16x32_bf16 v[24:27], v[80:83], v[176:179], v[24:27]
	v_mfma_f32_16x16x32_bf16 v[12:15], v[64:67], v[184:187], v[12:15]
	v_mfma_f32_16x16x32_bf16 v[8:11], v[80:83], v[184:187], v[8:11]
	v_mfma_f32_16x16x32_bf16 v[60:63], v[68:71], v[164:167], v[60:63]
	v_mfma_f32_16x16x32_bf16 v[56:59], v[84:87], v[164:167], v[56:59]
	v_mfma_f32_16x16x32_bf16 v[44:47], v[68:71], v[172:175], v[44:47]
	v_mfma_f32_16x16x32_bf16 v[40:43], v[84:87], v[172:175], v[40:43]
	v_mfma_f32_16x16x32_bf16 v[28:31], v[68:71], v[180:183], v[28:31]
	v_mfma_f32_16x16x32_bf16 v[24:27], v[84:87], v[180:183], v[24:27]
	v_mfma_f32_16x16x32_bf16 v[12:15], v[68:71], v[188:191], v[12:15]
	v_mfma_f32_16x16x32_bf16 v[8:11], v[84:87], v[188:191], v[8:11]
	s_setprio 0
	s_setprio 1
	v_mfma_f32_16x16x32_bf16 v[52:55], v[144:147], v[160:163], v[52:55]
	v_mfma_f32_16x16x32_bf16 v[48:51], v[152:155], v[160:163], v[48:51]
	v_mfma_f32_16x16x32_bf16 v[36:39], v[144:147], v[168:171], v[36:39]
	v_mfma_f32_16x16x32_bf16 v[32:35], v[152:155], v[168:171], v[32:35]
	v_mfma_f32_16x16x32_bf16 v[20:23], v[144:147], v[176:179], v[20:23]
	v_mfma_f32_16x16x32_bf16 v[16:19], v[152:155], v[176:179], v[16:19]
	v_mfma_f32_16x16x32_bf16 v[4:7], v[144:147], v[184:187], v[4:7]
	v_mfma_f32_16x16x32_bf16 v[0:3], v[152:155], v[184:187], v[0:3]
	v_mfma_f32_16x16x32_bf16 v[52:55], v[148:151], v[164:167], v[52:55]
	v_mfma_f32_16x16x32_bf16 v[48:51], v[156:159], v[164:167], v[48:51]
	v_mfma_f32_16x16x32_bf16 v[36:39], v[148:151], v[172:175], v[36:39]
	v_mfma_f32_16x16x32_bf16 v[32:35], v[156:159], v[172:175], v[32:35]
	v_mfma_f32_16x16x32_bf16 v[20:23], v[148:151], v[180:183], v[20:23]
	v_mfma_f32_16x16x32_bf16 v[16:19], v[156:159], v[180:183], v[16:19]
	v_mfma_f32_16x16x32_bf16 v[4:7], v[148:151], v[188:191], v[4:7]
	v_mfma_f32_16x16x32_bf16 v[0:3], v[156:159], v[188:191], v[0:3]
	s_setprio 0
	s_add_i32 s72, s72, 2
	s_add_u32 s56, s56, 0x100
	s_addc_u32 s57, s57, 0
	s_add_u32 s70, s70, 0x100
	s_addc_u32 s71, s71, 0
	s_cmp_gt_u32 s72, 29
	s_barrier
	s_cbranch_scc0 .LBB0_549
	s_and_b64 vcc, exec, s[42:43]
	s_cbranch_vccz .LBB0_552
	s_barrier

; #define PG8_STAGE(bufoff, gbase, voff) do { _Pragma("unroll") for (int _i = 0; _i < 2; ++_i) \
;         __builtin_amdgcn_global_load_lds((const unsigned*)((const char*)(gbase) + (voff)[_i]), (PG8_LAS unsigned*)(lds + (bufoff) + ldsw + _i * 8192), 16, 0, 0); } while (0)
; #define PG8_LDA(dst, b, h) do { _Pragma("unroll") for (int m = 0; m < 4; ++m) _Pragma("unroll") for (int k = 0; k < 2; ++k) dst[m][k] = *(const PG8_LAS bf16x8*)(lds + PG8_SA(b, h) + aoff + m * 2048 + k * 1024); } while (0)
; #define PG8_LDB(dst, b, h) do { _Pragma("unroll") for (int n = 0; n < 2; ++n) _Pragma("unroll") for (int k = 0; k < 2; ++k) dst[n][k] = *(const PG8_LAS bf16x8*)(lds + PG8_SB(b, h) + boff + n * 2048 + k * 1024); } while (0)
; #define PG8_MMA(ai, bj, At, Bt) do { __builtin_amdgcn_s_setprio(1); _Pragma("unroll") for (int m = 0; m < 4; ++m) _Pragma("unroll") for (int n = 0; n < 2; ++n) _Pragma("unroll") for (int k = 0; k < 2; ++k) \
;         acc[ai][bj][m][n] = __builtin_amdgcn_mfma_f32_16x16x32_bf16(Bt[n][k], At[m][k], acc[ai][bj][m][n], 0, 0, 0); __builtin_amdgcn_s_setprio(0); } while (0)
; #define PG8_WAIT_V(n) asm volatile("s_waitcnt vmcnt(" #n ")" ::: "memory")
; #define PG8_WAIT_L(n) asm volatile("s_waitcnt lgkmcnt(" #n ")" ::: "memory")
; #define PG8_BAR __builtin_amdgcn_s_barrier()
; template <class Epi, class Sched, bool ALIGN_EPI = false, bool SP2 = false>
; __device__ __forceinline__ void gemm_phase(PG8_LAS unsigned char* lds, const Gemm g, const Sched& S, const Epi& E, const int wid  ) {
;     ...
;         for (int t = 0; t < nt; t += 2) {
;             const bool last = (t == nt - 2);
;             const char* a1 = cA + (size_t)(t + 1) * kstep;
;             const char* a2 = last ? nA : cA + (size_t)(t + 2) * kstep; const char* b2 = last ? nB : cB + (size_t)(t + 2) * kstep;
;             const char* a3 = a2 + kstep; const char* b3 = b2 + kstep;
;             if (last && has_next) S.a_ready(nxt);
;             if constexpr (SP2) {
;             PG8_LDB(B0, 0, 0); PG8_LDB(B1, 0, 1); PG8_SCHED; PG8_LDA(At, 0, 0); PG8_STAGE(PG8_SA(1, 1), a1 + hstep, voffA);
;             PG8_WAIT_V(8); PG8_WAIT_L(0); PG8_BAR; PG8_MMA(0, 0, At, B0); PG8_MMA(0, 1, At, B1); PG8_BAR; PG8_SCHED;
;             PG8_LDA(At, 0, 1); PG8_STAGE(PG8_SB(0, 0), b2, voffB); PG8_STAGE(PG8_SB(0, 1), b2 + hstep, voffB); PG8_STAGE(PG8_SA(0, 0), a2, voffA);
.LBB0_687:
	s_add_u32 s100, s8, 0xfff80000
	s_addc_u32 s101, s9, -1
	ds_read_b128 v[144:147], v153
	ds_read_b128 v[158:161], v153 offset:1024
	ds_read_b128 v[162:165], v153 offset:2048
	ds_read_b128 v[166:169], v153 offset:3072
	ds_read_b128 v[170:173], v154
	ds_read_b128 v[174:177], v154 offset:1024
	ds_read_b128 v[178:181], v154 offset:2048
	ds_read_b128 v[182:185], v154 offset:3072
	s_add_u32 s10, s8, 0xfff80080
	s_addc_u32 s11, s9, -1
	s_cmp_eq_u32 s67, 28
	s_cselect_b32 s13, s14, s11
	s_cselect_b32 s12, s15, s10
	s_cselect_b32 s11, s47, s66
	s_cselect_b32 s10, s49, s65
	v_lshl_add_u64 v[222:223], s[100:101], 0, v[136:137]
	s_mov_b32 m0, s58
	v_lshl_add_u64 v[224:225], s[100:101], 0, v[138:139]
	global_load_lds_dwordx4 v[222:223], off
	s_mov_b32 m0, s59
	s_nop 0
	global_load_lds_dwordx4 v[224:225], off
	v_lshl_add_u64 v[218:219], s[8:9], 0, v[136:137]
	s_add_i32 m0, s37, 0xc000
	ds_read_b128 v[186:189], v155
	ds_read_b128 v[190:193], v155 offset:1024
	ds_read_b128 v[194:197], v155 offset:2048
	ds_read_b128 v[198:201], v155 offset:3072
	ds_read_b128 v[202:205], v155 offset:4096
	ds_read_b128 v[206:209], v155 offset:5120
	ds_read_b128 v[210:213], v155 offset:6144
	ds_read_b128 v[214:217], v155 offset:7168
	global_load_lds_dwordx4 v[218:219], off
	v_lshl_add_u64 v[218:219], s[8:9], 0, v[138:139]
	s_add_i32 m0, s37, 0xe000
	s_nop 0
	global_load_lds_dwordx4 v[218:219], off
	s_waitcnt vmcnt(8)
	s_waitcnt lgkmcnt(0)
	s_barrier
	s_setprio 1
	s_waitcnt lgkmcnt(0)
	v_mfma_f32_16x16x32_bf16 v[124:127], v[144:147], v[186:189], v[124:127]
	v_mfma_f32_16x16x32_bf16 v[120:123], v[162:165], v[186:189], v[120:123]
	v_mfma_f32_16x16x32_bf16 v[108:111], v[144:147], v[194:197], v[108:111]
	v_mfma_f32_16x16x32_bf16 v[104:107], v[162:165], v[194:197], v[104:107]
	v_mfma_f32_16x16x32_bf16 v[92:95], v[144:147], v[202:205], v[92:95]
	v_mfma_f32_16x16x32_bf16 v[88:91], v[162:165], v[202:205], v[88:91]
	v_mfma_f32_16x16x32_bf16 v[76:79], v[144:147], v[210:213], v[76:79]
	v_mfma_f32_16x16x32_bf16 v[72:75], v[162:165], v[210:213], v[72:75]
	v_mfma_f32_16x16x32_bf16 v[124:127], v[158:161], v[190:193], v[124:127]
	v_mfma_f32_16x16x32_bf16 v[120:123], v[166:169], v[190:193], v[120:123]
	v_mfma_f32_16x16x32_bf16 v[108:111], v[158:161], v[198:201], v[108:111]
	v_mfma_f32_16x16x32_bf16 v[104:107], v[166:169], v[198:201], v[104:107]
	v_mfma_f32_16x16x32_bf16 v[92:95], v[158:161], v[206:209], v[92:95]
	v_mfma_f32_16x16x32_bf16 v[88:91], v[166:169], v[206:209], v[88:91]
	v_mfma_f32_16x16x32_bf16 v[76:79], v[158:161], v[214:217], v[76:79]
	v_mfma_f32_16x16x32_bf16 v[72:75], v[166:169], v[214:217], v[72:75]
	s_setprio 0
	s_setprio 1
	v_mfma_f32_16x16x32_bf16 v[116:119], v[170:173], v[186:189], v[116:119]
	v_mfma_f32_16x16x32_bf16 v[112:115], v[178:181], v[186:189], v[112:115]
	v_mfma_f32_16x16x32_bf16 v[100:103], v[170:173], v[194:197], v[100:103]
	v_mfma_f32_16x16x32_bf16 v[96:99], v[178:181], v[194:197], v[96:99]
	v_mfma_f32_16x16x32_bf16 v[84:87], v[170:173], v[202:205], v[84:87]
	v_mfma_f32_16x16x32_bf16 v[80:83], v[178:181], v[202:205], v[80:83]
	v_mfma_f32_16x16x32_bf16 v[68:71], v[170:173], v[210:213], v[68:71]
	v_mfma_f32_16x16x32_bf16 v[64:67], v[178:181], v[210:213], v[64:67]
	v_mfma_f32_16x16x32_bf16 v[116:119], v[174:177], v[190:193], v[116:119]
	v_mfma_f32_16x16x32_bf16 v[112:115], v[182:185], v[190:193], v[112:115]
	v_mfma_f32_16x16x32_bf16 v[100:103], v[174:177], v[198:201], v[100:103]
	v_mfma_f32_16x16x32_bf16 v[96:99], v[182:185], v[198:201], v[96:99]
	v_mfma_f32_16x16x32_bf16 v[84:87], v[174:177], v[206:209], v[84:87]
	v_mfma_f32_16x16x32_bf16 v[80:83], v[182:185], v[206:209], v[80:83]
	v_mfma_f32_16x16x32_bf16 v[68:71], v[174:177], v[214:217], v[68:71]
	v_mfma_f32_16x16x32_bf16 v[64:67], v[182:185], v[214:217], v[64:67]
	s_setprio 0
	s_barrier
	s_add_i32 s68, s61, s31
	v_lshl_add_u64 v[218:219], s[10:11], 0, v[132:133]
	s_mov_b32 m0, s68
	ds_read_b128 v[186:189], v155 offset:16384
	ds_read_b128 v[190:193], v155 offset:17408
	ds_read_b128 v[194:197], v155 offset:18432
	ds_read_b128 v[198:201], v155 offset:19456
	ds_read_b128 v[202:205], v155 offset:20480
	ds_read_b128 v[206:209], v155 offset:21504
	ds_read_b128 v[210:213], v155 offset:22528
	ds_read_b128 v[214:217], v155 offset:23552
	global_load_lds_dwordx4 v[218:219], off
	s_add_i32 m0, s68, 0x2000
	s_add_u32 s68, s10, 0x80000
	v_lshl_add_u64 v[220:221], s[10:11], 0, v[128:129]
	s_addc_u32 s69, s11, 0
	s_add_i32 s70, s62, s31
	global_load_lds_dwordx4 v[220:221], off
	v_lshl_add_u64 v[222:223], s[68:69], 0, v[132:133]
	s_mov_b32 m0, s70
	s_nop 0
	global_load_lds_dwordx4 v[222:223], off
	v_lshl_add_u64 v[222:223], s[68:69], 0, v[128:129]
	s_add_i32 m0, s70, 0x2000
	s_nop 0
	global_load_lds_dwordx4 v[222:223], off
	s_waitcnt vmcnt(6)
	s_waitcnt lgkmcnt(0)
	s_barrier
; #define PG8_STAGE(bufoff, gbase, voff) do { _Pragma("unroll") for (int _i = 0; _i < 2; ++_i) \
;         __builtin_amdgcn_global_load_lds((const unsigned*)((const char*)(gbase) + (voff)[_i]), (PG8_LAS unsigned*)(lds + (bufoff) + ldsw + _i * 8192), 16, 0, 0); } while (0)
; #define PG8_LDA(dst, b, h) do { _Pragma("unroll") for (int m = 0; m < 4; ++m) _Pragma("unroll") for (int k = 0; k < 2; ++k) dst[m][k] = *(const PG8_LAS bf16x8*)(lds + PG8_SA(b, h) + aoff + m * 2048 + k * 1024); } while (0)
; #define PG8_LDB(dst, b, h) do { _Pragma("unroll") for (int n = 0; n < 2; ++n) _Pragma("unroll") for (int k = 0; k < 2; ++k) dst[n][k] = *(const PG8_LAS bf16x8*)(lds + PG8_SB(b, h) + boff + n * 2048 + k * 1024); } while (0)
; #define PG8_MMA(ai, bj, At, Bt) do { __builtin_amdgcn_s_setprio(1); _Pragma("unroll") for (int m = 0; m < 4; ++m) _Pragma("unroll") for (int n = 0; n < 2; ++n) _Pragma("unroll") for (int k = 0; k < 2; ++k) \
;         acc[ai][bj][m][n] = __builtin_amdgcn_mfma_f32_16x16x32_bf16(Bt[n][k], At[m][k], acc[ai][bj][m][n], 0, 0, 0); __builtin_amdgcn_s_setprio(0); } while (0)
; #define PG8_WAIT_V(n) asm volatile("s_waitcnt vmcnt(" #n ")" ::: "memory")
; #define PG8_WAIT_L(n) asm volatile("s_waitcnt lgkmcnt(" #n ")" ::: "memory")
; #define PG8_BAR __builtin_amdgcn_s_barrier()
; #define PG8_SCHED __builtin_amdgcn_sched_barrier(0)
; template <class Epi, class Sched, bool ALIGN_EPI = false, bool SP2 = false>
; __device__ __forceinline__ void gemm_phase(PG8_LAS unsigned char* lds, const Gemm g, const Sched& S, const Epi& E, const int wid  ) {
;     ...
;             PG8_WAIT_V(8); PG8_WAIT_L(0); PG8_BAR; PG8_MMA(1, 0, At, B0); PG8_MMA(1, 1, At, B1); PG8_BAR; PG8_SCHED;
;             PG8_LDB(B0, 1, 0); PG8_LDB(B1, 1, 1); PG8_SCHED; PG8_LDA(At, 1, 0); PG8_STAGE(PG8_SA(0, 1), a2 + hstep, voffA);
;             PG8_WAIT_V(8); PG8_WAIT_L(0); PG8_BAR; PG8_MMA(0, 0, At, B0); PG8_MMA(0, 1, At, B1); PG8_BAR; PG8_SCHED;
	s_setprio 1
	s_waitcnt lgkmcnt(0)
	v_mfma_f32_16x16x32_bf16 v[60:63], v[144:147], v[186:189], v[60:63]
	v_mfma_f32_16x16x32_bf16 v[56:59], v[162:165], v[186:189], v[56:59]
	v_mfma_f32_16x16x32_bf16 v[44:47], v[144:147], v[194:197], v[44:47]
	v_mfma_f32_16x16x32_bf16 v[40:43], v[162:165], v[194:197], v[40:43]
	v_mfma_f32_16x16x32_bf16 v[28:31], v[144:147], v[202:205], v[28:31]
	v_mfma_f32_16x16x32_bf16 v[24:27], v[162:165], v[202:205], v[24:27]
	v_mfma_f32_16x16x32_bf16 v[12:15], v[144:147], v[210:213], v[12:15]
	v_mfma_f32_16x16x32_bf16 v[8:11], v[162:165], v[210:213], v[8:11]
	v_mfma_f32_16x16x32_bf16 v[60:63], v[158:161], v[190:193], v[60:63]
	v_mfma_f32_16x16x32_bf16 v[56:59], v[166:169], v[190:193], v[56:59]
	v_mfma_f32_16x16x32_bf16 v[44:47], v[158:161], v[198:201], v[44:47]
	v_mfma_f32_16x16x32_bf16 v[40:43], v[166:169], v[198:201], v[40:43]
	v_mfma_f32_16x16x32_bf16 v[28:31], v[158:161], v[206:209], v[28:31]
	v_mfma_f32_16x16x32_bf16 v[24:27], v[166:169], v[206:209], v[24:27]
	v_mfma_f32_16x16x32_bf16 v[12:15], v[158:161], v[214:217], v[12:15]
	v_mfma_f32_16x16x32_bf16 v[8:11], v[166:169], v[214:217], v[8:11]
	s_setprio 0
	s_setprio 1
	v_mfma_f32_16x16x32_bf16 v[52:55], v[170:173], v[186:189], v[52:55]
	v_mfma_f32_16x16x32_bf16 v[48:51], v[178:181], v[186:189], v[48:51]
	v_mfma_f32_16x16x32_bf16 v[36:39], v[170:173], v[194:197], v[36:39]
	v_mfma_f32_16x16x32_bf16 v[32:35], v[178:181], v[194:197], v[32:35]
	v_mfma_f32_16x16x32_bf16 v[20:23], v[170:173], v[202:205], v[20:23]
	v_mfma_f32_16x16x32_bf16 v[16:19], v[178:181], v[202:205], v[16:19]
	v_mfma_f32_16x16x32_bf16 v[4:7], v[170:173], v[210:213], v[4:7]
	v_mfma_f32_16x16x32_bf16 v[0:3], v[178:181], v[210:213], v[0:3]
	v_mfma_f32_16x16x32_bf16 v[52:55], v[174:177], v[190:193], v[52:55]
	v_mfma_f32_16x16x32_bf16 v[48:51], v[182:185], v[190:193], v[48:51]
	v_mfma_f32_16x16x32_bf16 v[36:39], v[174:177], v[198:201], v[36:39]
	v_mfma_f32_16x16x32_bf16 v[32:35], v[182:185], v[198:201], v[32:35]
	v_mfma_f32_16x16x32_bf16 v[20:23], v[174:177], v[206:209], v[20:23]
	v_mfma_f32_16x16x32_bf16 v[16:19], v[182:185], v[206:209], v[16:19]
	v_mfma_f32_16x16x32_bf16 v[4:7], v[174:177], v[214:217], v[4:7]
	v_mfma_f32_16x16x32_bf16 v[0:3], v[182:185], v[214:217], v[0:3]
	s_setprio 0
	s_barrier
	s_add_i32 s68, 0, 0x18000
	v_add_u32_e32 v148, s68, v151
	s_add_i32 s69, 0, 0x1c000
	ds_read_b128 v[144:147], v148
	ds_read_b128 v[158:161], v148 offset:1024
	ds_read_b128 v[162:165], v148 offset:2048
	ds_read_b128 v[166:169], v148 offset:3072
	v_add_u32_e32 v148, s69, v151
	ds_read_b128 v[170:173], v148
	ds_read_b128 v[174:177], v148 offset:1024
	ds_read_b128 v[178:181], v148 offset:2048
	ds_read_b128 v[182:185], v148 offset:3072
	v_lshl_add_u64 v[222:223], s[12:13], 0, v[134:135]
	s_mov_b32 m0, s37
	v_lshl_add_u64 v[224:225], s[12:13], 0, v[130:131]
	global_load_lds_dwordx4 v[222:223], off
	s_mov_b32 m0, s54
	s_nop 0
	global_load_lds_dwordx4 v[224:225], off
	s_add_u32 s12, s12, 0x80000
	s_addc_u32 s13, s13, 0
	s_mov_b32 m0, s55
	v_lshl_add_u64 v[226:227], s[12:13], 0, v[134:135]
	ds_read_b128 v[186:189], v155 offset:32768
	ds_read_b128 v[190:193], v155 offset:33792
	ds_read_b128 v[194:197], v155 offset:34816
	ds_read_b128 v[198:201], v155 offset:35840
	ds_read_b128 v[202:205], v155 offset:36864
	ds_read_b128 v[206:209], v155 offset:37888
	ds_read_b128 v[210:213], v155 offset:38912
	ds_read_b128 v[214:217], v155 offset:39936
	global_load_lds_dwordx4 v[226:227], off
	v_lshl_add_u64 v[226:227], s[12:13], 0, v[130:131]
	s_mov_b32 m0, s56
	s_nop 0
	global_load_lds_dwordx4 v[226:227], off
	s_waitcnt vmcnt(8)
	s_waitcnt lgkmcnt(0)
	s_barrier
; #define PG8_STAGE(bufoff, gbase, voff) do { _Pragma("unroll") for (int _i = 0; _i < 2; ++_i) \
;         __builtin_amdgcn_global_load_lds((const unsigned*)((const char*)(gbase) + (voff)[_i]), (PG8_LAS unsigned*)(lds + (bufoff) + ldsw + _i * 8192), 16, 0, 0); } while (0)
; #define PG8_LDA(dst, b, h) do { _Pragma("unroll") for (int m = 0; m < 4; ++m) _Pragma("unroll") for (int k = 0; k < 2; ++k) dst[m][k] = *(const PG8_LAS bf16x8*)(lds + PG8_SA(b, h) + aoff + m * 2048 + k * 1024); } while (0)
; #define PG8_MMA(ai, bj, At, Bt) do { __builtin_amdgcn_s_setprio(1); _Pragma("unroll") for (int m = 0; m < 4; ++m) _Pragma("unroll") for (int n = 0; n < 2; ++n) _Pragma("unroll") for (int k = 0; k < 2; ++k) \
;         acc[ai][bj][m][n] = __builtin_amdgcn_mfma_f32_16x16x32_bf16(Bt[n][k], At[m][k], acc[ai][bj][m][n], 0, 0, 0); __builtin_amdgcn_s_setprio(0); } while (0)
; #define PG8_WAIT_V(n) asm volatile("s_waitcnt vmcnt(" #n ")" ::: "memory")
; #define PG8_WAIT_L(n) asm volatile("s_waitcnt lgkmcnt(" #n ")" ::: "memory")
; #define PG8_BAR __builtin_amdgcn_s_barrier()
; #define PG8_SCHED __builtin_amdgcn_sched_barrier(0)
; template <class Epi, class Sched, bool ALIGN_EPI = false, bool SP2 = false>
; __device__ __forceinline__ void gemm_phase(PG8_LAS unsigned char* lds, const Gemm g, const Sched& S, const Epi& E, const int wid  ) {
;     ...
;             PG8_WAIT_V(8); PG8_WAIT_L(0); PG8_BAR; PG8_MMA(0, 0, At, B0); PG8_MMA(0, 1, At, B1); PG8_BAR; PG8_SCHED;
;             PG8_LDA(At, 1, 1); PG8_STAGE(PG8_SB(1, 0), b3, voffB); PG8_STAGE(PG8_SB(1, 1), b3 + hstep, voffB); PG8_STAGE(PG8_SA(1, 0), a3, voffA);
;             PG8_WAIT_V(8); PG8_WAIT_L(0); PG8_BAR; PG8_MMA(1, 0, At, B0); PG8_MMA(1, 1, At, B1); PG8_BAR; PG8_SCHED;
	s_setprio 1
	s_waitcnt lgkmcnt(0)
	v_mfma_f32_16x16x32_bf16 v[124:127], v[144:147], v[186:189], v[124:127]
	v_mfma_f32_16x16x32_bf16 v[120:123], v[162:165], v[186:189], v[120:123]
	v_mfma_f32_16x16x32_bf16 v[108:111], v[144:147], v[194:197], v[108:111]
	v_mfma_f32_16x16x32_bf16 v[104:107], v[162:165], v[194:197], v[104:107]
	v_mfma_f32_16x16x32_bf16 v[92:95], v[144:147], v[202:205], v[92:95]
	v_mfma_f32_16x16x32_bf16 v[88:91], v[162:165], v[202:205], v[88:91]
	v_mfma_f32_16x16x32_bf16 v[76:79], v[144:147], v[210:213], v[76:79]
	v_mfma_f32_16x16x32_bf16 v[72:75], v[162:165], v[210:213], v[72:75]
	v_mfma_f32_16x16x32_bf16 v[124:127], v[158:161], v[190:193], v[124:127]
	v_mfma_f32_16x16x32_bf16 v[120:123], v[166:169], v[190:193], v[120:123]
	v_mfma_f32_16x16x32_bf16 v[108:111], v[158:161], v[198:201], v[108:111]
	v_mfma_f32_16x16x32_bf16 v[104:107], v[166:169], v[198:201], v[104:107]
	v_mfma_f32_16x16x32_bf16 v[92:95], v[158:161], v[206:209], v[92:95]
	v_mfma_f32_16x16x32_bf16 v[88:91], v[166:169], v[206:209], v[88:91]
	v_mfma_f32_16x16x32_bf16 v[76:79], v[158:161], v[214:217], v[76:79]
	v_mfma_f32_16x16x32_bf16 v[72:75], v[166:169], v[214:217], v[72:75]
	s_setprio 0
	s_setprio 1
	v_mfma_f32_16x16x32_bf16 v[116:119], v[170:173], v[186:189], v[116:119]
	v_mfma_f32_16x16x32_bf16 v[112:115], v[178:181], v[186:189], v[112:115]
	v_mfma_f32_16x16x32_bf16 v[100:103], v[170:173], v[194:197], v[100:103]
	v_mfma_f32_16x16x32_bf16 v[96:99], v[178:181], v[194:197], v[96:99]
	v_mfma_f32_16x16x32_bf16 v[84:87], v[170:173], v[202:205], v[84:87]
	v_mfma_f32_16x16x32_bf16 v[80:83], v[178:181], v[202:205], v[80:83]
	v_mfma_f32_16x16x32_bf16 v[68:71], v[170:173], v[210:213], v[68:71]
	v_mfma_f32_16x16x32_bf16 v[64:67], v[178:181], v[210:213], v[64:67]
	v_mfma_f32_16x16x32_bf16 v[116:119], v[174:177], v[190:193], v[116:119]
	v_mfma_f32_16x16x32_bf16 v[112:115], v[182:185], v[190:193], v[112:115]
	v_mfma_f32_16x16x32_bf16 v[100:103], v[174:177], v[198:201], v[100:103]
	v_mfma_f32_16x16x32_bf16 v[96:99], v[182:185], v[198:201], v[96:99]
	v_mfma_f32_16x16x32_bf16 v[84:87], v[174:177], v[206:209], v[84:87]
	v_mfma_f32_16x16x32_bf16 v[80:83], v[182:185], v[206:209], v[80:83]
	v_mfma_f32_16x16x32_bf16 v[68:71], v[174:177], v[214:217], v[68:71]
	v_mfma_f32_16x16x32_bf16 v[64:67], v[182:185], v[214:217], v[64:67]
	s_setprio 0
	s_barrier
	s_add_i32 s12, s68, s31
	v_lshl_add_u64 v[218:219], v[218:219], 0, s[42:43]
	s_mov_b32 m0, s12
	ds_read_b128 v[186:189], v155 offset:49152
	ds_read_b128 v[190:193], v155 offset:50176
	ds_read_b128 v[194:197], v155 offset:51200
	ds_read_b128 v[198:201], v155 offset:52224
	ds_read_b128 v[202:205], v155 offset:53248
	ds_read_b128 v[206:209], v155 offset:54272
	ds_read_b128 v[210:213], v155 offset:55296
	ds_read_b128 v[214:217], v155 offset:56320
	global_load_lds_dwordx4 v[218:219], off
	s_add_i32 m0, s12, 0x2000
	s_add_u32 s10, s10, 0x80080
	v_lshl_add_u64 v[218:219], v[220:221], 0, s[42:43]
	s_addc_u32 s11, s11, 0
	s_add_i32 s12, s69, s31
	global_load_lds_dwordx4 v[218:219], off
	v_lshl_add_u64 v[218:219], s[10:11], 0, v[132:133]
	s_mov_b32 m0, s12
	s_nop 0
	global_load_lds_dwordx4 v[218:219], off
	v_lshl_add_u64 v[218:219], s[10:11], 0, v[128:129]
	s_add_i32 m0, s12, 0x2000
	s_nop 0
	global_load_lds_dwordx4 v[218:219], off
	s_waitcnt vmcnt(6)
	s_waitcnt lgkmcnt(0)
	s_barrier
	s_setprio 1
	s_waitcnt lgkmcnt(0)
	v_mfma_f32_16x16x32_bf16 v[60:63], v[144:147], v[186:189], v[60:63]
	v_mfma_f32_16x16x32_bf16 v[56:59], v[162:165], v[186:189], v[56:59]
	v_mfma_f32_16x16x32_bf16 v[44:47], v[144:147], v[194:197], v[44:47]
	v_mfma_f32_16x16x32_bf16 v[40:43], v[162:165], v[194:197], v[40:43]
	v_mfma_f32_16x16x32_bf16 v[28:31], v[144:147], v[202:205], v[28:31]
	v_mfma_f32_16x16x32_bf16 v[24:27], v[162:165], v[202:205], v[24:27]
	v_mfma_f32_16x16x32_bf16 v[12:15], v[144:147], v[210:213], v[12:15]
	v_mfma_f32_16x16x32_bf16 v[8:11], v[162:165], v[210:213], v[8:11]
	v_mfma_f32_16x16x32_bf16 v[60:63], v[158:161], v[190:193], v[60:63]
	v_mfma_f32_16x16x32_bf16 v[56:59], v[166:169], v[190:193], v[56:59]
	v_mfma_f32_16x16x32_bf16 v[44:47], v[158:161], v[198:201], v[44:47]
	v_mfma_f32_16x16x32_bf16 v[40:43], v[166:169], v[198:201], v[40:43]
	v_mfma_f32_16x16x32_bf16 v[28:31], v[158:161], v[206:209], v[28:31]
	v_mfma_f32_16x16x32_bf16 v[24:27], v[166:169], v[206:209], v[24:27]
	v_mfma_f32_16x16x32_bf16 v[12:15], v[158:161], v[214:217], v[12:15]
	v_mfma_f32_16x16x32_bf16 v[8:11], v[166:169], v[214:217], v[8:11]
	s_setprio 0
	s_setprio 1
	v_mfma_f32_16x16x32_bf16 v[52:55], v[170:173], v[186:189], v[52:55]
	v_mfma_f32_16x16x32_bf16 v[48:51], v[178:181], v[186:189], v[48:51]
	v_mfma_f32_16x16x32_bf16 v[36:39], v[170:173], v[194:197], v[36:39]
	v_mfma_f32_16x16x32_bf16 v[32:35], v[178:181], v[194:197], v[32:35]
	v_mfma_f32_16x16x32_bf16 v[20:23], v[170:173], v[202:205], v[20:23]
	v_mfma_f32_16x16x32_bf16 v[16:19], v[178:181], v[202:205], v[16:19]
	v_mfma_f32_16x16x32_bf16 v[4:7], v[170:173], v[210:213], v[4:7]
	v_mfma_f32_16x16x32_bf16 v[0:3], v[178:181], v[210:213], v[0:3]
	v_mfma_f32_16x16x32_bf16 v[52:55], v[174:177], v[190:193], v[52:55]
	v_mfma_f32_16x16x32_bf16 v[48:51], v[182:185], v[190:193], v[48:51]
	v_mfma_f32_16x16x32_bf16 v[36:39], v[174:177], v[198:201], v[36:39]
	v_mfma_f32_16x16x32_bf16 v[32:35], v[182:185], v[198:201], v[32:35]
	v_mfma_f32_16x16x32_bf16 v[20:23], v[174:177], v[206:209], v[20:23]
	v_mfma_f32_16x16x32_bf16 v[16:19], v[182:185], v[206:209], v[16:19]
	v_mfma_f32_16x16x32_bf16 v[4:7], v[174:177], v[214:217], v[4:7]
	v_mfma_f32_16x16x32_bf16 v[0:3], v[182:185], v[214:217], v[0:3]
	s_setprio 0
	s_add_i32 s67, s67, 2
	s_add_u32 s8, s8, 0x100
	s_addc_u32 s9, s9, 0
	s_add_u32 s65, s65, 0x100
	s_addc_u32 s66, s66, 0
	s_cmp_gt_u32 s67, 29
	s_barrier
	s_cbranch_scc0 .LBB0_687
	s_and_b64 vcc, exec, s[44:45]
	s_cbranch_vccz .LBB0_690
	s_barrier

; #define PG8_STAGE(bufoff, gbase, voff) do { _Pragma("unroll") for (int _i = 0; _i < 2; ++_i) \
;         __builtin_amdgcn_global_load_lds((const unsigned*)((const char*)(gbase) + (voff)[_i]), (PG8_LAS unsigned*)(lds + (bufoff) + ldsw + _i * 8192), 16, 0, 0); } while (0)
; #define PG8_LDA(dst, b, h) do { _Pragma("unroll") for (int m = 0; m < 4; ++m) _Pragma("unroll") for (int k = 0; k < 2; ++k) dst[m][k] = *(const PG8_LAS bf16x8*)(lds + PG8_SA(b, h) + aoff + m * 2048 + k * 1024); } while (0)
; #define PG8_LDB(dst, b, h) do { _Pragma("unroll") for (int n = 0; n < 2; ++n) _Pragma("unroll") for (int k = 0; k < 2; ++k) dst[n][k] = *(const PG8_LAS bf16x8*)(lds + PG8_SB(b, h) + boff + n * 2048 + k * 1024); } while (0)
; #define PG8_MMA(ai, bj, At, Bt) do { __builtin_amdgcn_s_setprio(1); _Pragma("unroll") for (int m = 0; m < 4; ++m) _Pragma("unroll") for (int n = 0; n < 2; ++n) _Pragma("unroll") for (int k = 0; k < 2; ++k) \
;         acc[ai][bj][m][n] = __builtin_amdgcn_mfma_f32_16x16x32_bf16(Bt[n][k], At[m][k], acc[ai][bj][m][n], 0, 0, 0); __builtin_amdgcn_s_setprio(0); } while (0)
; #define PG8_WAIT_V(n) asm volatile("s_waitcnt vmcnt(" #n ")" ::: "memory")
; #define PG8_WAIT_L(n) asm volatile("s_waitcnt lgkmcnt(" #n ")" ::: "memory")
; #define PG8_BAR __builtin_amdgcn_s_barrier()
; template <class Epi, class Sched, bool ALIGN_EPI = false, bool SP2 = false>
; __device__ __forceinline__ void gemm_phase(PG8_LAS unsigned char* lds, const Gemm g, const Sched& S, const Epi& E, const int wid  ) {
;     ...
;         for (int t = 0; t < nt; t += 2) {
;             const bool last = (t == nt - 2);
;             const char* a1 = cA + (size_t)(t + 1) * kstep;
;             const char* a2 = last ? nA : cA + (size_t)(t + 2) * kstep; const char* b2 = last ? nB : cB + (size_t)(t + 2) * kstep;
;             const char* a3 = a2 + kstep; const char* b3 = b2 + kstep;
;             if (last && has_next) S.a_ready(nxt);
;             if constexpr (SP2) {
;             PG8_LDB(B0, 0, 0); PG8_LDB(B1, 0, 1); PG8_SCHED; PG8_LDA(At, 0, 0); PG8_STAGE(PG8_SA(1, 1), a1 + hstep, voffA);
;             PG8_WAIT_V(8); PG8_WAIT_L(0); PG8_BAR; PG8_MMA(0, 0, At, B0); PG8_MMA(0, 1, At, B1); PG8_BAR; PG8_SCHED;
;             PG8_LDA(At, 0, 1); PG8_STAGE(PG8_SB(0, 0), b2, voffB); PG8_STAGE(PG8_SB(0, 1), b2 + hstep, voffB); PG8_STAGE(PG8_SA(0, 0), a2, voffA);
.LBB0_780:
	s_add_u32 s100, s46, 0xffea0000
	s_addc_u32 s101, s47, -1
	ds_read_b128 v[72:75], v200
	ds_read_b128 v[76:79], v200 offset:1024
	ds_read_b128 v[88:91], v200 offset:2048
	ds_read_b128 v[92:95], v200 offset:3072
	ds_read_b128 v[144:147], v201
	ds_read_b128 v[148:151], v201 offset:1024
	ds_read_b128 v[152:155], v201 offset:2048
	ds_read_b128 v[156:159], v201 offset:3072
	s_add_u32 s48, s46, 0x100
	s_addc_u32 s49, s47, 0
	s_cmpk_eq_i32 s68, 0x54
	s_cselect_b32 s53, s9, s49
	s_cselect_b32 s52, s8, s48
	s_cselect_b32 s51, s45, s67
	s_cselect_b32 s50, s44, s66
	v_lshl_add_u64 v[220:221], s[100:101], 0, v[176:177]
	s_mov_b32 m0, s56
	v_lshl_add_u64 v[222:223], s[100:101], 0, v[178:179]
	global_load_lds_dwordx4 v[220:221], off
	s_mov_b32 m0, s57
	s_nop 0
	global_load_lds_dwordx4 v[222:223], off
	v_lshl_add_u64 v[216:217], s[46:47], 0, v[176:177]
	s_add_i32 m0, s34, 0xc000
	ds_read_b128 v[160:163], v202
	ds_read_b128 v[164:167], v202 offset:1024
	ds_read_b128 v[184:187], v202 offset:2048
	ds_read_b128 v[188:191], v202 offset:3072
	ds_read_b128 v[192:195], v202 offset:4096
	ds_read_b128 v[204:207], v202 offset:5120
	ds_read_b128 v[208:211], v202 offset:6144
	ds_read_b128 v[212:215], v202 offset:7168
	global_load_lds_dwordx4 v[216:217], off
	v_lshl_add_u64 v[216:217], s[46:47], 0, v[178:179]
	s_add_i32 m0, s34, 0xe000
	s_nop 0
	global_load_lds_dwordx4 v[216:217], off
	s_waitcnt vmcnt(8)
	s_waitcnt lgkmcnt(0)
	s_barrier
	s_setprio 1
	s_waitcnt lgkmcnt(0)
	v_mfma_f32_16x16x32_bf16 v[140:143], v[72:75], v[160:163], v[140:143]
	v_mfma_f32_16x16x32_bf16 v[136:139], v[88:91], v[160:163], v[136:139]
	v_mfma_f32_16x16x32_bf16 v[124:127], v[72:75], v[184:187], v[124:127]
	v_mfma_f32_16x16x32_bf16 v[120:123], v[88:91], v[184:187], v[120:123]
	v_mfma_f32_16x16x32_bf16 v[108:111], v[72:75], v[192:195], v[108:111]
	v_mfma_f32_16x16x32_bf16 v[104:107], v[88:91], v[192:195], v[104:107]
	v_mfma_f32_16x16x32_bf16 v[84:87], v[72:75], v[208:211], v[84:87]
	v_mfma_f32_16x16x32_bf16 v[80:83], v[88:91], v[208:211], v[80:83]
	v_mfma_f32_16x16x32_bf16 v[140:143], v[76:79], v[164:167], v[140:143]
	v_mfma_f32_16x16x32_bf16 v[136:139], v[92:95], v[164:167], v[136:139]
	v_mfma_f32_16x16x32_bf16 v[124:127], v[76:79], v[188:191], v[124:127]
	v_mfma_f32_16x16x32_bf16 v[120:123], v[92:95], v[188:191], v[120:123]
	v_mfma_f32_16x16x32_bf16 v[108:111], v[76:79], v[204:207], v[108:111]
	v_mfma_f32_16x16x32_bf16 v[104:107], v[92:95], v[204:207], v[104:107]
	v_mfma_f32_16x16x32_bf16 v[84:87], v[76:79], v[212:215], v[84:87]
	v_mfma_f32_16x16x32_bf16 v[80:83], v[92:95], v[212:215], v[80:83]
	s_setprio 0
	s_setprio 1
	v_mfma_f32_16x16x32_bf16 v[132:135], v[144:147], v[160:163], v[132:135]
	v_mfma_f32_16x16x32_bf16 v[128:131], v[152:155], v[160:163], v[128:131]
	v_mfma_f32_16x16x32_bf16 v[116:119], v[144:147], v[184:187], v[116:119]
	v_mfma_f32_16x16x32_bf16 v[112:115], v[152:155], v[184:187], v[112:115]
	v_mfma_f32_16x16x32_bf16 v[100:103], v[144:147], v[192:195], v[100:103]
	v_mfma_f32_16x16x32_bf16 v[96:99], v[152:155], v[192:195], v[96:99]
	v_mfma_f32_16x16x32_bf16 v[68:71], v[144:147], v[208:211], v[68:71]
	v_mfma_f32_16x16x32_bf16 v[64:67], v[152:155], v[208:211], v[64:67]
	v_mfma_f32_16x16x32_bf16 v[132:135], v[148:151], v[164:167], v[132:135]
	v_mfma_f32_16x16x32_bf16 v[128:131], v[156:159], v[164:167], v[128:131]
	v_mfma_f32_16x16x32_bf16 v[116:119], v[148:151], v[188:191], v[116:119]
	v_mfma_f32_16x16x32_bf16 v[112:115], v[156:159], v[188:191], v[112:115]
	v_mfma_f32_16x16x32_bf16 v[100:103], v[148:151], v[204:207], v[100:103]
	v_mfma_f32_16x16x32_bf16 v[96:99], v[156:159], v[204:207], v[96:99]
	v_mfma_f32_16x16x32_bf16 v[68:71], v[148:151], v[212:215], v[68:71]
	v_mfma_f32_16x16x32_bf16 v[64:67], v[156:159], v[212:215], v[64:67]
	s_setprio 0
	s_barrier
	s_add_i32 s46, s60, s31
	v_lshl_add_u64 v[216:217], s[50:51], 0, v[170:171]
	s_mov_b32 m0, s46
	ds_read_b128 v[160:163], v202 offset:16384
	ds_read_b128 v[164:167], v202 offset:17408
	ds_read_b128 v[184:187], v202 offset:18432
	ds_read_b128 v[188:191], v202 offset:19456
	ds_read_b128 v[192:195], v202 offset:20480
	ds_read_b128 v[204:207], v202 offset:21504
	ds_read_b128 v[208:211], v202 offset:22528
	ds_read_b128 v[212:215], v202 offset:23552
	global_load_lds_dwordx4 v[216:217], off
	s_add_i32 m0, s46, 0x2000
	s_add_u32 s46, s50, 0x160000
	v_lshl_add_u64 v[218:219], s[50:51], 0, v[174:175]
	s_addc_u32 s47, s51, 0
	s_add_i32 s69, s61, s31
	global_load_lds_dwordx4 v[218:219], off
	v_lshl_add_u64 v[220:221], s[46:47], 0, v[170:171]
	s_mov_b32 m0, s69
	s_nop 0
	global_load_lds_dwordx4 v[220:221], off
	v_lshl_add_u64 v[220:221], s[46:47], 0, v[174:175]
	s_add_i32 m0, s69, 0x2000
	s_nop 0
	global_load_lds_dwordx4 v[220:221], off
	s_waitcnt vmcnt(6)
	s_waitcnt lgkmcnt(0)
	s_barrier
; #define PG8_STAGE(bufoff, gbase, voff) do { _Pragma("unroll") for (int _i = 0; _i < 2; ++_i) \
;         __builtin_amdgcn_global_load_lds((const unsigned*)((const char*)(gbase) + (voff)[_i]), (PG8_LAS unsigned*)(lds + (bufoff) + ldsw + _i * 8192), 16, 0, 0); } while (0)
; #define PG8_LDA(dst, b, h) do { _Pragma("unroll") for (int m = 0; m < 4; ++m) _Pragma("unroll") for (int k = 0; k < 2; ++k) dst[m][k] = *(const PG8_LAS bf16x8*)(lds + PG8_SA(b, h) + aoff + m * 2048 + k * 1024); } while (0)
; #define PG8_LDB(dst, b, h) do { _Pragma("unroll") for (int n = 0; n < 2; ++n) _Pragma("unroll") for (int k = 0; k < 2; ++k) dst[n][k] = *(const PG8_LAS bf16x8*)(lds + PG8_SB(b, h) + boff + n * 2048 + k * 1024); } while (0)
; #define PG8_MMA(ai, bj, At, Bt) do { __builtin_amdgcn_s_setprio(1); _Pragma("unroll") for (int m = 0; m < 4; ++m) _Pragma("unroll") for (int n = 0; n < 2; ++n) _Pragma("unroll") for (int k = 0; k < 2; ++k) \
;         acc[ai][bj][m][n] = __builtin_amdgcn_mfma_f32_16x16x32_bf16(Bt[n][k], At[m][k], acc[ai][bj][m][n], 0, 0, 0); __builtin_amdgcn_s_setprio(0); } while (0)
; #define PG8_WAIT_V(n) asm volatile("s_waitcnt vmcnt(" #n ")" ::: "memory")
; #define PG8_WAIT_L(n) asm volatile("s_waitcnt lgkmcnt(" #n ")" ::: "memory")
; #define PG8_BAR __builtin_amdgcn_s_barrier()
; #define PG8_SCHED __builtin_amdgcn_sched_barrier(0)
; template <class Epi, class Sched, bool ALIGN_EPI = false, bool SP2 = false>
; __device__ __forceinline__ void gemm_phase(PG8_LAS unsigned char* lds, const Gemm g, const Sched& S, const Epi& E, const int wid  ) {
;     ...
;             PG8_WAIT_V(8); PG8_WAIT_L(0); PG8_BAR; PG8_MMA(1, 0, At, B0); PG8_MMA(1, 1, At, B1); PG8_BAR; PG8_SCHED;
;             PG8_LDB(B0, 1, 0); PG8_LDB(B1, 1, 1); PG8_SCHED; PG8_LDA(At, 1, 0); PG8_STAGE(PG8_SA(0, 1), a2 + hstep, voffA);
;             PG8_WAIT_V(8); PG8_WAIT_L(0); PG8_BAR; PG8_MMA(0, 0, At, B0); PG8_MMA(0, 1, At, B1); PG8_BAR; PG8_SCHED;
	s_setprio 1
	s_waitcnt lgkmcnt(0)
	v_mfma_f32_16x16x32_bf16 v[60:63], v[72:75], v[160:163], v[60:63]
	v_mfma_f32_16x16x32_bf16 v[56:59], v[88:91], v[160:163], v[56:59]
	v_mfma_f32_16x16x32_bf16 v[44:47], v[72:75], v[184:187], v[44:47]
	v_mfma_f32_16x16x32_bf16 v[40:43], v[88:91], v[184:187], v[40:43]
	v_mfma_f32_16x16x32_bf16 v[28:31], v[72:75], v[192:195], v[28:31]
	v_mfma_f32_16x16x32_bf16 v[24:27], v[88:91], v[192:195], v[24:27]
	v_mfma_f32_16x16x32_bf16 v[12:15], v[72:75], v[208:211], v[12:15]
	v_mfma_f32_16x16x32_bf16 v[8:11], v[88:91], v[208:211], v[8:11]
	v_mfma_f32_16x16x32_bf16 v[60:63], v[76:79], v[164:167], v[60:63]
	v_mfma_f32_16x16x32_bf16 v[56:59], v[92:95], v[164:167], v[56:59]
	v_mfma_f32_16x16x32_bf16 v[44:47], v[76:79], v[188:191], v[44:47]
	v_mfma_f32_16x16x32_bf16 v[40:43], v[92:95], v[188:191], v[40:43]
	v_mfma_f32_16x16x32_bf16 v[28:31], v[76:79], v[204:207], v[28:31]
	v_mfma_f32_16x16x32_bf16 v[24:27], v[92:95], v[204:207], v[24:27]
	v_mfma_f32_16x16x32_bf16 v[12:15], v[76:79], v[212:215], v[12:15]
	v_mfma_f32_16x16x32_bf16 v[8:11], v[92:95], v[212:215], v[8:11]
	s_setprio 0
	s_setprio 1
	v_mfma_f32_16x16x32_bf16 v[52:55], v[144:147], v[160:163], v[52:55]
	v_mfma_f32_16x16x32_bf16 v[48:51], v[152:155], v[160:163], v[48:51]
	v_mfma_f32_16x16x32_bf16 v[36:39], v[144:147], v[184:187], v[36:39]
	v_mfma_f32_16x16x32_bf16 v[32:35], v[152:155], v[184:187], v[32:35]
	v_mfma_f32_16x16x32_bf16 v[20:23], v[144:147], v[192:195], v[20:23]
	v_mfma_f32_16x16x32_bf16 v[16:19], v[152:155], v[192:195], v[16:19]
	v_mfma_f32_16x16x32_bf16 v[4:7], v[144:147], v[208:211], v[4:7]
	v_mfma_f32_16x16x32_bf16 v[0:3], v[152:155], v[208:211], v[0:3]
	v_mfma_f32_16x16x32_bf16 v[52:55], v[148:151], v[164:167], v[52:55]
	v_mfma_f32_16x16x32_bf16 v[48:51], v[156:159], v[164:167], v[48:51]
	v_mfma_f32_16x16x32_bf16 v[36:39], v[148:151], v[188:191], v[36:39]
	v_mfma_f32_16x16x32_bf16 v[32:35], v[156:159], v[188:191], v[32:35]
	v_mfma_f32_16x16x32_bf16 v[20:23], v[148:151], v[204:207], v[20:23]
	v_mfma_f32_16x16x32_bf16 v[16:19], v[156:159], v[204:207], v[16:19]
	v_mfma_f32_16x16x32_bf16 v[4:7], v[148:151], v[212:215], v[4:7]
	v_mfma_f32_16x16x32_bf16 v[0:3], v[156:159], v[212:215], v[0:3]
	s_setprio 0
	s_barrier
	s_add_i32 s69, 0, 0x18000
	s_add_i32 s70, 0, 0x1c000
	v_add_u32_e32 v92, s69, v198
	v_add_u32_e32 v156, s70, v198
	ds_read_b128 v[72:75], v92
	ds_read_b128 v[76:79], v92 offset:1024
	ds_read_b128 v[88:91], v92 offset:2048
	ds_read_b128 v[92:95], v92 offset:3072
	ds_read_b128 v[144:147], v156
	ds_read_b128 v[148:151], v156 offset:1024
	ds_read_b128 v[152:155], v156 offset:2048
	ds_read_b128 v[156:159], v156 offset:3072
	v_lshl_add_u64 v[220:221], s[52:53], 0, v[168:169]
	s_mov_b32 m0, s34
	v_lshl_add_u64 v[222:223], s[52:53], 0, v[172:173]
	global_load_lds_dwordx4 v[220:221], off
	s_mov_b32 m0, s35
	s_nop 0
	global_load_lds_dwordx4 v[222:223], off
	s_add_u32 s46, s52, 0x160000
	s_addc_u32 s47, s53, 0
	s_mov_b32 m0, s37
	v_lshl_add_u64 v[224:225], s[46:47], 0, v[168:169]
	ds_read_b128 v[160:163], v202 offset:32768
	ds_read_b128 v[164:167], v202 offset:33792
	ds_read_b128 v[184:187], v202 offset:34816
	ds_read_b128 v[188:191], v202 offset:35840
	ds_read_b128 v[192:195], v202 offset:36864
	ds_read_b128 v[204:207], v202 offset:37888
	ds_read_b128 v[208:211], v202 offset:38912
	ds_read_b128 v[212:215], v202 offset:39936
	global_load_lds_dwordx4 v[224:225], off
	v_lshl_add_u64 v[224:225], s[46:47], 0, v[172:173]
	s_mov_b32 m0, s54
	s_nop 0
	global_load_lds_dwordx4 v[224:225], off
	s_waitcnt vmcnt(8)
	s_waitcnt lgkmcnt(0)
	s_barrier
; #define PG8_STAGE(bufoff, gbase, voff) do { _Pragma("unroll") for (int _i = 0; _i < 2; ++_i) \
;         __builtin_amdgcn_global_load_lds((const unsigned*)((const char*)(gbase) + (voff)[_i]), (PG8_LAS unsigned*)(lds + (bufoff) + ldsw + _i * 8192), 16, 0, 0); } while (0)
; #define PG8_LDA(dst, b, h) do { _Pragma("unroll") for (int m = 0; m < 4; ++m) _Pragma("unroll") for (int k = 0; k < 2; ++k) dst[m][k] = *(const PG8_LAS bf16x8*)(lds + PG8_SA(b, h) + aoff + m * 2048 + k * 1024); } while (0)
; #define PG8_MMA(ai, bj, At, Bt) do { __builtin_amdgcn_s_setprio(1); _Pragma("unroll") for (int m = 0; m < 4; ++m) _Pragma("unroll") for (int n = 0; n < 2; ++n) _Pragma("unroll") for (int k = 0; k < 2; ++k) \
;         acc[ai][bj][m][n] = __builtin_amdgcn_mfma_f32_16x16x32_bf16(Bt[n][k], At[m][k], acc[ai][bj][m][n], 0, 0, 0); __builtin_amdgcn_s_setprio(0); } while (0)
; #define PG8_WAIT_V(n) asm volatile("s_waitcnt vmcnt(" #n ")" ::: "memory")
; #define PG8_WAIT_L(n) asm volatile("s_waitcnt lgkmcnt(" #n ")" ::: "memory")
; #define PG8_BAR __builtin_amdgcn_s_barrier()
; #define PG8_SCHED __builtin_amdgcn_sched_barrier(0)
; template <class Epi, class Sched, bool ALIGN_EPI = false, bool SP2 = false>
; __device__ __forceinline__ void gemm_phase(PG8_LAS unsigned char* lds, const Gemm g, const Sched& S, const Epi& E, const int wid  ) {
;     ...
;             PG8_WAIT_V(8); PG8_WAIT_L(0); PG8_BAR; PG8_MMA(0, 0, At, B0); PG8_MMA(0, 1, At, B1); PG8_BAR; PG8_SCHED;
;             PG8_LDA(At, 1, 1); PG8_STAGE(PG8_SB(1, 0), b3, voffB); PG8_STAGE(PG8_SB(1, 1), b3 + hstep, voffB); PG8_STAGE(PG8_SA(1, 0), a3, voffA);
;             PG8_WAIT_V(8); PG8_WAIT_L(0); PG8_BAR; PG8_MMA(1, 0, At, B0); PG8_MMA(1, 1, At, B1); PG8_BAR; PG8_SCHED;
	s_setprio 1
	s_waitcnt lgkmcnt(0)
	v_mfma_f32_16x16x32_bf16 v[140:143], v[72:75], v[160:163], v[140:143]
	v_mfma_f32_16x16x32_bf16 v[136:139], v[88:91], v[160:163], v[136:139]
	v_mfma_f32_16x16x32_bf16 v[124:127], v[72:75], v[184:187], v[124:127]
	v_mfma_f32_16x16x32_bf16 v[120:123], v[88:91], v[184:187], v[120:123]
	v_mfma_f32_16x16x32_bf16 v[108:111], v[72:75], v[192:195], v[108:111]
	v_mfma_f32_16x16x32_bf16 v[104:107], v[88:91], v[192:195], v[104:107]
	v_mfma_f32_16x16x32_bf16 v[84:87], v[72:75], v[208:211], v[84:87]
	v_mfma_f32_16x16x32_bf16 v[80:83], v[88:91], v[208:211], v[80:83]
	v_mfma_f32_16x16x32_bf16 v[140:143], v[76:79], v[164:167], v[140:143]
	v_mfma_f32_16x16x32_bf16 v[136:139], v[92:95], v[164:167], v[136:139]
	v_mfma_f32_16x16x32_bf16 v[124:127], v[76:79], v[188:191], v[124:127]
	v_mfma_f32_16x16x32_bf16 v[120:123], v[92:95], v[188:191], v[120:123]
	v_mfma_f32_16x16x32_bf16 v[108:111], v[76:79], v[204:207], v[108:111]
	v_mfma_f32_16x16x32_bf16 v[104:107], v[92:95], v[204:207], v[104:107]
	v_mfma_f32_16x16x32_bf16 v[84:87], v[76:79], v[212:215], v[84:87]
	v_mfma_f32_16x16x32_bf16 v[80:83], v[92:95], v[212:215], v[80:83]
	s_setprio 0
	s_setprio 1
	v_mfma_f32_16x16x32_bf16 v[132:135], v[144:147], v[160:163], v[132:135]
	v_mfma_f32_16x16x32_bf16 v[128:131], v[152:155], v[160:163], v[128:131]
	v_mfma_f32_16x16x32_bf16 v[116:119], v[144:147], v[184:187], v[116:119]
	v_mfma_f32_16x16x32_bf16 v[112:115], v[152:155], v[184:187], v[112:115]
	v_mfma_f32_16x16x32_bf16 v[100:103], v[144:147], v[192:195], v[100:103]
	v_mfma_f32_16x16x32_bf16 v[96:99], v[152:155], v[192:195], v[96:99]
	v_mfma_f32_16x16x32_bf16 v[68:71], v[144:147], v[208:211], v[68:71]
	v_mfma_f32_16x16x32_bf16 v[64:67], v[152:155], v[208:211], v[64:67]
	v_mfma_f32_16x16x32_bf16 v[132:135], v[148:151], v[164:167], v[132:135]
	v_mfma_f32_16x16x32_bf16 v[128:131], v[156:159], v[164:167], v[128:131]
	v_mfma_f32_16x16x32_bf16 v[116:119], v[148:151], v[188:191], v[116:119]
	v_mfma_f32_16x16x32_bf16 v[112:115], v[156:159], v[188:191], v[112:115]
	v_mfma_f32_16x16x32_bf16 v[100:103], v[148:151], v[204:207], v[100:103]
	v_mfma_f32_16x16x32_bf16 v[96:99], v[156:159], v[204:207], v[96:99]
	v_mfma_f32_16x16x32_bf16 v[68:71], v[148:151], v[212:215], v[68:71]
	v_mfma_f32_16x16x32_bf16 v[64:67], v[156:159], v[212:215], v[64:67]
	s_setprio 0
	s_barrier
	s_add_i32 s46, s69, s31
	v_lshl_add_u64 v[216:217], v[216:217], 0, s[40:41]
	s_mov_b32 m0, s46
	ds_read_b128 v[160:163], v202 offset:49152
	ds_read_b128 v[164:167], v202 offset:50176
	ds_read_b128 v[184:187], v202 offset:51200
	ds_read_b128 v[188:191], v202 offset:52224
	ds_read_b128 v[192:195], v202 offset:53248
	ds_read_b128 v[204:207], v202 offset:54272
	ds_read_b128 v[208:211], v202 offset:55296
	ds_read_b128 v[212:215], v202 offset:56320
	global_load_lds_dwordx4 v[216:217], off
	s_add_i32 m0, s46, 0x2000
	s_add_u32 s46, s50, 0x160080
	v_lshl_add_u64 v[216:217], v[218:219], 0, s[40:41]
	s_addc_u32 s47, s51, 0
	s_add_i32 s50, s70, s31
	global_load_lds_dwordx4 v[216:217], off
	v_lshl_add_u64 v[216:217], s[46:47], 0, v[170:171]
	s_mov_b32 m0, s50
	s_nop 0
	global_load_lds_dwordx4 v[216:217], off
	v_lshl_add_u64 v[216:217], s[46:47], 0, v[174:175]
	s_add_i32 m0, s50, 0x2000
	s_nop 0
	global_load_lds_dwordx4 v[216:217], off
	s_waitcnt vmcnt(6)
	s_waitcnt lgkmcnt(0)
	s_barrier
	s_setprio 1
	s_waitcnt lgkmcnt(0)
	v_mfma_f32_16x16x32_bf16 v[60:63], v[72:75], v[160:163], v[60:63]
	v_mfma_f32_16x16x32_bf16 v[56:59], v[88:91], v[160:163], v[56:59]
	v_mfma_f32_16x16x32_bf16 v[44:47], v[72:75], v[184:187], v[44:47]
	v_mfma_f32_16x16x32_bf16 v[40:43], v[88:91], v[184:187], v[40:43]
	v_mfma_f32_16x16x32_bf16 v[28:31], v[72:75], v[192:195], v[28:31]
	v_mfma_f32_16x16x32_bf16 v[24:27], v[88:91], v[192:195], v[24:27]
	v_mfma_f32_16x16x32_bf16 v[12:15], v[72:75], v[208:211], v[12:15]
	v_mfma_f32_16x16x32_bf16 v[8:11], v[88:91], v[208:211], v[8:11]
	v_mfma_f32_16x16x32_bf16 v[60:63], v[76:79], v[164:167], v[60:63]
	v_mfma_f32_16x16x32_bf16 v[56:59], v[92:95], v[164:167], v[56:59]
	v_mfma_f32_16x16x32_bf16 v[44:47], v[76:79], v[188:191], v[44:47]
	v_mfma_f32_16x16x32_bf16 v[40:43], v[92:95], v[188:191], v[40:43]
	v_mfma_f32_16x16x32_bf16 v[28:31], v[76:79], v[204:207], v[28:31]
	v_mfma_f32_16x16x32_bf16 v[24:27], v[92:95], v[204:207], v[24:27]
	v_mfma_f32_16x16x32_bf16 v[12:15], v[76:79], v[212:215], v[12:15]
	v_mfma_f32_16x16x32_bf16 v[8:11], v[92:95], v[212:215], v[8:11]
	s_setprio 0
	s_setprio 1
	v_mfma_f32_16x16x32_bf16 v[52:55], v[144:147], v[160:163], v[52:55]
	v_mfma_f32_16x16x32_bf16 v[48:51], v[152:155], v[160:163], v[48:51]
	v_mfma_f32_16x16x32_bf16 v[36:39], v[144:147], v[184:187], v[36:39]
	v_mfma_f32_16x16x32_bf16 v[32:35], v[152:155], v[184:187], v[32:35]
	v_mfma_f32_16x16x32_bf16 v[20:23], v[144:147], v[192:195], v[20:23]
	v_mfma_f32_16x16x32_bf16 v[16:19], v[152:155], v[192:195], v[16:19]
	v_mfma_f32_16x16x32_bf16 v[4:7], v[144:147], v[208:211], v[4:7]
	v_mfma_f32_16x16x32_bf16 v[0:3], v[152:155], v[208:211], v[0:3]
	v_mfma_f32_16x16x32_bf16 v[52:55], v[148:151], v[164:167], v[52:55]
	v_mfma_f32_16x16x32_bf16 v[48:51], v[156:159], v[164:167], v[48:51]
	v_mfma_f32_16x16x32_bf16 v[36:39], v[148:151], v[188:191], v[36:39]
	v_mfma_f32_16x16x32_bf16 v[32:35], v[156:159], v[188:191], v[32:35]
	v_mfma_f32_16x16x32_bf16 v[20:23], v[148:151], v[204:207], v[20:23]
	v_mfma_f32_16x16x32_bf16 v[16:19], v[156:159], v[204:207], v[16:19]
	v_mfma_f32_16x16x32_bf16 v[4:7], v[148:151], v[212:215], v[4:7]
	v_mfma_f32_16x16x32_bf16 v[0:3], v[156:159], v[212:215], v[0:3]
	s_setprio 0
	s_add_i32 s68, s68, 2
	s_add_u32 s66, s66, 0x100
	s_addc_u32 s67, s67, 0
	s_cmpk_gt_u32 s68, 0x55
	s_mov_b64 s[46:47], s[48:49]
	s_barrier
	s_cbranch_scc0 .LBB0_780
	s_and_b64 vcc, exec, s[42:43]
	s_cbranch_vccz .LBB0_783
	s_barrier

; #define PG8_STAGE(bufoff, gbase, voff) do { _Pragma("unroll") for (int _i = 0; _i < 2; ++_i) \
;         __builtin_amdgcn_global_load_lds((const unsigned*)((const char*)(gbase) + (voff)[_i]), (PG8_LAS unsigned*)(lds + (bufoff) + ldsw + _i * 8192), 16, 0, 0); } while (0)
; #define PG8_LDA(dst, b, h) do { _Pragma("unroll") for (int m = 0; m < 4; ++m) _Pragma("unroll") for (int k = 0; k < 2; ++k) dst[m][k] = *(const PG8_LAS bf16x8*)(lds + PG8_SA(b, h) + aoff + m * 2048 + k * 1024); } while (0)
; #define PG8_LDB(dst, b, h) do { _Pragma("unroll") for (int n = 0; n < 2; ++n) _Pragma("unroll") for (int k = 0; k < 2; ++k) dst[n][k] = *(const PG8_LAS bf16x8*)(lds + PG8_SB(b, h) + boff + n * 2048 + k * 1024); } while (0)
; #define PG8_MMA(ai, bj, At, Bt) do { __builtin_amdgcn_s_setprio(1); _Pragma("unroll") for (int m = 0; m < 4; ++m) _Pragma("unroll") for (int n = 0; n < 2; ++n) _Pragma("unroll") for (int k = 0; k < 2; ++k) \
;         acc[ai][bj][m][n] = __builtin_amdgcn_mfma_f32_16x16x32_bf16(Bt[n][k], At[m][k], acc[ai][bj][m][n], 0, 0, 0); __builtin_amdgcn_s_setprio(0); } while (0)
; #define PG8_WAIT_V(n) asm volatile("s_waitcnt vmcnt(" #n ")" ::: "memory")
; #define PG8_WAIT_L(n) asm volatile("s_waitcnt lgkmcnt(" #n ")" ::: "memory")
; #define PG8_BAR __builtin_amdgcn_s_barrier()
; template <class Epi, class Sched, bool ALIGN_EPI = false, bool SP2 = false>
; __device__ __forceinline__ void gemm_phase(PG8_LAS unsigned char* lds, const Gemm g, const Sched& S, const Epi& E, const int wid  ) {
;     ...
;         for (int t = 0; t < nt; t += 2) {
;             const bool last = (t == nt - 2);
;             const char* a1 = cA + (size_t)(t + 1) * kstep;
;             const char* a2 = last ? nA : cA + (size_t)(t + 2) * kstep; const char* b2 = last ? nB : cB + (size_t)(t + 2) * kstep;
;             const char* a3 = a2 + kstep; const char* b3 = b2 + kstep;
;             if (last && has_next) S.a_ready(nxt);
;             if constexpr (SP2) {
;             PG8_LDB(B0, 0, 0); PG8_LDB(B1, 0, 1); PG8_SCHED; PG8_LDA(At, 0, 0); PG8_STAGE(PG8_SA(1, 1), a1 + hstep, voffA);
;             PG8_WAIT_V(8); PG8_WAIT_L(0); PG8_BAR; PG8_MMA(0, 0, At, B0); PG8_MMA(0, 1, At, B1); PG8_BAR; PG8_SCHED;
;             PG8_LDA(At, 0, 1); PG8_STAGE(PG8_SB(0, 0), b2, voffB); PG8_STAGE(PG8_SB(0, 1), b2 + hstep, voffB); PG8_STAGE(PG8_SA(0, 0), a2, voffA);
.LBB0_879:
	s_add_u32 s100, s10, 0xfff80000
	s_addc_u32 s101, s11, -1
	ds_read_b128 v[128:131], v187
	ds_read_b128 v[132:135], v187 offset:1024
	ds_read_b128 v[136:139], v187 offset:2048
	ds_read_b128 v[140:143], v187 offset:3072
	ds_read_b128 v[166:169], v188
	ds_read_b128 v[170:173], v188 offset:1024
	ds_read_b128 v[174:177], v188 offset:2048
	ds_read_b128 v[178:181], v188 offset:3072
	s_add_u32 s12, s10, 0xfff80080
	s_addc_u32 s13, s11, -1
	s_cmp_eq_u32 s80, 28
	s_cselect_b32 s15, s9, s13
	s_cselect_b32 s14, s63, s12
	s_cselect_b32 s13, s61, s79
	s_cselect_b32 s12, s77, s78
	v_lshl_add_u64 v[228:229], s[100:101], 0, v[158:159]
	s_mov_b32 m0, s68
	v_lshl_add_u64 v[230:231], s[100:101], 0, v[160:161]
	global_load_lds_dwordx4 v[228:229], off
	s_mov_b32 m0, s69
	s_nop 0
	global_load_lds_dwordx4 v[230:231], off
	v_lshl_add_u64 v[224:225], s[10:11], 0, v[158:159]
	s_add_i32 m0, s34, 0xc000
	ds_read_b128 v[192:195], v189
	ds_read_b128 v[196:199], v189 offset:1024
	ds_read_b128 v[200:203], v189 offset:2048
	ds_read_b128 v[204:207], v189 offset:3072
	ds_read_b128 v[208:211], v189 offset:4096
	ds_read_b128 v[212:215], v189 offset:5120
	ds_read_b128 v[216:219], v189 offset:6144
	ds_read_b128 v[220:223], v189 offset:7168
	global_load_lds_dwordx4 v[224:225], off
	v_lshl_add_u64 v[224:225], s[10:11], 0, v[160:161]
	s_add_i32 m0, s34, 0xe000
	s_nop 0
	global_load_lds_dwordx4 v[224:225], off
	s_waitcnt vmcnt(8)
	s_waitcnt lgkmcnt(0)
	s_barrier
	s_setprio 1
	s_waitcnt lgkmcnt(0)
	v_mfma_f32_16x16x32_bf16 v[124:127], v[128:131], v[192:195], v[124:127]
	v_mfma_f32_16x16x32_bf16 v[120:123], v[136:139], v[192:195], v[120:123]
	v_mfma_f32_16x16x32_bf16 v[116:119], v[128:131], v[200:203], v[116:119]
	v_mfma_f32_16x16x32_bf16 v[112:115], v[136:139], v[200:203], v[112:115]
	v_mfma_f32_16x16x32_bf16 v[108:111], v[128:131], v[208:211], v[108:111]
	v_mfma_f32_16x16x32_bf16 v[100:103], v[136:139], v[208:211], v[100:103]
	v_mfma_f32_16x16x32_bf16 v[92:95], v[128:131], v[216:219], v[92:95]
	v_mfma_f32_16x16x32_bf16 v[84:87], v[136:139], v[216:219], v[84:87]
	v_mfma_f32_16x16x32_bf16 v[124:127], v[132:135], v[196:199], v[124:127]
	v_mfma_f32_16x16x32_bf16 v[120:123], v[140:143], v[196:199], v[120:123]
	v_mfma_f32_16x16x32_bf16 v[116:119], v[132:135], v[204:207], v[116:119]
	v_mfma_f32_16x16x32_bf16 v[112:115], v[140:143], v[204:207], v[112:115]
	v_mfma_f32_16x16x32_bf16 v[108:111], v[132:135], v[212:215], v[108:111]
	v_mfma_f32_16x16x32_bf16 v[100:103], v[140:143], v[212:215], v[100:103]
	v_mfma_f32_16x16x32_bf16 v[92:95], v[132:135], v[220:223], v[92:95]
	v_mfma_f32_16x16x32_bf16 v[84:87], v[140:143], v[220:223], v[84:87]
	s_setprio 0
	s_setprio 1
	v_mfma_f32_16x16x32_bf16 v[104:107], v[166:169], v[192:195], v[104:107]
	v_mfma_f32_16x16x32_bf16 v[96:99], v[174:177], v[192:195], v[96:99]
	v_mfma_f32_16x16x32_bf16 v[88:91], v[166:169], v[200:203], v[88:91]
	v_mfma_f32_16x16x32_bf16 v[80:83], v[174:177], v[200:203], v[80:83]
	v_mfma_f32_16x16x32_bf16 v[76:79], v[166:169], v[208:211], v[76:79]
	v_mfma_f32_16x16x32_bf16 v[72:75], v[174:177], v[208:211], v[72:75]
	v_mfma_f32_16x16x32_bf16 v[68:71], v[166:169], v[216:219], v[68:71]
	v_mfma_f32_16x16x32_bf16 v[64:67], v[174:177], v[216:219], v[64:67]
	v_mfma_f32_16x16x32_bf16 v[104:107], v[170:173], v[196:199], v[104:107]
	v_mfma_f32_16x16x32_bf16 v[96:99], v[178:181], v[196:199], v[96:99]
	v_mfma_f32_16x16x32_bf16 v[88:91], v[170:173], v[204:207], v[88:91]
	v_mfma_f32_16x16x32_bf16 v[80:83], v[178:181], v[204:207], v[80:83]
	v_mfma_f32_16x16x32_bf16 v[76:79], v[170:173], v[212:215], v[76:79]
	v_mfma_f32_16x16x32_bf16 v[72:75], v[178:181], v[212:215], v[72:75]
	v_mfma_f32_16x16x32_bf16 v[68:71], v[170:173], v[220:223], v[68:71]
	v_mfma_f32_16x16x32_bf16 v[64:67], v[178:181], v[220:223], v[64:67]
	s_setprio 0
	s_barrier
	s_add_i32 s81, s73, s31
	v_lshl_add_u64 v[224:225], s[12:13], 0, v[146:147]
	s_mov_b32 m0, s81
	ds_read_b128 v[192:195], v189 offset:16384
	ds_read_b128 v[196:199], v189 offset:17408
	ds_read_b128 v[200:203], v189 offset:18432
	ds_read_b128 v[204:207], v189 offset:19456
	ds_read_b128 v[208:211], v189 offset:20480
	ds_read_b128 v[212:215], v189 offset:21504
	ds_read_b128 v[216:219], v189 offset:22528
	ds_read_b128 v[220:223], v189 offset:23552
	global_load_lds_dwordx4 v[224:225], off
	s_add_i32 m0, s81, 0x2000
	s_add_u32 s82, s12, 0x80000
	v_lshl_add_u64 v[226:227], s[12:13], 0, v[150:151]
	s_addc_u32 s83, s13, 0
	s_add_i32 s81, s74, s31
	global_load_lds_dwordx4 v[226:227], off
	v_lshl_add_u64 v[228:229], s[82:83], 0, v[146:147]
	s_mov_b32 m0, s81
	s_nop 0
	global_load_lds_dwordx4 v[228:229], off
	v_lshl_add_u64 v[228:229], s[82:83], 0, v[150:151]
	s_add_i32 m0, s81, 0x2000
	s_nop 0
	global_load_lds_dwordx4 v[228:229], off
	s_waitcnt vmcnt(6)
	s_waitcnt lgkmcnt(0)
	s_barrier
; #define PG8_STAGE(bufoff, gbase, voff) do { _Pragma("unroll") for (int _i = 0; _i < 2; ++_i) \
;         __builtin_amdgcn_global_load_lds((const unsigned*)((const char*)(gbase) + (voff)[_i]), (PG8_LAS unsigned*)(lds + (bufoff) + ldsw + _i * 8192), 16, 0, 0); } while (0)
; #define PG8_LDA(dst, b, h) do { _Pragma("unroll") for (int m = 0; m < 4; ++m) _Pragma("unroll") for (int k = 0; k < 2; ++k) dst[m][k] = *(const PG8_LAS bf16x8*)(lds + PG8_SA(b, h) + aoff + m * 2048 + k * 1024); } while (0)
; #define PG8_LDB(dst, b, h) do { _Pragma("unroll") for (int n = 0; n < 2; ++n) _Pragma("unroll") for (int k = 0; k < 2; ++k) dst[n][k] = *(const PG8_LAS bf16x8*)(lds + PG8_SB(b, h) + boff + n * 2048 + k * 1024); } while (0)
; #define PG8_MMA(ai, bj, At, Bt) do { __builtin_amdgcn_s_setprio(1); _Pragma("unroll") for (int m = 0; m < 4; ++m) _Pragma("unroll") for (int n = 0; n < 2; ++n) _Pragma("unroll") for (int k = 0; k < 2; ++k) \
;         acc[ai][bj][m][n] = __builtin_amdgcn_mfma_f32_16x16x32_bf16(Bt[n][k], At[m][k], acc[ai][bj][m][n], 0, 0, 0); __builtin_amdgcn_s_setprio(0); } while (0)
; #define PG8_WAIT_V(n) asm volatile("s_waitcnt vmcnt(" #n ")" ::: "memory")
; #define PG8_WAIT_L(n) asm volatile("s_waitcnt lgkmcnt(" #n ")" ::: "memory")
; #define PG8_BAR __builtin_amdgcn_s_barrier()
; #define PG8_SCHED __builtin_amdgcn_sched_barrier(0)
; template <class Epi, class Sched, bool ALIGN_EPI = false, bool SP2 = false>
; __device__ __forceinline__ void gemm_phase(PG8_LAS unsigned char* lds, const Gemm g, const Sched& S, const Epi& E, const int wid  ) {
;     ...
;             PG8_WAIT_V(8); PG8_WAIT_L(0); PG8_BAR; PG8_MMA(1, 0, At, B0); PG8_MMA(1, 1, At, B1); PG8_BAR; PG8_SCHED;
;             PG8_LDB(B0, 1, 0); PG8_LDB(B1, 1, 1); PG8_SCHED; PG8_LDA(At, 1, 0); PG8_STAGE(PG8_SA(0, 1), a2 + hstep, voffA);
;             PG8_WAIT_V(8); PG8_WAIT_L(0); PG8_BAR; PG8_MMA(0, 0, At, B0); PG8_MMA(0, 1, At, B1); PG8_BAR; PG8_SCHED;
	s_setprio 1
	s_waitcnt lgkmcnt(0)
	v_mfma_f32_16x16x32_bf16 v[60:63], v[128:131], v[192:195], v[60:63]
	v_mfma_f32_16x16x32_bf16 v[56:59], v[136:139], v[192:195], v[56:59]
	v_mfma_f32_16x16x32_bf16 v[52:55], v[128:131], v[200:203], v[52:55]
	v_mfma_f32_16x16x32_bf16 v[48:51], v[136:139], v[200:203], v[48:51]
	v_mfma_f32_16x16x32_bf16 v[40:43], v[128:131], v[208:211], v[40:43]
	v_mfma_f32_16x16x32_bf16 v[32:35], v[136:139], v[208:211], v[32:35]
	v_mfma_f32_16x16x32_bf16 v[20:23], v[128:131], v[216:219], v[20:23]
	v_mfma_f32_16x16x32_bf16 v[16:19], v[136:139], v[216:219], v[16:19]
	v_mfma_f32_16x16x32_bf16 v[60:63], v[132:135], v[196:199], v[60:63]
	v_mfma_f32_16x16x32_bf16 v[56:59], v[140:143], v[196:199], v[56:59]
	v_mfma_f32_16x16x32_bf16 v[52:55], v[132:135], v[204:207], v[52:55]
	v_mfma_f32_16x16x32_bf16 v[48:51], v[140:143], v[204:207], v[48:51]
	v_mfma_f32_16x16x32_bf16 v[40:43], v[132:135], v[212:215], v[40:43]
	v_mfma_f32_16x16x32_bf16 v[32:35], v[140:143], v[212:215], v[32:35]
	v_mfma_f32_16x16x32_bf16 v[20:23], v[132:135], v[220:223], v[20:23]
	v_mfma_f32_16x16x32_bf16 v[16:19], v[140:143], v[220:223], v[16:19]
	s_setprio 0
	s_setprio 1
	v_mfma_f32_16x16x32_bf16 v[44:47], v[166:169], v[192:195], v[44:47]
	v_mfma_f32_16x16x32_bf16 v[36:39], v[174:177], v[192:195], v[36:39]
	v_mfma_f32_16x16x32_bf16 v[28:31], v[166:169], v[200:203], v[28:31]
	v_mfma_f32_16x16x32_bf16 v[24:27], v[174:177], v[200:203], v[24:27]
	v_mfma_f32_16x16x32_bf16 v[12:15], v[166:169], v[208:211], v[12:15]
	v_mfma_f32_16x16x32_bf16 v[8:11], v[174:177], v[208:211], v[8:11]
	v_mfma_f32_16x16x32_bf16 v[4:7], v[166:169], v[216:219], v[4:7]
	v_mfma_f32_16x16x32_bf16 v[0:3], v[174:177], v[216:219], v[0:3]
	v_mfma_f32_16x16x32_bf16 v[44:47], v[170:173], v[196:199], v[44:47]
	v_mfma_f32_16x16x32_bf16 v[36:39], v[178:181], v[196:199], v[36:39]
	v_mfma_f32_16x16x32_bf16 v[28:31], v[170:173], v[204:207], v[28:31]
	v_mfma_f32_16x16x32_bf16 v[24:27], v[178:181], v[204:207], v[24:27]
	v_mfma_f32_16x16x32_bf16 v[12:15], v[170:173], v[212:215], v[12:15]
	v_mfma_f32_16x16x32_bf16 v[8:11], v[178:181], v[212:215], v[8:11]
	v_mfma_f32_16x16x32_bf16 v[4:7], v[170:173], v[220:223], v[4:7]
	v_mfma_f32_16x16x32_bf16 v[0:3], v[178:181], v[220:223], v[0:3]
	s_setprio 0
	s_barrier
	s_add_i32 s81, 0, 0x18000
	s_add_i32 s82, 0, 0x1c000
	v_add_u32_e32 v140, s81, v184
	v_add_u32_e32 v178, s82, v184
	ds_read_b128 v[128:131], v140
	ds_read_b128 v[132:135], v140 offset:1024
	ds_read_b128 v[136:139], v140 offset:2048
	ds_read_b128 v[140:143], v140 offset:3072
	ds_read_b128 v[166:169], v178
	ds_read_b128 v[170:173], v178 offset:1024
	ds_read_b128 v[174:177], v178 offset:2048
	ds_read_b128 v[178:181], v178 offset:3072
	v_lshl_add_u64 v[228:229], s[14:15], 0, v[144:145]
	s_mov_b32 m0, s34
	v_lshl_add_u64 v[230:231], s[14:15], 0, v[148:149]
	global_load_lds_dwordx4 v[228:229], off
	s_mov_b32 m0, s35
	s_nop 0
	global_load_lds_dwordx4 v[230:231], off
	s_add_u32 s14, s14, 0x80000
	s_addc_u32 s15, s15, 0
	s_mov_b32 m0, s37
	v_lshl_add_u64 v[232:233], s[14:15], 0, v[144:145]
	ds_read_b128 v[192:195], v189 offset:32768
	ds_read_b128 v[196:199], v189 offset:33792
	ds_read_b128 v[200:203], v189 offset:34816
	ds_read_b128 v[204:207], v189 offset:35840
	ds_read_b128 v[208:211], v189 offset:36864
	ds_read_b128 v[212:215], v189 offset:37888
	ds_read_b128 v[216:219], v189 offset:38912
	ds_read_b128 v[220:223], v189 offset:39936
	global_load_lds_dwordx4 v[232:233], off
	v_lshl_add_u64 v[232:233], s[14:15], 0, v[148:149]
	s_mov_b32 m0, s53
	s_nop 0
	global_load_lds_dwordx4 v[232:233], off
	s_waitcnt vmcnt(8)
	s_waitcnt lgkmcnt(0)
	s_barrier
; #define PG8_STAGE(bufoff, gbase, voff) do { _Pragma("unroll") for (int _i = 0; _i < 2; ++_i) \
;         __builtin_amdgcn_global_load_lds((const unsigned*)((const char*)(gbase) + (voff)[_i]), (PG8_LAS unsigned*)(lds + (bufoff) + ldsw + _i * 8192), 16, 0, 0); } while (0)
; #define PG8_LDA(dst, b, h) do { _Pragma("unroll") for (int m = 0; m < 4; ++m) _Pragma("unroll") for (int k = 0; k < 2; ++k) dst[m][k] = *(const PG8_LAS bf16x8*)(lds + PG8_SA(b, h) + aoff + m * 2048 + k * 1024); } while (0)
; #define PG8_MMA(ai, bj, At, Bt) do { __builtin_amdgcn_s_setprio(1); _Pragma("unroll") for (int m = 0; m < 4; ++m) _Pragma("unroll") for (int n = 0; n < 2; ++n) _Pragma("unroll") for (int k = 0; k < 2; ++k) \
;         acc[ai][bj][m][n] = __builtin_amdgcn_mfma_f32_16x16x32_bf16(Bt[n][k], At[m][k], acc[ai][bj][m][n], 0, 0, 0); __builtin_amdgcn_s_setprio(0); } while (0)
; #define PG8_WAIT_V(n) asm volatile("s_waitcnt vmcnt(" #n ")" ::: "memory")
; #define PG8_WAIT_L(n) asm volatile("s_waitcnt lgkmcnt(" #n ")" ::: "memory")
; #define PG8_BAR __builtin_amdgcn_s_barrier()
; #define PG8_SCHED __builtin_amdgcn_sched_barrier(0)
; template <class Epi, class Sched, bool ALIGN_EPI = false, bool SP2 = false>
; __device__ __forceinline__ void gemm_phase(PG8_LAS unsigned char* lds, const Gemm g, const Sched& S, const Epi& E, const int wid  ) {
;     ...
;             PG8_WAIT_V(8); PG8_WAIT_L(0); PG8_BAR; PG8_MMA(0, 0, At, B0); PG8_MMA(0, 1, At, B1); PG8_BAR; PG8_SCHED;
;             PG8_LDA(At, 1, 1); PG8_STAGE(PG8_SB(1, 0), b3, voffB); PG8_STAGE(PG8_SB(1, 1), b3 + hstep, voffB); PG8_STAGE(PG8_SA(1, 0), a3, voffA);
;             PG8_WAIT_V(8); PG8_WAIT_L(0); PG8_BAR; PG8_MMA(1, 0, At, B0); PG8_MMA(1, 1, At, B1); PG8_BAR; PG8_SCHED;
	s_setprio 1
	s_waitcnt lgkmcnt(0)
	v_mfma_f32_16x16x32_bf16 v[124:127], v[128:131], v[192:195], v[124:127]
	v_mfma_f32_16x16x32_bf16 v[120:123], v[136:139], v[192:195], v[120:123]
	v_mfma_f32_16x16x32_bf16 v[116:119], v[128:131], v[200:203], v[116:119]
	v_mfma_f32_16x16x32_bf16 v[112:115], v[136:139], v[200:203], v[112:115]
	v_mfma_f32_16x16x32_bf16 v[108:111], v[128:131], v[208:211], v[108:111]
	v_mfma_f32_16x16x32_bf16 v[100:103], v[136:139], v[208:211], v[100:103]
	v_mfma_f32_16x16x32_bf16 v[92:95], v[128:131], v[216:219], v[92:95]
	v_mfma_f32_16x16x32_bf16 v[84:87], v[136:139], v[216:219], v[84:87]
	v_mfma_f32_16x16x32_bf16 v[124:127], v[132:135], v[196:199], v[124:127]
	v_mfma_f32_16x16x32_bf16 v[120:123], v[140:143], v[196:199], v[120:123]
	v_mfma_f32_16x16x32_bf16 v[116:119], v[132:135], v[204:207], v[116:119]
	v_mfma_f32_16x16x32_bf16 v[112:115], v[140:143], v[204:207], v[112:115]
	v_mfma_f32_16x16x32_bf16 v[108:111], v[132:135], v[212:215], v[108:111]
	v_mfma_f32_16x16x32_bf16 v[100:103], v[140:143], v[212:215], v[100:103]
	v_mfma_f32_16x16x32_bf16 v[92:95], v[132:135], v[220:223], v[92:95]
	v_mfma_f32_16x16x32_bf16 v[84:87], v[140:143], v[220:223], v[84:87]
	s_setprio 0
	s_setprio 1
	v_mfma_f32_16x16x32_bf16 v[104:107], v[166:169], v[192:195], v[104:107]
	v_mfma_f32_16x16x32_bf16 v[96:99], v[174:177], v[192:195], v[96:99]
	v_mfma_f32_16x16x32_bf16 v[88:91], v[166:169], v[200:203], v[88:91]
	v_mfma_f32_16x16x32_bf16 v[80:83], v[174:177], v[200:203], v[80:83]
	v_mfma_f32_16x16x32_bf16 v[76:79], v[166:169], v[208:211], v[76:79]
	v_mfma_f32_16x16x32_bf16 v[72:75], v[174:177], v[208:211], v[72:75]
	v_mfma_f32_16x16x32_bf16 v[68:71], v[166:169], v[216:219], v[68:71]
	v_mfma_f32_16x16x32_bf16 v[64:67], v[174:177], v[216:219], v[64:67]
	v_mfma_f32_16x16x32_bf16 v[104:107], v[170:173], v[196:199], v[104:107]
	v_mfma_f32_16x16x32_bf16 v[96:99], v[178:181], v[196:199], v[96:99]
	v_mfma_f32_16x16x32_bf16 v[88:91], v[170:173], v[204:207], v[88:91]
	v_mfma_f32_16x16x32_bf16 v[80:83], v[178:181], v[204:207], v[80:83]
	v_mfma_f32_16x16x32_bf16 v[76:79], v[170:173], v[212:215], v[76:79]
	v_mfma_f32_16x16x32_bf16 v[72:75], v[178:181], v[212:215], v[72:75]
	v_mfma_f32_16x16x32_bf16 v[68:71], v[170:173], v[220:223], v[68:71]
	v_mfma_f32_16x16x32_bf16 v[64:67], v[178:181], v[220:223], v[64:67]
	s_setprio 0
	s_barrier
	s_add_i32 s14, s81, s31
	v_lshl_add_u64 v[224:225], v[224:225], 0, s[54:55]
	s_mov_b32 m0, s14
	ds_read_b128 v[192:195], v189 offset:49152
	ds_read_b128 v[196:199], v189 offset:50176
	ds_read_b128 v[200:203], v189 offset:51200
	ds_read_b128 v[204:207], v189 offset:52224
	ds_read_b128 v[208:211], v189 offset:53248
	ds_read_b128 v[212:215], v189 offset:54272
	ds_read_b128 v[216:219], v189 offset:55296
	ds_read_b128 v[220:223], v189 offset:56320
	global_load_lds_dwordx4 v[224:225], off
	s_add_i32 m0, s14, 0x2000
	s_add_u32 s12, s12, 0x80080
	v_lshl_add_u64 v[224:225], v[226:227], 0, s[54:55]
	s_addc_u32 s13, s13, 0
	s_add_i32 s14, s82, s31
	global_load_lds_dwordx4 v[224:225], off
	v_lshl_add_u64 v[224:225], s[12:13], 0, v[146:147]
	s_mov_b32 m0, s14
	s_nop 0
	global_load_lds_dwordx4 v[224:225], off
	v_lshl_add_u64 v[224:225], s[12:13], 0, v[150:151]
	s_add_i32 m0, s14, 0x2000
	s_nop 0
	global_load_lds_dwordx4 v[224:225], off
	s_waitcnt vmcnt(6)
	s_waitcnt lgkmcnt(0)
	s_barrier
	s_setprio 1
	s_waitcnt lgkmcnt(0)
	v_mfma_f32_16x16x32_bf16 v[60:63], v[128:131], v[192:195], v[60:63]
	v_mfma_f32_16x16x32_bf16 v[56:59], v[136:139], v[192:195], v[56:59]
	v_mfma_f32_16x16x32_bf16 v[52:55], v[128:131], v[200:203], v[52:55]
	v_mfma_f32_16x16x32_bf16 v[48:51], v[136:139], v[200:203], v[48:51]
	v_mfma_f32_16x16x32_bf16 v[40:43], v[128:131], v[208:211], v[40:43]
	v_mfma_f32_16x16x32_bf16 v[32:35], v[136:139], v[208:211], v[32:35]
	v_mfma_f32_16x16x32_bf16 v[20:23], v[128:131], v[216:219], v[20:23]
	v_mfma_f32_16x16x32_bf16 v[16:19], v[136:139], v[216:219], v[16:19]
	v_mfma_f32_16x16x32_bf16 v[60:63], v[132:135], v[196:199], v[60:63]
	v_mfma_f32_16x16x32_bf16 v[56:59], v[140:143], v[196:199], v[56:59]
	v_mfma_f32_16x16x32_bf16 v[52:55], v[132:135], v[204:207], v[52:55]
	v_mfma_f32_16x16x32_bf16 v[48:51], v[140:143], v[204:207], v[48:51]
	v_mfma_f32_16x16x32_bf16 v[40:43], v[132:135], v[212:215], v[40:43]
	v_mfma_f32_16x16x32_bf16 v[32:35], v[140:143], v[212:215], v[32:35]
	v_mfma_f32_16x16x32_bf16 v[20:23], v[132:135], v[220:223], v[20:23]
	v_mfma_f32_16x16x32_bf16 v[16:19], v[140:143], v[220:223], v[16:19]
	s_setprio 0
	s_setprio 1
	v_mfma_f32_16x16x32_bf16 v[44:47], v[166:169], v[192:195], v[44:47]
	v_mfma_f32_16x16x32_bf16 v[36:39], v[174:177], v[192:195], v[36:39]
	v_mfma_f32_16x16x32_bf16 v[28:31], v[166:169], v[200:203], v[28:31]
	v_mfma_f32_16x16x32_bf16 v[24:27], v[174:177], v[200:203], v[24:27]
	v_mfma_f32_16x16x32_bf16 v[12:15], v[166:169], v[208:211], v[12:15]
	v_mfma_f32_16x16x32_bf16 v[8:11], v[174:177], v[208:211], v[8:11]
	v_mfma_f32_16x16x32_bf16 v[4:7], v[166:169], v[216:219], v[4:7]
	v_mfma_f32_16x16x32_bf16 v[0:3], v[174:177], v[216:219], v[0:3]
	v_mfma_f32_16x16x32_bf16 v[44:47], v[170:173], v[196:199], v[44:47]
	v_mfma_f32_16x16x32_bf16 v[36:39], v[178:181], v[196:199], v[36:39]
	v_mfma_f32_16x16x32_bf16 v[28:31], v[170:173], v[204:207], v[28:31]
	v_mfma_f32_16x16x32_bf16 v[24:27], v[178:181], v[204:207], v[24:27]
	v_mfma_f32_16x16x32_bf16 v[12:15], v[170:173], v[212:215], v[12:15]
	v_mfma_f32_16x16x32_bf16 v[8:11], v[178:181], v[212:215], v[8:11]
	v_mfma_f32_16x16x32_bf16 v[4:7], v[170:173], v[220:223], v[4:7]
	v_mfma_f32_16x16x32_bf16 v[0:3], v[178:181], v[220:223], v[0:3]
	s_setprio 0
	s_add_i32 s80, s80, 2
	s_add_u32 s10, s10, 0x100
	s_addc_u32 s11, s11, 0
	s_add_u32 s78, s78, 0x100
	s_addc_u32 s79, s79, 0
	s_cmp_gt_u32 s80, 29
	s_barrier
	s_cbranch_scc0 .LBB0_879
	s_and_b64 vcc, exec, s[56:57]
	s_cbranch_vccz .LBB0_882
	s_barrier

; #define PG8_STAGE(bufoff, gbase, voff) do { _Pragma("unroll") for (int _i = 0; _i < 2; ++_i) \
;         __builtin_amdgcn_global_load_lds((const unsigned*)((const char*)(gbase) + (voff)[_i]), (PG8_LAS unsigned*)(lds + (bufoff) + ldsw + _i * 8192), 16, 0, 0); } while (0)
; #define PG8_LDA(dst, b, h) do { _Pragma("unroll") for (int m = 0; m < 4; ++m) _Pragma("unroll") for (int k = 0; k < 2; ++k) dst[m][k] = *(const PG8_LAS bf16x8*)(lds + PG8_SA(b, h) + aoff + m * 2048 + k * 1024); } while (0)
; #define PG8_LDB(dst, b, h) do { _Pragma("unroll") for (int n = 0; n < 2; ++n) _Pragma("unroll") for (int k = 0; k < 2; ++k) dst[n][k] = *(const PG8_LAS bf16x8*)(lds + PG8_SB(b, h) + boff + n * 2048 + k * 1024); } while (0)
; #define PG8_MMA(ai, bj, At, Bt) do { __builtin_amdgcn_s_setprio(1); _Pragma("unroll") for (int m = 0; m < 4; ++m) _Pragma("unroll") for (int n = 0; n < 2; ++n) _Pragma("unroll") for (int k = 0; k < 2; ++k) \
;         acc[ai][bj][m][n] = __builtin_amdgcn_mfma_f32_16x16x32_bf16(Bt[n][k], At[m][k], acc[ai][bj][m][n], 0, 0, 0); __builtin_amdgcn_s_setprio(0); } while (0)
; #define PG8_WAIT_V(n) asm volatile("s_waitcnt vmcnt(" #n ")" ::: "memory")
; #define PG8_WAIT_L(n) asm volatile("s_waitcnt lgkmcnt(" #n ")" ::: "memory")
; #define PG8_BAR __builtin_amdgcn_s_barrier()
; template <class Epi, class Sched, bool ALIGN_EPI = false, bool SP2 = false>
; __device__ __forceinline__ void gemm_phase(PG8_LAS unsigned char* lds, const Gemm g, const Sched& S, const Epi& E, const int wid  ) {
;     ...
;         for (int t = 0; t < nt; t += 2) {
;             const bool last = (t == nt - 2);
;             const char* a1 = cA + (size_t)(t + 1) * kstep;
;             const char* a2 = last ? nA : cA + (size_t)(t + 2) * kstep; const char* b2 = last ? nB : cB + (size_t)(t + 2) * kstep;
;             const char* a3 = a2 + kstep; const char* b3 = b2 + kstep;
;             if (last && has_next) S.a_ready(nxt);
;             if constexpr (SP2) {
;             PG8_LDB(B0, 0, 0); PG8_LDB(B1, 0, 1); PG8_SCHED; PG8_LDA(At, 0, 0); PG8_STAGE(PG8_SA(1, 1), a1 + hstep, voffA);
;             PG8_WAIT_V(8); PG8_WAIT_L(0); PG8_BAR; PG8_MMA(0, 0, At, B0); PG8_MMA(0, 1, At, B1); PG8_BAR; PG8_SCHED;
;             PG8_LDA(At, 0, 1); PG8_STAGE(PG8_SB(0, 0), b2, voffB); PG8_STAGE(PG8_SB(0, 1), b2 + hstep, voffB); PG8_STAGE(PG8_SA(0, 0), a2, voffA);
.LBB0_5665:
	s_add_u32 s100, s50, 0xfff80000
	s_addc_u32 s101, s51, -1
	ds_read_b128 v[72:75], v200
	ds_read_b128 v[76:79], v200 offset:1024
	ds_read_b128 v[88:91], v200 offset:2048
	ds_read_b128 v[92:95], v200 offset:3072
	ds_read_b128 v[144:147], v201
	ds_read_b128 v[148:151], v201 offset:1024
	ds_read_b128 v[152:155], v201 offset:2048
	ds_read_b128 v[156:159], v201 offset:3072
	s_add_u32 s52, s50, 0xfff80080
	s_addc_u32 s53, s51, -1
	s_cmp_eq_u32 s68, 28
	s_cselect_b32 s55, s41, s53
	s_cselect_b32 s54, s47, s52
	s_cselect_b32 s53, s39, s67
	s_cselect_b32 s52, s65, s66
	v_lshl_add_u64 v[220:221], s[100:101], 0, v[176:177]
	s_mov_b32 m0, s59
	v_lshl_add_u64 v[222:223], s[100:101], 0, v[178:179]
	global_load_lds_dwordx4 v[220:221], off
	s_mov_b32 m0, s60
	s_nop 0
	global_load_lds_dwordx4 v[222:223], off
	v_lshl_add_u64 v[216:217], s[50:51], 0, v[176:177]
	s_add_i32 m0, s35, 0xc000
	ds_read_b128 v[160:163], v202
	ds_read_b128 v[164:167], v202 offset:1024
	ds_read_b128 v[184:187], v202 offset:2048
	ds_read_b128 v[188:191], v202 offset:3072
	ds_read_b128 v[192:195], v202 offset:4096
	ds_read_b128 v[204:207], v202 offset:5120
	ds_read_b128 v[208:211], v202 offset:6144
	ds_read_b128 v[212:215], v202 offset:7168
	global_load_lds_dwordx4 v[216:217], off
	v_lshl_add_u64 v[216:217], s[50:51], 0, v[178:179]
	s_add_i32 m0, s35, 0xe000
	s_nop 0
	global_load_lds_dwordx4 v[216:217], off
	s_waitcnt vmcnt(8)
	s_waitcnt lgkmcnt(0)
	s_barrier
	s_setprio 1
	s_waitcnt lgkmcnt(0)
	v_mfma_f32_16x16x32_bf16 v[140:143], v[72:75], v[160:163], v[140:143]
	v_mfma_f32_16x16x32_bf16 v[136:139], v[88:91], v[160:163], v[136:139]
	v_mfma_f32_16x16x32_bf16 v[124:127], v[72:75], v[184:187], v[124:127]
	v_mfma_f32_16x16x32_bf16 v[120:123], v[88:91], v[184:187], v[120:123]
	v_mfma_f32_16x16x32_bf16 v[108:111], v[72:75], v[192:195], v[108:111]
	v_mfma_f32_16x16x32_bf16 v[104:107], v[88:91], v[192:195], v[104:107]
	v_mfma_f32_16x16x32_bf16 v[84:87], v[72:75], v[208:211], v[84:87]
	v_mfma_f32_16x16x32_bf16 v[80:83], v[88:91], v[208:211], v[80:83]
	v_mfma_f32_16x16x32_bf16 v[140:143], v[76:79], v[164:167], v[140:143]
	v_mfma_f32_16x16x32_bf16 v[136:139], v[92:95], v[164:167], v[136:139]
	v_mfma_f32_16x16x32_bf16 v[124:127], v[76:79], v[188:191], v[124:127]
	v_mfma_f32_16x16x32_bf16 v[120:123], v[92:95], v[188:191], v[120:123]
	v_mfma_f32_16x16x32_bf16 v[108:111], v[76:79], v[204:207], v[108:111]
	v_mfma_f32_16x16x32_bf16 v[104:107], v[92:95], v[204:207], v[104:107]
	v_mfma_f32_16x16x32_bf16 v[84:87], v[76:79], v[212:215], v[84:87]
	v_mfma_f32_16x16x32_bf16 v[80:83], v[92:95], v[212:215], v[80:83]
	s_setprio 0
	s_setprio 1
	v_mfma_f32_16x16x32_bf16 v[132:135], v[144:147], v[160:163], v[132:135]
	v_mfma_f32_16x16x32_bf16 v[128:131], v[152:155], v[160:163], v[128:131]
	v_mfma_f32_16x16x32_bf16 v[116:119], v[144:147], v[184:187], v[116:119]
	v_mfma_f32_16x16x32_bf16 v[112:115], v[152:155], v[184:187], v[112:115]
	v_mfma_f32_16x16x32_bf16 v[100:103], v[144:147], v[192:195], v[100:103]
	v_mfma_f32_16x16x32_bf16 v[96:99], v[152:155], v[192:195], v[96:99]
	v_mfma_f32_16x16x32_bf16 v[68:71], v[144:147], v[208:211], v[68:71]
	v_mfma_f32_16x16x32_bf16 v[64:67], v[152:155], v[208:211], v[64:67]
	v_mfma_f32_16x16x32_bf16 v[132:135], v[148:151], v[164:167], v[132:135]
	v_mfma_f32_16x16x32_bf16 v[128:131], v[156:159], v[164:167], v[128:131]
	v_mfma_f32_16x16x32_bf16 v[116:119], v[148:151], v[188:191], v[116:119]
	v_mfma_f32_16x16x32_bf16 v[112:115], v[156:159], v[188:191], v[112:115]
	v_mfma_f32_16x16x32_bf16 v[100:103], v[148:151], v[204:207], v[100:103]
	v_mfma_f32_16x16x32_bf16 v[96:99], v[156:159], v[204:207], v[96:99]
	v_mfma_f32_16x16x32_bf16 v[68:71], v[148:151], v[212:215], v[68:71]
	v_mfma_f32_16x16x32_bf16 v[64:67], v[156:159], v[212:215], v[64:67]
	s_setprio 0
	s_barrier
	s_add_i32 s69, s63, s34
	v_lshl_add_u64 v[216:217], s[52:53], 0, v[170:171]
	s_mov_b32 m0, s69
	ds_read_b128 v[160:163], v202 offset:16384
	ds_read_b128 v[164:167], v202 offset:17408
	ds_read_b128 v[184:187], v202 offset:18432
	ds_read_b128 v[188:191], v202 offset:19456
	ds_read_b128 v[192:195], v202 offset:20480
	ds_read_b128 v[204:207], v202 offset:21504
	ds_read_b128 v[208:211], v202 offset:22528
	ds_read_b128 v[212:215], v202 offset:23552
	global_load_lds_dwordx4 v[216:217], off
	s_add_i32 m0, s69, 0x2000
	s_add_u32 s70, s52, 0x80000
	v_lshl_add_u64 v[218:219], s[52:53], 0, v[174:175]
	s_addc_u32 s71, s53, 0
	s_add_i32 s69, s64, s34
	global_load_lds_dwordx4 v[218:219], off
	v_lshl_add_u64 v[220:221], s[70:71], 0, v[170:171]
	s_mov_b32 m0, s69
	s_nop 0
	global_load_lds_dwordx4 v[220:221], off
	v_lshl_add_u64 v[220:221], s[70:71], 0, v[174:175]
	s_add_i32 m0, s69, 0x2000
	s_nop 0
	global_load_lds_dwordx4 v[220:221], off
	s_waitcnt vmcnt(6)
	s_waitcnt lgkmcnt(0)
	s_barrier
; #define PG8_STAGE(bufoff, gbase, voff) do { _Pragma("unroll") for (int _i = 0; _i < 2; ++_i) \
;         __builtin_amdgcn_global_load_lds((const unsigned*)((const char*)(gbase) + (voff)[_i]), (PG8_LAS unsigned*)(lds + (bufoff) + ldsw + _i * 8192), 16, 0, 0); } while (0)
; #define PG8_LDA(dst, b, h) do { _Pragma("unroll") for (int m = 0; m < 4; ++m) _Pragma("unroll") for (int k = 0; k < 2; ++k) dst[m][k] = *(const PG8_LAS bf16x8*)(lds + PG8_SA(b, h) + aoff + m * 2048 + k * 1024); } while (0)
; #define PG8_LDB(dst, b, h) do { _Pragma("unroll") for (int n = 0; n < 2; ++n) _Pragma("unroll") for (int k = 0; k < 2; ++k) dst[n][k] = *(const PG8_LAS bf16x8*)(lds + PG8_SB(b, h) + boff + n * 2048 + k * 1024); } while (0)
; #define PG8_MMA(ai, bj, At, Bt) do { __builtin_amdgcn_s_setprio(1); _Pragma("unroll") for (int m = 0; m < 4; ++m) _Pragma("unroll") for (int n = 0; n < 2; ++n) _Pragma("unroll") for (int k = 0; k < 2; ++k) \
;         acc[ai][bj][m][n] = __builtin_amdgcn_mfma_f32_16x16x32_bf16(Bt[n][k], At[m][k], acc[ai][bj][m][n], 0, 0, 0); __builtin_amdgcn_s_setprio(0); } while (0)
; #define PG8_WAIT_V(n) asm volatile("s_waitcnt vmcnt(" #n ")" ::: "memory")
; #define PG8_WAIT_L(n) asm volatile("s_waitcnt lgkmcnt(" #n ")" ::: "memory")
; #define PG8_BAR __builtin_amdgcn_s_barrier()
; #define PG8_SCHED __builtin_amdgcn_sched_barrier(0)
; template <class Epi, class Sched, bool ALIGN_EPI = false, bool SP2 = false>
; __device__ __forceinline__ void gemm_phase(PG8_LAS unsigned char* lds, const Gemm g, const Sched& S, const Epi& E, const int wid  ) {
;     ...
;             PG8_WAIT_V(8); PG8_WAIT_L(0); PG8_BAR; PG8_MMA(1, 0, At, B0); PG8_MMA(1, 1, At, B1); PG8_BAR; PG8_SCHED;
;             PG8_LDB(B0, 1, 0); PG8_LDB(B1, 1, 1); PG8_SCHED; PG8_LDA(At, 1, 0); PG8_STAGE(PG8_SA(0, 1), a2 + hstep, voffA);
;             PG8_WAIT_V(8); PG8_WAIT_L(0); PG8_BAR; PG8_MMA(0, 0, At, B0); PG8_MMA(0, 1, At, B1); PG8_BAR; PG8_SCHED;
	s_setprio 1
	s_waitcnt lgkmcnt(0)
	v_mfma_f32_16x16x32_bf16 v[60:63], v[72:75], v[160:163], v[60:63]
	v_mfma_f32_16x16x32_bf16 v[56:59], v[88:91], v[160:163], v[56:59]
	v_mfma_f32_16x16x32_bf16 v[44:47], v[72:75], v[184:187], v[44:47]
	v_mfma_f32_16x16x32_bf16 v[40:43], v[88:91], v[184:187], v[40:43]
	v_mfma_f32_16x16x32_bf16 v[28:31], v[72:75], v[192:195], v[28:31]
	v_mfma_f32_16x16x32_bf16 v[24:27], v[88:91], v[192:195], v[24:27]
	v_mfma_f32_16x16x32_bf16 v[12:15], v[72:75], v[208:211], v[12:15]
	v_mfma_f32_16x16x32_bf16 v[8:11], v[88:91], v[208:211], v[8:11]
	v_mfma_f32_16x16x32_bf16 v[60:63], v[76:79], v[164:167], v[60:63]
	v_mfma_f32_16x16x32_bf16 v[56:59], v[92:95], v[164:167], v[56:59]
	v_mfma_f32_16x16x32_bf16 v[44:47], v[76:79], v[188:191], v[44:47]
	v_mfma_f32_16x16x32_bf16 v[40:43], v[92:95], v[188:191], v[40:43]
	v_mfma_f32_16x16x32_bf16 v[28:31], v[76:79], v[204:207], v[28:31]
	v_mfma_f32_16x16x32_bf16 v[24:27], v[92:95], v[204:207], v[24:27]
	v_mfma_f32_16x16x32_bf16 v[12:15], v[76:79], v[212:215], v[12:15]
	v_mfma_f32_16x16x32_bf16 v[8:11], v[92:95], v[212:215], v[8:11]
	s_setprio 0
	s_setprio 1
	v_mfma_f32_16x16x32_bf16 v[52:55], v[144:147], v[160:163], v[52:55]
	v_mfma_f32_16x16x32_bf16 v[48:51], v[152:155], v[160:163], v[48:51]
	v_mfma_f32_16x16x32_bf16 v[36:39], v[144:147], v[184:187], v[36:39]
	v_mfma_f32_16x16x32_bf16 v[32:35], v[152:155], v[184:187], v[32:35]
	v_mfma_f32_16x16x32_bf16 v[20:23], v[144:147], v[192:195], v[20:23]
	v_mfma_f32_16x16x32_bf16 v[16:19], v[152:155], v[192:195], v[16:19]
	v_mfma_f32_16x16x32_bf16 v[4:7], v[144:147], v[208:211], v[4:7]
	v_mfma_f32_16x16x32_bf16 v[0:3], v[152:155], v[208:211], v[0:3]
	v_mfma_f32_16x16x32_bf16 v[52:55], v[148:151], v[164:167], v[52:55]
	v_mfma_f32_16x16x32_bf16 v[48:51], v[156:159], v[164:167], v[48:51]
	v_mfma_f32_16x16x32_bf16 v[36:39], v[148:151], v[188:191], v[36:39]
	v_mfma_f32_16x16x32_bf16 v[32:35], v[156:159], v[188:191], v[32:35]
	v_mfma_f32_16x16x32_bf16 v[20:23], v[148:151], v[204:207], v[20:23]
	v_mfma_f32_16x16x32_bf16 v[16:19], v[156:159], v[204:207], v[16:19]
	v_mfma_f32_16x16x32_bf16 v[4:7], v[148:151], v[212:215], v[4:7]
	v_mfma_f32_16x16x32_bf16 v[0:3], v[156:159], v[212:215], v[0:3]
	s_setprio 0
	s_barrier
	s_add_i32 s69, 0, 0x18000
	s_add_i32 s70, 0, 0x1c000
	v_add_u32_e32 v92, s69, v198
	v_add_u32_e32 v156, s70, v198
	ds_read_b128 v[72:75], v92
	ds_read_b128 v[76:79], v92 offset:1024
	ds_read_b128 v[88:91], v92 offset:2048
	ds_read_b128 v[92:95], v92 offset:3072
	ds_read_b128 v[144:147], v156
	ds_read_b128 v[148:151], v156 offset:1024
	ds_read_b128 v[152:155], v156 offset:2048
	ds_read_b128 v[156:159], v156 offset:3072
	v_lshl_add_u64 v[220:221], s[54:55], 0, v[168:169]
	s_mov_b32 m0, s35
	v_lshl_add_u64 v[222:223], s[54:55], 0, v[172:173]
	global_load_lds_dwordx4 v[220:221], off
	s_mov_b32 m0, s49
	s_nop 0
	global_load_lds_dwordx4 v[222:223], off
	s_add_u32 s54, s54, 0x80000
	s_addc_u32 s55, s55, 0
	s_mov_b32 m0, s56
	v_lshl_add_u64 v[224:225], s[54:55], 0, v[168:169]
	ds_read_b128 v[160:163], v202 offset:32768
	ds_read_b128 v[164:167], v202 offset:33792
	ds_read_b128 v[184:187], v202 offset:34816
	ds_read_b128 v[188:191], v202 offset:35840
	ds_read_b128 v[192:195], v202 offset:36864
	ds_read_b128 v[204:207], v202 offset:37888
	ds_read_b128 v[208:211], v202 offset:38912
	ds_read_b128 v[212:215], v202 offset:39936
	global_load_lds_dwordx4 v[224:225], off
	v_lshl_add_u64 v[224:225], s[54:55], 0, v[172:173]
	s_mov_b32 m0, s57
	s_nop 0
	global_load_lds_dwordx4 v[224:225], off
	s_waitcnt vmcnt(8)
	s_waitcnt lgkmcnt(0)
	s_barrier
; #define PG8_STAGE(bufoff, gbase, voff) do { _Pragma("unroll") for (int _i = 0; _i < 2; ++_i) \
;         __builtin_amdgcn_global_load_lds((const unsigned*)((const char*)(gbase) + (voff)[_i]), (PG8_LAS unsigned*)(lds + (bufoff) + ldsw + _i * 8192), 16, 0, 0); } while (0)
; #define PG8_LDA(dst, b, h) do { _Pragma("unroll") for (int m = 0; m < 4; ++m) _Pragma("unroll") for (int k = 0; k < 2; ++k) dst[m][k] = *(const PG8_LAS bf16x8*)(lds + PG8_SA(b, h) + aoff + m * 2048 + k * 1024); } while (0)
; #define PG8_MMA(ai, bj, At, Bt) do { __builtin_amdgcn_s_setprio(1); _Pragma("unroll") for (int m = 0; m < 4; ++m) _Pragma("unroll") for (int n = 0; n < 2; ++n) _Pragma("unroll") for (int k = 0; k < 2; ++k) \
;         acc[ai][bj][m][n] = __builtin_amdgcn_mfma_f32_16x16x32_bf16(Bt[n][k], At[m][k], acc[ai][bj][m][n], 0, 0, 0); __builtin_amdgcn_s_setprio(0); } while (0)
; #define PG8_WAIT_V(n) asm volatile("s_waitcnt vmcnt(" #n ")" ::: "memory")
; #define PG8_WAIT_L(n) asm volatile("s_waitcnt lgkmcnt(" #n ")" ::: "memory")
; #define PG8_BAR __builtin_amdgcn_s_barrier()
; #define PG8_SCHED __builtin_amdgcn_sched_barrier(0)
; template <class Epi, class Sched, bool ALIGN_EPI = false, bool SP2 = false>
; __device__ __forceinline__ void gemm_phase(PG8_LAS unsigned char* lds, const Gemm g, const Sched& S, const Epi& E, const int wid  ) {
;     ...
;             PG8_WAIT_V(8); PG8_WAIT_L(0); PG8_BAR; PG8_MMA(0, 0, At, B0); PG8_MMA(0, 1, At, B1); PG8_BAR; PG8_SCHED;
;             PG8_LDA(At, 1, 1); PG8_STAGE(PG8_SB(1, 0), b3, voffB); PG8_STAGE(PG8_SB(1, 1), b3 + hstep, voffB); PG8_STAGE(PG8_SA(1, 0), a3, voffA);
;             PG8_WAIT_V(8); PG8_WAIT_L(0); PG8_BAR; PG8_MMA(1, 0, At, B0); PG8_MMA(1, 1, At, B1); PG8_BAR; PG8_SCHED;
	s_setprio 1
	s_waitcnt lgkmcnt(0)
	v_mfma_f32_16x16x32_bf16 v[140:143], v[72:75], v[160:163], v[140:143]
	v_mfma_f32_16x16x32_bf16 v[136:139], v[88:91], v[160:163], v[136:139]
	v_mfma_f32_16x16x32_bf16 v[124:127], v[72:75], v[184:187], v[124:127]
	v_mfma_f32_16x16x32_bf16 v[120:123], v[88:91], v[184:187], v[120:123]
	v_mfma_f32_16x16x32_bf16 v[108:111], v[72:75], v[192:195], v[108:111]
	v_mfma_f32_16x16x32_bf16 v[104:107], v[88:91], v[192:195], v[104:107]
	v_mfma_f32_16x16x32_bf16 v[84:87], v[72:75], v[208:211], v[84:87]
	v_mfma_f32_16x16x32_bf16 v[80:83], v[88:91], v[208:211], v[80:83]
	v_mfma_f32_16x16x32_bf16 v[140:143], v[76:79], v[164:167], v[140:143]
	v_mfma_f32_16x16x32_bf16 v[136:139], v[92:95], v[164:167], v[136:139]
	v_mfma_f32_16x16x32_bf16 v[124:127], v[76:79], v[188:191], v[124:127]
	v_mfma_f32_16x16x32_bf16 v[120:123], v[92:95], v[188:191], v[120:123]
	v_mfma_f32_16x16x32_bf16 v[108:111], v[76:79], v[204:207], v[108:111]
	v_mfma_f32_16x16x32_bf16 v[104:107], v[92:95], v[204:207], v[104:107]
	v_mfma_f32_16x16x32_bf16 v[84:87], v[76:79], v[212:215], v[84:87]
	v_mfma_f32_16x16x32_bf16 v[80:83], v[92:95], v[212:215], v[80:83]
	s_setprio 0
	s_setprio 1
	v_mfma_f32_16x16x32_bf16 v[132:135], v[144:147], v[160:163], v[132:135]
	v_mfma_f32_16x16x32_bf16 v[128:131], v[152:155], v[160:163], v[128:131]
	v_mfma_f32_16x16x32_bf16 v[116:119], v[144:147], v[184:187], v[116:119]
	v_mfma_f32_16x16x32_bf16 v[112:115], v[152:155], v[184:187], v[112:115]
	v_mfma_f32_16x16x32_bf16 v[100:103], v[144:147], v[192:195], v[100:103]
	v_mfma_f32_16x16x32_bf16 v[96:99], v[152:155], v[192:195], v[96:99]
	v_mfma_f32_16x16x32_bf16 v[68:71], v[144:147], v[208:211], v[68:71]
	v_mfma_f32_16x16x32_bf16 v[64:67], v[152:155], v[208:211], v[64:67]
	v_mfma_f32_16x16x32_bf16 v[132:135], v[148:151], v[164:167], v[132:135]
	v_mfma_f32_16x16x32_bf16 v[128:131], v[156:159], v[164:167], v[128:131]
	v_mfma_f32_16x16x32_bf16 v[116:119], v[148:151], v[188:191], v[116:119]
	v_mfma_f32_16x16x32_bf16 v[112:115], v[156:159], v[188:191], v[112:115]
	v_mfma_f32_16x16x32_bf16 v[100:103], v[148:151], v[204:207], v[100:103]
	v_mfma_f32_16x16x32_bf16 v[96:99], v[156:159], v[204:207], v[96:99]
	v_mfma_f32_16x16x32_bf16 v[68:71], v[148:151], v[212:215], v[68:71]
	v_mfma_f32_16x16x32_bf16 v[64:67], v[156:159], v[212:215], v[64:67]
	s_setprio 0
	s_barrier
	s_add_i32 s54, s69, s34
	v_lshl_add_u64 v[216:217], v[216:217], 0, s[22:23]
	s_mov_b32 m0, s54
	ds_read_b128 v[160:163], v202 offset:49152
	ds_read_b128 v[164:167], v202 offset:50176
	ds_read_b128 v[184:187], v202 offset:51200
	ds_read_b128 v[188:191], v202 offset:52224
	ds_read_b128 v[192:195], v202 offset:53248
	ds_read_b128 v[204:207], v202 offset:54272
	ds_read_b128 v[208:211], v202 offset:55296
	ds_read_b128 v[212:215], v202 offset:56320
	global_load_lds_dwordx4 v[216:217], off
	s_add_i32 m0, s54, 0x2000
	s_add_u32 s52, s52, 0x80080
	v_lshl_add_u64 v[216:217], v[218:219], 0, s[22:23]
	s_addc_u32 s53, s53, 0
	s_add_i32 s54, s70, s34
	global_load_lds_dwordx4 v[216:217], off
	v_lshl_add_u64 v[216:217], s[52:53], 0, v[170:171]
	s_mov_b32 m0, s54
	s_nop 0
	global_load_lds_dwordx4 v[216:217], off
	v_lshl_add_u64 v[216:217], s[52:53], 0, v[174:175]
	s_add_i32 m0, s54, 0x2000
	s_nop 0
	global_load_lds_dwordx4 v[216:217], off
	s_waitcnt vmcnt(6)
	s_waitcnt lgkmcnt(0)
	s_barrier
	s_setprio 1
	s_waitcnt lgkmcnt(0)
	v_mfma_f32_16x16x32_bf16 v[60:63], v[72:75], v[160:163], v[60:63]
	v_mfma_f32_16x16x32_bf16 v[56:59], v[88:91], v[160:163], v[56:59]
	v_mfma_f32_16x16x32_bf16 v[44:47], v[72:75], v[184:187], v[44:47]
	v_mfma_f32_16x16x32_bf16 v[40:43], v[88:91], v[184:187], v[40:43]
	v_mfma_f32_16x16x32_bf16 v[28:31], v[72:75], v[192:195], v[28:31]
	v_mfma_f32_16x16x32_bf16 v[24:27], v[88:91], v[192:195], v[24:27]
	v_mfma_f32_16x16x32_bf16 v[12:15], v[72:75], v[208:211], v[12:15]
	v_mfma_f32_16x16x32_bf16 v[8:11], v[88:91], v[208:211], v[8:11]
	v_mfma_f32_16x16x32_bf16 v[60:63], v[76:79], v[164:167], v[60:63]
	v_mfma_f32_16x16x32_bf16 v[56:59], v[92:95], v[164:167], v[56:59]
	v_mfma_f32_16x16x32_bf16 v[44:47], v[76:79], v[188:191], v[44:47]
	v_mfma_f32_16x16x32_bf16 v[40:43], v[92:95], v[188:191], v[40:43]
	v_mfma_f32_16x16x32_bf16 v[28:31], v[76:79], v[204:207], v[28:31]
	v_mfma_f32_16x16x32_bf16 v[24:27], v[92:95], v[204:207], v[24:27]
	v_mfma_f32_16x16x32_bf16 v[12:15], v[76:79], v[212:215], v[12:15]
	v_mfma_f32_16x16x32_bf16 v[8:11], v[92:95], v[212:215], v[8:11]
	s_setprio 0
	s_setprio 1
	v_mfma_f32_16x16x32_bf16 v[52:55], v[144:147], v[160:163], v[52:55]
	v_mfma_f32_16x16x32_bf16 v[48:51], v[152:155], v[160:163], v[48:51]
	v_mfma_f32_16x16x32_bf16 v[36:39], v[144:147], v[184:187], v[36:39]
	v_mfma_f32_16x16x32_bf16 v[32:35], v[152:155], v[184:187], v[32:35]
	v_mfma_f32_16x16x32_bf16 v[20:23], v[144:147], v[192:195], v[20:23]
	v_mfma_f32_16x16x32_bf16 v[16:19], v[152:155], v[192:195], v[16:19]
	v_mfma_f32_16x16x32_bf16 v[4:7], v[144:147], v[208:211], v[4:7]
	v_mfma_f32_16x16x32_bf16 v[0:3], v[152:155], v[208:211], v[0:3]
	v_mfma_f32_16x16x32_bf16 v[52:55], v[148:151], v[164:167], v[52:55]
	v_mfma_f32_16x16x32_bf16 v[48:51], v[156:159], v[164:167], v[48:51]
	v_mfma_f32_16x16x32_bf16 v[36:39], v[148:151], v[188:191], v[36:39]
	v_mfma_f32_16x16x32_bf16 v[32:35], v[156:159], v[188:191], v[32:35]
	v_mfma_f32_16x16x32_bf16 v[20:23], v[148:151], v[204:207], v[20:23]
	v_mfma_f32_16x16x32_bf16 v[16:19], v[156:159], v[204:207], v[16:19]
	v_mfma_f32_16x16x32_bf16 v[4:7], v[148:151], v[212:215], v[4:7]
	v_mfma_f32_16x16x32_bf16 v[0:3], v[156:159], v[212:215], v[0:3]
	s_setprio 0
	s_add_i32 s68, s68, 2
	s_add_u32 s50, s50, 0x100
	s_addc_u32 s51, s51, 0
	s_add_u32 s66, s66, 0x100
	s_addc_u32 s67, s67, 0
	s_cmp_gt_u32 s68, 29
	s_barrier
	s_cbranch_scc0 .LBB0_5665
	s_and_b64 vcc, exec, s[36:37]
	s_cbranch_vccz .LBB0_5668
	s_barrier

; #define PG8_STAGE(bufoff, gbase, voff) do { _Pragma("unroll") for (int _i = 0; _i < 2; ++_i) \
;         __builtin_amdgcn_global_load_lds((const unsigned*)((const char*)(gbase) + (voff)[_i]), (PG8_LAS unsigned*)(lds + (bufoff) + ldsw + _i * 8192), 16, 0, 0); } while (0)
; #define PG8_LDA(dst, b, h) do { _Pragma("unroll") for (int m = 0; m < 4; ++m) _Pragma("unroll") for (int k = 0; k < 2; ++k) dst[m][k] = *(const PG8_LAS bf16x8*)(lds + PG8_SA(b, h) + aoff + m * 2048 + k * 1024); } while (0)
; #define PG8_LDB(dst, b, h) do { _Pragma("unroll") for (int n = 0; n < 2; ++n) _Pragma("unroll") for (int k = 0; k < 2; ++k) dst[n][k] = *(const PG8_LAS bf16x8*)(lds + PG8_SB(b, h) + boff + n * 2048 + k * 1024); } while (0)
; #define PG8_MMA(ai, bj, At, Bt) do { __builtin_amdgcn_s_setprio(1); _Pragma("unroll") for (int m = 0; m < 4; ++m) _Pragma("unroll") for (int n = 0; n < 2; ++n) _Pragma("unroll") for (int k = 0; k < 2; ++k) \
;         acc[ai][bj][m][n] = __builtin_amdgcn_mfma_f32_16x16x32_bf16(Bt[n][k], At[m][k], acc[ai][bj][m][n], 0, 0, 0); __builtin_amdgcn_s_setprio(0); } while (0)
; #define PG8_WAIT_V(n) asm volatile("s_waitcnt vmcnt(" #n ")" ::: "memory")
; #define PG8_WAIT_L(n) asm volatile("s_waitcnt lgkmcnt(" #n ")" ::: "memory")
; #define PG8_BAR __builtin_amdgcn_s_barrier()
; template <class Epi, class Sched, bool ALIGN_EPI = false, bool SP2 = false>
; __device__ __forceinline__ void gemm_phase(PG8_LAS unsigned char* lds, const Gemm g, const Sched& S, const Epi& E, const int wid  ) {
;     ...
;         for (int t = 0; t < nt; t += 2) {
;             const bool last = (t == nt - 2);
;             const char* a1 = cA + (size_t)(t + 1) * kstep;
;             const char* a2 = last ? nA : cA + (size_t)(t + 2) * kstep; const char* b2 = last ? nB : cB + (size_t)(t + 2) * kstep;
;             const char* a3 = a2 + kstep; const char* b3 = b2 + kstep;
;             if (last && has_next) S.a_ready(nxt);
;             if constexpr (SP2) {
;             PG8_LDB(B0, 0, 0); PG8_LDB(B1, 0, 1); PG8_SCHED; PG8_LDA(At, 0, 0); PG8_STAGE(PG8_SA(1, 1), a1 + hstep, voffA);
;             PG8_WAIT_V(8); PG8_WAIT_L(0); PG8_BAR; PG8_MMA(0, 0, At, B0); PG8_MMA(0, 1, At, B1); PG8_BAR; PG8_SCHED;
;             PG8_LDA(At, 0, 1); PG8_STAGE(PG8_SB(0, 0), b2, voffB); PG8_STAGE(PG8_SB(0, 1), b2 + hstep, voffB); PG8_STAGE(PG8_SA(0, 0), a2, voffA);
.LBB0_5761:
	s_add_u32 s100, s8, 0xfff80000
	s_addc_u32 s101, s9, -1
	ds_read_b128 v[144:147], v153
	ds_read_b128 v[158:161], v153 offset:1024
	ds_read_b128 v[162:165], v153 offset:2048
	ds_read_b128 v[166:169], v153 offset:3072
	ds_read_b128 v[170:173], v154
	ds_read_b128 v[174:177], v154 offset:1024
	ds_read_b128 v[178:181], v154 offset:2048
	ds_read_b128 v[182:185], v154 offset:3072
	s_add_u32 s10, s8, 0xfff80080
	s_addc_u32 s11, s9, -1
	s_cmp_eq_u32 s65, 28
	s_cselect_b32 s13, s14, s11
	s_cselect_b32 s12, s15, s10
	s_cselect_b32 s11, s43, s64
	s_cselect_b32 s10, s45, s63
	v_lshl_add_u64 v[222:223], s[100:101], 0, v[136:137]
	s_mov_b32 m0, s56
	v_lshl_add_u64 v[224:225], s[100:101], 0, v[138:139]
	global_load_lds_dwordx4 v[222:223], off
	s_mov_b32 m0, s57
	s_nop 0
	global_load_lds_dwordx4 v[224:225], off
	v_lshl_add_u64 v[218:219], s[8:9], 0, v[136:137]
	s_add_i32 m0, s51, 0xc000
	ds_read_b128 v[186:189], v155
	ds_read_b128 v[190:193], v155 offset:1024
	ds_read_b128 v[194:197], v155 offset:2048
	ds_read_b128 v[198:201], v155 offset:3072
	ds_read_b128 v[202:205], v155 offset:4096
	ds_read_b128 v[206:209], v155 offset:5120
	ds_read_b128 v[210:213], v155 offset:6144
	ds_read_b128 v[214:217], v155 offset:7168
	global_load_lds_dwordx4 v[218:219], off
	v_lshl_add_u64 v[218:219], s[8:9], 0, v[138:139]
	s_add_i32 m0, s51, 0xe000
	s_nop 0
	global_load_lds_dwordx4 v[218:219], off
	s_waitcnt vmcnt(8)
	s_waitcnt lgkmcnt(0)
	s_barrier
	s_setprio 1
	s_waitcnt lgkmcnt(0)
	v_mfma_f32_16x16x32_bf16 v[124:127], v[144:147], v[186:189], v[124:127]
	v_mfma_f32_16x16x32_bf16 v[120:123], v[162:165], v[186:189], v[120:123]
	v_mfma_f32_16x16x32_bf16 v[108:111], v[144:147], v[194:197], v[108:111]
	v_mfma_f32_16x16x32_bf16 v[104:107], v[162:165], v[194:197], v[104:107]
	v_mfma_f32_16x16x32_bf16 v[92:95], v[144:147], v[202:205], v[92:95]
	v_mfma_f32_16x16x32_bf16 v[88:91], v[162:165], v[202:205], v[88:91]
	v_mfma_f32_16x16x32_bf16 v[76:79], v[144:147], v[210:213], v[76:79]
	v_mfma_f32_16x16x32_bf16 v[72:75], v[162:165], v[210:213], v[72:75]
	v_mfma_f32_16x16x32_bf16 v[124:127], v[158:161], v[190:193], v[124:127]
	v_mfma_f32_16x16x32_bf16 v[120:123], v[166:169], v[190:193], v[120:123]
	v_mfma_f32_16x16x32_bf16 v[108:111], v[158:161], v[198:201], v[108:111]
	v_mfma_f32_16x16x32_bf16 v[104:107], v[166:169], v[198:201], v[104:107]
	v_mfma_f32_16x16x32_bf16 v[92:95], v[158:161], v[206:209], v[92:95]
	v_mfma_f32_16x16x32_bf16 v[88:91], v[166:169], v[206:209], v[88:91]
	v_mfma_f32_16x16x32_bf16 v[76:79], v[158:161], v[214:217], v[76:79]
	v_mfma_f32_16x16x32_bf16 v[72:75], v[166:169], v[214:217], v[72:75]
	s_setprio 0
	s_setprio 1
	v_mfma_f32_16x16x32_bf16 v[116:119], v[170:173], v[186:189], v[116:119]
	v_mfma_f32_16x16x32_bf16 v[112:115], v[178:181], v[186:189], v[112:115]
	v_mfma_f32_16x16x32_bf16 v[100:103], v[170:173], v[194:197], v[100:103]
	v_mfma_f32_16x16x32_bf16 v[96:99], v[178:181], v[194:197], v[96:99]
	v_mfma_f32_16x16x32_bf16 v[84:87], v[170:173], v[202:205], v[84:87]
	v_mfma_f32_16x16x32_bf16 v[80:83], v[178:181], v[202:205], v[80:83]
	v_mfma_f32_16x16x32_bf16 v[68:71], v[170:173], v[210:213], v[68:71]
	v_mfma_f32_16x16x32_bf16 v[64:67], v[178:181], v[210:213], v[64:67]
	v_mfma_f32_16x16x32_bf16 v[116:119], v[174:177], v[190:193], v[116:119]
	v_mfma_f32_16x16x32_bf16 v[112:115], v[182:185], v[190:193], v[112:115]
	v_mfma_f32_16x16x32_bf16 v[100:103], v[174:177], v[198:201], v[100:103]
	v_mfma_f32_16x16x32_bf16 v[96:99], v[182:185], v[198:201], v[96:99]
	v_mfma_f32_16x16x32_bf16 v[84:87], v[174:177], v[206:209], v[84:87]
	v_mfma_f32_16x16x32_bf16 v[80:83], v[182:185], v[206:209], v[80:83]
	v_mfma_f32_16x16x32_bf16 v[68:71], v[174:177], v[214:217], v[68:71]
	v_mfma_f32_16x16x32_bf16 v[64:67], v[182:185], v[214:217], v[64:67]
	s_setprio 0
	s_barrier
	s_add_i32 s66, s59, s34
	v_lshl_add_u64 v[218:219], s[10:11], 0, v[132:133]
	s_mov_b32 m0, s66
	ds_read_b128 v[186:189], v155 offset:16384
	ds_read_b128 v[190:193], v155 offset:17408
	ds_read_b128 v[194:197], v155 offset:18432
	ds_read_b128 v[198:201], v155 offset:19456
	ds_read_b128 v[202:205], v155 offset:20480
	ds_read_b128 v[206:209], v155 offset:21504
	ds_read_b128 v[210:213], v155 offset:22528
	ds_read_b128 v[214:217], v155 offset:23552
	global_load_lds_dwordx4 v[218:219], off
	s_add_i32 m0, s66, 0x2000
	s_add_u32 s66, s10, 0x80000
	v_lshl_add_u64 v[220:221], s[10:11], 0, v[128:129]
	s_addc_u32 s67, s11, 0
	s_add_i32 s68, s60, s34
	global_load_lds_dwordx4 v[220:221], off
	v_lshl_add_u64 v[222:223], s[66:67], 0, v[132:133]
	s_mov_b32 m0, s68
	s_nop 0
	global_load_lds_dwordx4 v[222:223], off
	v_lshl_add_u64 v[222:223], s[66:67], 0, v[128:129]
	s_add_i32 m0, s68, 0x2000
	s_nop 0
	global_load_lds_dwordx4 v[222:223], off
	s_waitcnt vmcnt(6)
	s_waitcnt lgkmcnt(0)
	s_barrier
; #define PG8_STAGE(bufoff, gbase, voff) do { _Pragma("unroll") for (int _i = 0; _i < 2; ++_i) \
;         __builtin_amdgcn_global_load_lds((const unsigned*)((const char*)(gbase) + (voff)[_i]), (PG8_LAS unsigned*)(lds + (bufoff) + ldsw + _i * 8192), 16, 0, 0); } while (0)
; #define PG8_LDA(dst, b, h) do { _Pragma("unroll") for (int m = 0; m < 4; ++m) _Pragma("unroll") for (int k = 0; k < 2; ++k) dst[m][k] = *(const PG8_LAS bf16x8*)(lds + PG8_SA(b, h) + aoff + m * 2048 + k * 1024); } while (0)
; #define PG8_LDB(dst, b, h) do { _Pragma("unroll") for (int n = 0; n < 2; ++n) _Pragma("unroll") for (int k = 0; k < 2; ++k) dst[n][k] = *(const PG8_LAS bf16x8*)(lds + PG8_SB(b, h) + boff + n * 2048 + k * 1024); } while (0)
; #define PG8_MMA(ai, bj, At, Bt) do { __builtin_amdgcn_s_setprio(1); _Pragma("unroll") for (int m = 0; m < 4; ++m) _Pragma("unroll") for (int n = 0; n < 2; ++n) _Pragma("unroll") for (int k = 0; k < 2; ++k) \
;         acc[ai][bj][m][n] = __builtin_amdgcn_mfma_f32_16x16x32_bf16(Bt[n][k], At[m][k], acc[ai][bj][m][n], 0, 0, 0); __builtin_amdgcn_s_setprio(0); } while (0)
; #define PG8_WAIT_V(n) asm volatile("s_waitcnt vmcnt(" #n ")" ::: "memory")
; #define PG8_WAIT_L(n) asm volatile("s_waitcnt lgkmcnt(" #n ")" ::: "memory")
; #define PG8_BAR __builtin_amdgcn_s_barrier()
; #define PG8_SCHED __builtin_amdgcn_sched_barrier(0)
; template <class Epi, class Sched, bool ALIGN_EPI = false, bool SP2 = false>
; __device__ __forceinline__ void gemm_phase(PG8_LAS unsigned char* lds, const Gemm g, const Sched& S, const Epi& E, const int wid  ) {
;     ...
;             PG8_WAIT_V(8); PG8_WAIT_L(0); PG8_BAR; PG8_MMA(1, 0, At, B0); PG8_MMA(1, 1, At, B1); PG8_BAR; PG8_SCHED;
;             PG8_LDB(B0, 1, 0); PG8_LDB(B1, 1, 1); PG8_SCHED; PG8_LDA(At, 1, 0); PG8_STAGE(PG8_SA(0, 1), a2 + hstep, voffA);
;             PG8_WAIT_V(8); PG8_WAIT_L(0); PG8_BAR; PG8_MMA(0, 0, At, B0); PG8_MMA(0, 1, At, B1); PG8_BAR; PG8_SCHED;
	s_setprio 1
	s_waitcnt lgkmcnt(0)
	v_mfma_f32_16x16x32_bf16 v[60:63], v[144:147], v[186:189], v[60:63]
	v_mfma_f32_16x16x32_bf16 v[56:59], v[162:165], v[186:189], v[56:59]
	v_mfma_f32_16x16x32_bf16 v[44:47], v[144:147], v[194:197], v[44:47]
	v_mfma_f32_16x16x32_bf16 v[40:43], v[162:165], v[194:197], v[40:43]
	v_mfma_f32_16x16x32_bf16 v[28:31], v[144:147], v[202:205], v[28:31]
	v_mfma_f32_16x16x32_bf16 v[24:27], v[162:165], v[202:205], v[24:27]
	v_mfma_f32_16x16x32_bf16 v[12:15], v[144:147], v[210:213], v[12:15]
	v_mfma_f32_16x16x32_bf16 v[8:11], v[162:165], v[210:213], v[8:11]
	v_mfma_f32_16x16x32_bf16 v[60:63], v[158:161], v[190:193], v[60:63]
	v_mfma_f32_16x16x32_bf16 v[56:59], v[166:169], v[190:193], v[56:59]
	v_mfma_f32_16x16x32_bf16 v[44:47], v[158:161], v[198:201], v[44:47]
	v_mfma_f32_16x16x32_bf16 v[40:43], v[166:169], v[198:201], v[40:43]
	v_mfma_f32_16x16x32_bf16 v[28:31], v[158:161], v[206:209], v[28:31]
	v_mfma_f32_16x16x32_bf16 v[24:27], v[166:169], v[206:209], v[24:27]
	v_mfma_f32_16x16x32_bf16 v[12:15], v[158:161], v[214:217], v[12:15]
	v_mfma_f32_16x16x32_bf16 v[8:11], v[166:169], v[214:217], v[8:11]
	s_setprio 0
	s_setprio 1
	v_mfma_f32_16x16x32_bf16 v[52:55], v[170:173], v[186:189], v[52:55]
	v_mfma_f32_16x16x32_bf16 v[48:51], v[178:181], v[186:189], v[48:51]
	v_mfma_f32_16x16x32_bf16 v[36:39], v[170:173], v[194:197], v[36:39]
	v_mfma_f32_16x16x32_bf16 v[32:35], v[178:181], v[194:197], v[32:35]
	v_mfma_f32_16x16x32_bf16 v[20:23], v[170:173], v[202:205], v[20:23]
	v_mfma_f32_16x16x32_bf16 v[16:19], v[178:181], v[202:205], v[16:19]
	v_mfma_f32_16x16x32_bf16 v[4:7], v[170:173], v[210:213], v[4:7]
	v_mfma_f32_16x16x32_bf16 v[0:3], v[178:181], v[210:213], v[0:3]
	v_mfma_f32_16x16x32_bf16 v[52:55], v[174:177], v[190:193], v[52:55]
	v_mfma_f32_16x16x32_bf16 v[48:51], v[182:185], v[190:193], v[48:51]
	v_mfma_f32_16x16x32_bf16 v[36:39], v[174:177], v[198:201], v[36:39]
	v_mfma_f32_16x16x32_bf16 v[32:35], v[182:185], v[198:201], v[32:35]
	v_mfma_f32_16x16x32_bf16 v[20:23], v[174:177], v[206:209], v[20:23]
	v_mfma_f32_16x16x32_bf16 v[16:19], v[182:185], v[206:209], v[16:19]
	v_mfma_f32_16x16x32_bf16 v[4:7], v[174:177], v[214:217], v[4:7]
	v_mfma_f32_16x16x32_bf16 v[0:3], v[182:185], v[214:217], v[0:3]
	s_setprio 0
	s_barrier
	s_add_i32 s66, 0, 0x18000
	v_add_u32_e32 v148, s66, v151
	s_add_i32 s67, 0, 0x1c000
	ds_read_b128 v[144:147], v148
	ds_read_b128 v[158:161], v148 offset:1024
	ds_read_b128 v[162:165], v148 offset:2048
	ds_read_b128 v[166:169], v148 offset:3072
	v_add_u32_e32 v148, s67, v151
	ds_read_b128 v[170:173], v148
	ds_read_b128 v[174:177], v148 offset:1024
	ds_read_b128 v[178:181], v148 offset:2048
	ds_read_b128 v[182:185], v148 offset:3072
	v_lshl_add_u64 v[222:223], s[12:13], 0, v[134:135]
	s_mov_b32 m0, s51
	v_lshl_add_u64 v[224:225], s[12:13], 0, v[130:131]
	global_load_lds_dwordx4 v[222:223], off
	s_mov_b32 m0, s52
	s_nop 0
	global_load_lds_dwordx4 v[224:225], off
	s_add_u32 s12, s12, 0x80000
	s_addc_u32 s13, s13, 0
	s_mov_b32 m0, s53
	v_lshl_add_u64 v[226:227], s[12:13], 0, v[134:135]
	ds_read_b128 v[186:189], v155 offset:32768
	ds_read_b128 v[190:193], v155 offset:33792
	ds_read_b128 v[194:197], v155 offset:34816
	ds_read_b128 v[198:201], v155 offset:35840
	ds_read_b128 v[202:205], v155 offset:36864
	ds_read_b128 v[206:209], v155 offset:37888
	ds_read_b128 v[210:213], v155 offset:38912
	ds_read_b128 v[214:217], v155 offset:39936
	global_load_lds_dwordx4 v[226:227], off
	v_lshl_add_u64 v[226:227], s[12:13], 0, v[130:131]
	s_mov_b32 m0, s54
	s_nop 0
	global_load_lds_dwordx4 v[226:227], off
	s_waitcnt vmcnt(8)
	s_waitcnt lgkmcnt(0)
	s_barrier
; #define PG8_STAGE(bufoff, gbase, voff) do { _Pragma("unroll") for (int _i = 0; _i < 2; ++_i) \
;         __builtin_amdgcn_global_load_lds((const unsigned*)((const char*)(gbase) + (voff)[_i]), (PG8_LAS unsigned*)(lds + (bufoff) + ldsw + _i * 8192), 16, 0, 0); } while (0)
; #define PG8_LDA(dst, b, h) do { _Pragma("unroll") for (int m = 0; m < 4; ++m) _Pragma("unroll") for (int k = 0; k < 2; ++k) dst[m][k] = *(const PG8_LAS bf16x8*)(lds + PG8_SA(b, h) + aoff + m * 2048 + k * 1024); } while (0)
; #define PG8_MMA(ai, bj, At, Bt) do { __builtin_amdgcn_s_setprio(1); _Pragma("unroll") for (int m = 0; m < 4; ++m) _Pragma("unroll") for (int n = 0; n < 2; ++n) _Pragma("unroll") for (int k = 0; k < 2; ++k) \
;         acc[ai][bj][m][n] = __builtin_amdgcn_mfma_f32_16x16x32_bf16(Bt[n][k], At[m][k], acc[ai][bj][m][n], 0, 0, 0); __builtin_amdgcn_s_setprio(0); } while (0)
; #define PG8_WAIT_V(n) asm volatile("s_waitcnt vmcnt(" #n ")" ::: "memory")
; #define PG8_WAIT_L(n) asm volatile("s_waitcnt lgkmcnt(" #n ")" ::: "memory")
; #define PG8_BAR __builtin_amdgcn_s_barrier()
; #define PG8_SCHED __builtin_amdgcn_sched_barrier(0)
; template <class Epi, class Sched, bool ALIGN_EPI = false, bool SP2 = false>
; __device__ __forceinline__ void gemm_phase(PG8_LAS unsigned char* lds, const Gemm g, const Sched& S, const Epi& E, const int wid  ) {
;     ...
;             PG8_WAIT_V(8); PG8_WAIT_L(0); PG8_BAR; PG8_MMA(0, 0, At, B0); PG8_MMA(0, 1, At, B1); PG8_BAR; PG8_SCHED;
;             PG8_LDA(At, 1, 1); PG8_STAGE(PG8_SB(1, 0), b3, voffB); PG8_STAGE(PG8_SB(1, 1), b3 + hstep, voffB); PG8_STAGE(PG8_SA(1, 0), a3, voffA);
;             PG8_WAIT_V(8); PG8_WAIT_L(0); PG8_BAR; PG8_MMA(1, 0, At, B0); PG8_MMA(1, 1, At, B1); PG8_BAR; PG8_SCHED;
	s_setprio 1
	s_waitcnt lgkmcnt(0)
	v_mfma_f32_16x16x32_bf16 v[124:127], v[144:147], v[186:189], v[124:127]
	v_mfma_f32_16x16x32_bf16 v[120:123], v[162:165], v[186:189], v[120:123]
	v_mfma_f32_16x16x32_bf16 v[108:111], v[144:147], v[194:197], v[108:111]
	v_mfma_f32_16x16x32_bf16 v[104:107], v[162:165], v[194:197], v[104:107]
	v_mfma_f32_16x16x32_bf16 v[92:95], v[144:147], v[202:205], v[92:95]
	v_mfma_f32_16x16x32_bf16 v[88:91], v[162:165], v[202:205], v[88:91]
	v_mfma_f32_16x16x32_bf16 v[76:79], v[144:147], v[210:213], v[76:79]
	v_mfma_f32_16x16x32_bf16 v[72:75], v[162:165], v[210:213], v[72:75]
	v_mfma_f32_16x16x32_bf16 v[124:127], v[158:161], v[190:193], v[124:127]
	v_mfma_f32_16x16x32_bf16 v[120:123], v[166:169], v[190:193], v[120:123]
	v_mfma_f32_16x16x32_bf16 v[108:111], v[158:161], v[198:201], v[108:111]
	v_mfma_f32_16x16x32_bf16 v[104:107], v[166:169], v[198:201], v[104:107]
	v_mfma_f32_16x16x32_bf16 v[92:95], v[158:161], v[206:209], v[92:95]
	v_mfma_f32_16x16x32_bf16 v[88:91], v[166:169], v[206:209], v[88:91]
	v_mfma_f32_16x16x32_bf16 v[76:79], v[158:161], v[214:217], v[76:79]
	v_mfma_f32_16x16x32_bf16 v[72:75], v[166:169], v[214:217], v[72:75]
	s_setprio 0
	s_setprio 1
	v_mfma_f32_16x16x32_bf16 v[116:119], v[170:173], v[186:189], v[116:119]
	v_mfma_f32_16x16x32_bf16 v[112:115], v[178:181], v[186:189], v[112:115]
	v_mfma_f32_16x16x32_bf16 v[100:103], v[170:173], v[194:197], v[100:103]
	v_mfma_f32_16x16x32_bf16 v[96:99], v[178:181], v[194:197], v[96:99]
	v_mfma_f32_16x16x32_bf16 v[84:87], v[170:173], v[202:205], v[84:87]
	v_mfma_f32_16x16x32_bf16 v[80:83], v[178:181], v[202:205], v[80:83]
	v_mfma_f32_16x16x32_bf16 v[68:71], v[170:173], v[210:213], v[68:71]
	v_mfma_f32_16x16x32_bf16 v[64:67], v[178:181], v[210:213], v[64:67]
	v_mfma_f32_16x16x32_bf16 v[116:119], v[174:177], v[190:193], v[116:119]
	v_mfma_f32_16x16x32_bf16 v[112:115], v[182:185], v[190:193], v[112:115]
	v_mfma_f32_16x16x32_bf16 v[100:103], v[174:177], v[198:201], v[100:103]
	v_mfma_f32_16x16x32_bf16 v[96:99], v[182:185], v[198:201], v[96:99]
	v_mfma_f32_16x16x32_bf16 v[84:87], v[174:177], v[206:209], v[84:87]
	v_mfma_f32_16x16x32_bf16 v[80:83], v[182:185], v[206:209], v[80:83]
	v_mfma_f32_16x16x32_bf16 v[68:71], v[174:177], v[214:217], v[68:71]
	v_mfma_f32_16x16x32_bf16 v[64:67], v[182:185], v[214:217], v[64:67]
	s_setprio 0
	s_barrier
	s_add_i32 s12, s66, s34
	v_lshl_add_u64 v[218:219], v[218:219], 0, s[38:39]
	s_mov_b32 m0, s12
	ds_read_b128 v[186:189], v155 offset:49152
	ds_read_b128 v[190:193], v155 offset:50176
	ds_read_b128 v[194:197], v155 offset:51200
	ds_read_b128 v[198:201], v155 offset:52224
	ds_read_b128 v[202:205], v155 offset:53248
	ds_read_b128 v[206:209], v155 offset:54272
	ds_read_b128 v[210:213], v155 offset:55296
	ds_read_b128 v[214:217], v155 offset:56320
	global_load_lds_dwordx4 v[218:219], off
	s_add_i32 m0, s12, 0x2000
	s_add_u32 s10, s10, 0x80080
	v_lshl_add_u64 v[218:219], v[220:221], 0, s[38:39]
	s_addc_u32 s11, s11, 0
	s_add_i32 s12, s67, s34
	global_load_lds_dwordx4 v[218:219], off
	v_lshl_add_u64 v[218:219], s[10:11], 0, v[132:133]
	s_mov_b32 m0, s12
	s_nop 0
	global_load_lds_dwordx4 v[218:219], off
	v_lshl_add_u64 v[218:219], s[10:11], 0, v[128:129]
	s_add_i32 m0, s12, 0x2000
	s_nop 0
	global_load_lds_dwordx4 v[218:219], off
	s_waitcnt vmcnt(6)
	s_waitcnt lgkmcnt(0)
	s_barrier
	s_setprio 1
	s_waitcnt lgkmcnt(0)
	v_mfma_f32_16x16x32_bf16 v[60:63], v[144:147], v[186:189], v[60:63]
	v_mfma_f32_16x16x32_bf16 v[56:59], v[162:165], v[186:189], v[56:59]
	v_mfma_f32_16x16x32_bf16 v[44:47], v[144:147], v[194:197], v[44:47]
	v_mfma_f32_16x16x32_bf16 v[40:43], v[162:165], v[194:197], v[40:43]
	v_mfma_f32_16x16x32_bf16 v[28:31], v[144:147], v[202:205], v[28:31]
	v_mfma_f32_16x16x32_bf16 v[24:27], v[162:165], v[202:205], v[24:27]
	v_mfma_f32_16x16x32_bf16 v[12:15], v[144:147], v[210:213], v[12:15]
	v_mfma_f32_16x16x32_bf16 v[8:11], v[162:165], v[210:213], v[8:11]
	v_mfma_f32_16x16x32_bf16 v[60:63], v[158:161], v[190:193], v[60:63]
	v_mfma_f32_16x16x32_bf16 v[56:59], v[166:169], v[190:193], v[56:59]
	v_mfma_f32_16x16x32_bf16 v[44:47], v[158:161], v[198:201], v[44:47]
	v_mfma_f32_16x16x32_bf16 v[40:43], v[166:169], v[198:201], v[40:43]
	v_mfma_f32_16x16x32_bf16 v[28:31], v[158:161], v[206:209], v[28:31]
	v_mfma_f32_16x16x32_bf16 v[24:27], v[166:169], v[206:209], v[24:27]
	v_mfma_f32_16x16x32_bf16 v[12:15], v[158:161], v[214:217], v[12:15]
	v_mfma_f32_16x16x32_bf16 v[8:11], v[166:169], v[214:217], v[8:11]
	s_setprio 0
	s_setprio 1
	v_mfma_f32_16x16x32_bf16 v[52:55], v[170:173], v[186:189], v[52:55]
	v_mfma_f32_16x16x32_bf16 v[48:51], v[178:181], v[186:189], v[48:51]
	v_mfma_f32_16x16x32_bf16 v[36:39], v[170:173], v[194:197], v[36:39]
	v_mfma_f32_16x16x32_bf16 v[32:35], v[178:181], v[194:197], v[32:35]
	v_mfma_f32_16x16x32_bf16 v[20:23], v[170:173], v[202:205], v[20:23]
	v_mfma_f32_16x16x32_bf16 v[16:19], v[178:181], v[202:205], v[16:19]
	v_mfma_f32_16x16x32_bf16 v[4:7], v[170:173], v[210:213], v[4:7]
	v_mfma_f32_16x16x32_bf16 v[0:3], v[178:181], v[210:213], v[0:3]
	v_mfma_f32_16x16x32_bf16 v[52:55], v[174:177], v[190:193], v[52:55]
	v_mfma_f32_16x16x32_bf16 v[48:51], v[182:185], v[190:193], v[48:51]
	v_mfma_f32_16x16x32_bf16 v[36:39], v[174:177], v[198:201], v[36:39]
	v_mfma_f32_16x16x32_bf16 v[32:35], v[182:185], v[198:201], v[32:35]
	v_mfma_f32_16x16x32_bf16 v[20:23], v[174:177], v[206:209], v[20:23]
	v_mfma_f32_16x16x32_bf16 v[16:19], v[182:185], v[206:209], v[16:19]
	v_mfma_f32_16x16x32_bf16 v[4:7], v[174:177], v[214:217], v[4:7]
	v_mfma_f32_16x16x32_bf16 v[0:3], v[182:185], v[214:217], v[0:3]
	s_setprio 0
	s_add_i32 s65, s65, 2
	s_add_u32 s8, s8, 0x100
	s_addc_u32 s9, s9, 0
	s_add_u32 s63, s63, 0x100
	s_addc_u32 s64, s64, 0
	s_cmp_gt_u32 s65, 29
	s_barrier
	s_cbranch_scc0 .LBB0_5761
	s_and_b64 vcc, exec, s[40:41]
	s_cbranch_vccz .LBB0_5764
	s_barrier

; #define PG8_STAGE(bufoff, gbase, voff) do { _Pragma("unroll") for (int _i = 0; _i < 2; ++_i) \
;         __builtin_amdgcn_global_load_lds((const unsigned*)((const char*)(gbase) + (voff)[_i]), (PG8_LAS unsigned*)(lds + (bufoff) + ldsw + _i * 8192), 16, 0, 0); } while (0)
; #define PG8_LDA(dst, b, h) do { _Pragma("unroll") for (int m = 0; m < 4; ++m) _Pragma("unroll") for (int k = 0; k < 2; ++k) dst[m][k] = *(const PG8_LAS bf16x8*)(lds + PG8_SA(b, h) + aoff + m * 2048 + k * 1024); } while (0)
; #define PG8_LDB(dst, b, h) do { _Pragma("unroll") for (int n = 0; n < 2; ++n) _Pragma("unroll") for (int k = 0; k < 2; ++k) dst[n][k] = *(const PG8_LAS bf16x8*)(lds + PG8_SB(b, h) + boff + n * 2048 + k * 1024); } while (0)
; #define PG8_MMA(ai, bj, At, Bt) do { __builtin_amdgcn_s_setprio(1); _Pragma("unroll") for (int m = 0; m < 4; ++m) _Pragma("unroll") for (int n = 0; n < 2; ++n) _Pragma("unroll") for (int k = 0; k < 2; ++k) \
;         acc[ai][bj][m][n] = __builtin_amdgcn_mfma_f32_16x16x32_bf16(Bt[n][k], At[m][k], acc[ai][bj][m][n], 0, 0, 0); __builtin_amdgcn_s_setprio(0); } while (0)
; #define PG8_WAIT_V(n) asm volatile("s_waitcnt vmcnt(" #n ")" ::: "memory")
; #define PG8_WAIT_L(n) asm volatile("s_waitcnt lgkmcnt(" #n ")" ::: "memory")
; #define PG8_BAR __builtin_amdgcn_s_barrier()
; template <class Epi, class Sched, bool ALIGN_EPI = false, bool SP2 = false>
; __device__ __forceinline__ void gemm_phase(PG8_LAS unsigned char* lds, const Gemm g, const Sched& S, const Epi& E, const int wid  ) {
;     ...
;         for (int t = 0; t < nt; t += 2) {
;             const bool last = (t == nt - 2);
;             const char* a1 = cA + (size_t)(t + 1) * kstep;
;             const char* a2 = last ? nA : cA + (size_t)(t + 2) * kstep; const char* b2 = last ? nB : cB + (size_t)(t + 2) * kstep;
;             const char* a3 = a2 + kstep; const char* b3 = b2 + kstep;
;             if (last && has_next) S.a_ready(nxt);
;             if constexpr (SP2) {
;             PG8_LDB(B0, 0, 0); PG8_LDB(B1, 0, 1); PG8_SCHED; PG8_LDA(At, 0, 0); PG8_STAGE(PG8_SA(1, 1), a1 + hstep, voffA);
;             PG8_WAIT_V(8); PG8_WAIT_L(0); PG8_BAR; PG8_MMA(0, 0, At, B0); PG8_MMA(0, 1, At, B1); PG8_BAR; PG8_SCHED;
;             PG8_LDA(At, 0, 1); PG8_STAGE(PG8_SB(0, 0), b2, voffB); PG8_STAGE(PG8_SB(0, 1), b2 + hstep, voffB); PG8_STAGE(PG8_SA(0, 0), a2, voffA);
.LBB0_5850:
	s_add_u32 s100, s18, 0xffea0000
	s_addc_u32 s101, s19, -1
	ds_read_b128 v[144:147], v153
	ds_read_b128 v[156:159], v153 offset:1024
	ds_read_b128 v[160:163], v153 offset:2048
	ds_read_b128 v[164:167], v153 offset:3072
	ds_read_b128 v[168:171], v154
	ds_read_b128 v[172:175], v154 offset:1024
	ds_read_b128 v[176:179], v154 offset:2048
	ds_read_b128 v[180:183], v154 offset:3072
	s_add_u32 s20, s18, 0x100
	s_addc_u32 s21, s19, 0
	s_cmpk_eq_i32 s49, 0x54
	s_cselect_b32 s25, s5, s21
	s_cselect_b32 s24, s4, s20
	s_cselect_b32 s23, s17, s48
	s_cselect_b32 s22, s16, s47
	v_lshl_add_u64 v[218:219], s[100:101], 0, v[136:137]
	s_mov_b32 m0, s39
	v_lshl_add_u64 v[220:221], s[100:101], 0, v[138:139]
	global_load_lds_dwordx4 v[218:219], off
	s_mov_b32 m0, s40
	s_nop 0
	global_load_lds_dwordx4 v[220:221], off
	v_lshl_add_u64 v[148:149], s[18:19], 0, v[136:137]
	s_add_i32 m0, s34, 0xc000
	ds_read_b128 v[184:187], v155
	ds_read_b128 v[188:191], v155 offset:1024
	ds_read_b128 v[192:195], v155 offset:2048
	ds_read_b128 v[196:199], v155 offset:3072
	ds_read_b128 v[200:203], v155 offset:4096
	ds_read_b128 v[204:207], v155 offset:5120
	ds_read_b128 v[208:211], v155 offset:6144
	ds_read_b128 v[212:215], v155 offset:7168
	global_load_lds_dwordx4 v[148:149], off
	v_lshl_add_u64 v[148:149], s[18:19], 0, v[138:139]
	s_add_i32 m0, s34, 0xe000
	s_nop 0
	global_load_lds_dwordx4 v[148:149], off
	s_waitcnt vmcnt(8)
	s_waitcnt lgkmcnt(0)
	s_barrier
	s_setprio 1
	s_waitcnt lgkmcnt(0)
	v_mfma_f32_16x16x32_bf16 v[124:127], v[144:147], v[184:187], v[124:127]
	v_mfma_f32_16x16x32_bf16 v[120:123], v[160:163], v[184:187], v[120:123]
	v_mfma_f32_16x16x32_bf16 v[112:115], v[144:147], v[192:195], v[112:115]
	v_mfma_f32_16x16x32_bf16 v[104:107], v[160:163], v[192:195], v[104:107]
	v_mfma_f32_16x16x32_bf16 v[96:99], v[144:147], v[200:203], v[96:99]
	v_mfma_f32_16x16x32_bf16 v[88:91], v[160:163], v[200:203], v[88:91]
	v_mfma_f32_16x16x32_bf16 v[80:83], v[144:147], v[208:211], v[80:83]
	v_mfma_f32_16x16x32_bf16 v[72:75], v[160:163], v[208:211], v[72:75]
	v_mfma_f32_16x16x32_bf16 v[124:127], v[156:159], v[188:191], v[124:127]
	v_mfma_f32_16x16x32_bf16 v[120:123], v[164:167], v[188:191], v[120:123]
	v_mfma_f32_16x16x32_bf16 v[112:115], v[156:159], v[196:199], v[112:115]
	v_mfma_f32_16x16x32_bf16 v[104:107], v[164:167], v[196:199], v[104:107]
	v_mfma_f32_16x16x32_bf16 v[96:99], v[156:159], v[204:207], v[96:99]
	v_mfma_f32_16x16x32_bf16 v[88:91], v[164:167], v[204:207], v[88:91]
	v_mfma_f32_16x16x32_bf16 v[80:83], v[156:159], v[212:215], v[80:83]
	v_mfma_f32_16x16x32_bf16 v[72:75], v[164:167], v[212:215], v[72:75]
	s_setprio 0
	s_setprio 1
	v_mfma_f32_16x16x32_bf16 v[116:119], v[168:171], v[184:187], v[116:119]
	v_mfma_f32_16x16x32_bf16 v[108:111], v[176:179], v[184:187], v[108:111]
	v_mfma_f32_16x16x32_bf16 v[100:103], v[168:171], v[192:195], v[100:103]
	v_mfma_f32_16x16x32_bf16 v[92:95], v[176:179], v[192:195], v[92:95]
	v_mfma_f32_16x16x32_bf16 v[84:87], v[168:171], v[200:203], v[84:87]
	v_mfma_f32_16x16x32_bf16 v[76:79], v[176:179], v[200:203], v[76:79]
	v_mfma_f32_16x16x32_bf16 v[68:71], v[168:171], v[208:211], v[68:71]
	v_mfma_f32_16x16x32_bf16 v[64:67], v[176:179], v[208:211], v[64:67]
	v_mfma_f32_16x16x32_bf16 v[116:119], v[172:175], v[188:191], v[116:119]
	v_mfma_f32_16x16x32_bf16 v[108:111], v[180:183], v[188:191], v[108:111]
	v_mfma_f32_16x16x32_bf16 v[100:103], v[172:175], v[196:199], v[100:103]
	v_mfma_f32_16x16x32_bf16 v[92:95], v[180:183], v[196:199], v[92:95]
	v_mfma_f32_16x16x32_bf16 v[84:87], v[172:175], v[204:207], v[84:87]
	v_mfma_f32_16x16x32_bf16 v[76:79], v[180:183], v[204:207], v[76:79]
	v_mfma_f32_16x16x32_bf16 v[68:71], v[172:175], v[212:215], v[68:71]
	v_mfma_f32_16x16x32_bf16 v[64:67], v[180:183], v[212:215], v[64:67]
	s_setprio 0
	s_barrier
	s_add_i32 s18, s41, s31
	v_lshl_add_u64 v[148:149], s[22:23], 0, v[130:131]
	s_mov_b32 m0, s18
	ds_read_b128 v[184:187], v155 offset:16384
	ds_read_b128 v[188:191], v155 offset:17408
	ds_read_b128 v[192:195], v155 offset:18432
	ds_read_b128 v[196:199], v155 offset:19456
	ds_read_b128 v[200:203], v155 offset:20480
	ds_read_b128 v[204:207], v155 offset:21504
	ds_read_b128 v[208:211], v155 offset:22528
	ds_read_b128 v[212:215], v155 offset:23552
	global_load_lds_dwordx4 v[148:149], off
	s_add_i32 m0, s18, 0x2000
	s_add_u32 s18, s22, 0x160000
	v_lshl_add_u64 v[216:217], s[22:23], 0, v[134:135]
	s_addc_u32 s19, s23, 0
	s_add_i32 s50, s42, s31
	global_load_lds_dwordx4 v[216:217], off
	v_lshl_add_u64 v[218:219], s[18:19], 0, v[130:131]
	s_mov_b32 m0, s50
	s_nop 0
	global_load_lds_dwordx4 v[218:219], off
	v_lshl_add_u64 v[218:219], s[18:19], 0, v[134:135]
	s_add_i32 m0, s50, 0x2000
	s_nop 0
	global_load_lds_dwordx4 v[218:219], off
	s_waitcnt vmcnt(6)
	s_waitcnt lgkmcnt(0)
	s_barrier
; #define PG8_STAGE(bufoff, gbase, voff) do { _Pragma("unroll") for (int _i = 0; _i < 2; ++_i) \
;         __builtin_amdgcn_global_load_lds((const unsigned*)((const char*)(gbase) + (voff)[_i]), (PG8_LAS unsigned*)(lds + (bufoff) + ldsw + _i * 8192), 16, 0, 0); } while (0)
; #define PG8_LDA(dst, b, h) do { _Pragma("unroll") for (int m = 0; m < 4; ++m) _Pragma("unroll") for (int k = 0; k < 2; ++k) dst[m][k] = *(const PG8_LAS bf16x8*)(lds + PG8_SA(b, h) + aoff + m * 2048 + k * 1024); } while (0)
; #define PG8_LDB(dst, b, h) do { _Pragma("unroll") for (int n = 0; n < 2; ++n) _Pragma("unroll") for (int k = 0; k < 2; ++k) dst[n][k] = *(const PG8_LAS bf16x8*)(lds + PG8_SB(b, h) + boff + n * 2048 + k * 1024); } while (0)
; #define PG8_MMA(ai, bj, At, Bt) do { __builtin_amdgcn_s_setprio(1); _Pragma("unroll") for (int m = 0; m < 4; ++m) _Pragma("unroll") for (int n = 0; n < 2; ++n) _Pragma("unroll") for (int k = 0; k < 2; ++k) \
;         acc[ai][bj][m][n] = __builtin_amdgcn_mfma_f32_16x16x32_bf16(Bt[n][k], At[m][k], acc[ai][bj][m][n], 0, 0, 0); __builtin_amdgcn_s_setprio(0); } while (0)
; #define PG8_WAIT_V(n) asm volatile("s_waitcnt vmcnt(" #n ")" ::: "memory")
; #define PG8_WAIT_L(n) asm volatile("s_waitcnt lgkmcnt(" #n ")" ::: "memory")
; #define PG8_BAR __builtin_amdgcn_s_barrier()
; #define PG8_SCHED __builtin_amdgcn_sched_barrier(0)
; template <class Epi, class Sched, bool ALIGN_EPI = false, bool SP2 = false>
; __device__ __forceinline__ void gemm_phase(PG8_LAS unsigned char* lds, const Gemm g, const Sched& S, const Epi& E, const int wid  ) {
;     ...
;             PG8_WAIT_V(8); PG8_WAIT_L(0); PG8_BAR; PG8_MMA(1, 0, At, B0); PG8_MMA(1, 1, At, B1); PG8_BAR; PG8_SCHED;
;             PG8_LDB(B0, 1, 0); PG8_LDB(B1, 1, 1); PG8_SCHED; PG8_LDA(At, 1, 0); PG8_STAGE(PG8_SA(0, 1), a2 + hstep, voffA);
;             PG8_WAIT_V(8); PG8_WAIT_L(0); PG8_BAR; PG8_MMA(0, 0, At, B0); PG8_MMA(0, 1, At, B1); PG8_BAR; PG8_SCHED;
	s_setprio 1
	s_waitcnt lgkmcnt(0)
	v_mfma_f32_16x16x32_bf16 v[60:63], v[144:147], v[184:187], v[60:63]
	v_mfma_f32_16x16x32_bf16 v[56:59], v[160:163], v[184:187], v[56:59]
	v_mfma_f32_16x16x32_bf16 v[48:51], v[144:147], v[192:195], v[48:51]
	v_mfma_f32_16x16x32_bf16 v[40:43], v[160:163], v[192:195], v[40:43]
	v_mfma_f32_16x16x32_bf16 v[32:35], v[144:147], v[200:203], v[32:35]
	v_mfma_f32_16x16x32_bf16 v[24:27], v[160:163], v[200:203], v[24:27]
	v_mfma_f32_16x16x32_bf16 v[16:19], v[144:147], v[208:211], v[16:19]
	v_mfma_f32_16x16x32_bf16 v[8:11], v[160:163], v[208:211], v[8:11]
	v_mfma_f32_16x16x32_bf16 v[60:63], v[156:159], v[188:191], v[60:63]
	v_mfma_f32_16x16x32_bf16 v[56:59], v[164:167], v[188:191], v[56:59]
	v_mfma_f32_16x16x32_bf16 v[48:51], v[156:159], v[196:199], v[48:51]
	v_mfma_f32_16x16x32_bf16 v[40:43], v[164:167], v[196:199], v[40:43]
	v_mfma_f32_16x16x32_bf16 v[32:35], v[156:159], v[204:207], v[32:35]
	v_mfma_f32_16x16x32_bf16 v[24:27], v[164:167], v[204:207], v[24:27]
	v_mfma_f32_16x16x32_bf16 v[16:19], v[156:159], v[212:215], v[16:19]
	v_mfma_f32_16x16x32_bf16 v[8:11], v[164:167], v[212:215], v[8:11]
	s_setprio 0
	s_setprio 1
	v_mfma_f32_16x16x32_bf16 v[52:55], v[168:171], v[184:187], v[52:55]
	v_mfma_f32_16x16x32_bf16 v[44:47], v[176:179], v[184:187], v[44:47]
	v_mfma_f32_16x16x32_bf16 v[36:39], v[168:171], v[192:195], v[36:39]
	v_mfma_f32_16x16x32_bf16 v[28:31], v[176:179], v[192:195], v[28:31]
	v_mfma_f32_16x16x32_bf16 v[20:23], v[168:171], v[200:203], v[20:23]
	v_mfma_f32_16x16x32_bf16 v[12:15], v[176:179], v[200:203], v[12:15]
	v_mfma_f32_16x16x32_bf16 v[4:7], v[168:171], v[208:211], v[4:7]
	v_mfma_f32_16x16x32_bf16 v[0:3], v[176:179], v[208:211], v[0:3]
	v_mfma_f32_16x16x32_bf16 v[52:55], v[172:175], v[188:191], v[52:55]
	v_mfma_f32_16x16x32_bf16 v[44:47], v[180:183], v[188:191], v[44:47]
	v_mfma_f32_16x16x32_bf16 v[36:39], v[172:175], v[196:199], v[36:39]
	v_mfma_f32_16x16x32_bf16 v[28:31], v[180:183], v[196:199], v[28:31]
	v_mfma_f32_16x16x32_bf16 v[20:23], v[172:175], v[204:207], v[20:23]
	v_mfma_f32_16x16x32_bf16 v[12:15], v[180:183], v[204:207], v[12:15]
	v_mfma_f32_16x16x32_bf16 v[4:7], v[172:175], v[212:215], v[4:7]
	v_mfma_f32_16x16x32_bf16 v[0:3], v[180:183], v[212:215], v[0:3]
	s_setprio 0
	s_barrier
	s_add_i32 s50, 0, 0x18000
	s_add_i32 s51, 0, 0x1c000
	v_add_u32_e32 v164, s50, v151
	v_add_u32_e32 v180, s51, v151
	ds_read_b128 v[144:147], v164
	ds_read_b128 v[156:159], v164 offset:1024
	ds_read_b128 v[160:163], v164 offset:2048
	ds_read_b128 v[164:167], v164 offset:3072
	ds_read_b128 v[168:171], v180
	ds_read_b128 v[172:175], v180 offset:1024
	ds_read_b128 v[176:179], v180 offset:2048
	ds_read_b128 v[180:183], v180 offset:3072
	v_lshl_add_u64 v[218:219], s[24:25], 0, v[128:129]
	s_mov_b32 m0, s34
	v_lshl_add_u64 v[220:221], s[24:25], 0, v[132:133]
	global_load_lds_dwordx4 v[218:219], off
	s_mov_b32 m0, s35
	s_nop 0
	global_load_lds_dwordx4 v[220:221], off
	s_add_u32 s18, s24, 0x160000
	s_addc_u32 s19, s25, 0
	s_mov_b32 m0, s36
	v_lshl_add_u64 v[222:223], s[18:19], 0, v[128:129]
	ds_read_b128 v[184:187], v155 offset:32768
	ds_read_b128 v[188:191], v155 offset:33792
	ds_read_b128 v[192:195], v155 offset:34816
	ds_read_b128 v[196:199], v155 offset:35840
	ds_read_b128 v[200:203], v155 offset:36864
	ds_read_b128 v[204:207], v155 offset:37888
	ds_read_b128 v[208:211], v155 offset:38912
	ds_read_b128 v[212:215], v155 offset:39936
	global_load_lds_dwordx4 v[222:223], off
	v_lshl_add_u64 v[222:223], s[18:19], 0, v[132:133]
	s_mov_b32 m0, s37
	s_nop 0
	global_load_lds_dwordx4 v[222:223], off
	s_waitcnt vmcnt(8)
	s_waitcnt lgkmcnt(0)
	s_barrier
; #define PG8_STAGE(bufoff, gbase, voff) do { _Pragma("unroll") for (int _i = 0; _i < 2; ++_i) \
;         __builtin_amdgcn_global_load_lds((const unsigned*)((const char*)(gbase) + (voff)[_i]), (PG8_LAS unsigned*)(lds + (bufoff) + ldsw + _i * 8192), 16, 0, 0); } while (0)
; #define PG8_LDA(dst, b, h) do { _Pragma("unroll") for (int m = 0; m < 4; ++m) _Pragma("unroll") for (int k = 0; k < 2; ++k) dst[m][k] = *(const PG8_LAS bf16x8*)(lds + PG8_SA(b, h) + aoff + m * 2048 + k * 1024); } while (0)
; #define PG8_LDB(dst, b, h) do { _Pragma("unroll") for (int n = 0; n < 2; ++n) _Pragma("unroll") for (int k = 0; k < 2; ++k) dst[n][k] = *(const PG8_LAS bf16x8*)(lds + PG8_SB(b, h) + boff + n * 2048 + k * 1024); } while (0)
; #define PG8_MMA(ai, bj, At, Bt) do { __builtin_amdgcn_s_setprio(1); _Pragma("unroll") for (int m = 0; m < 4; ++m) _Pragma("unroll") for (int n = 0; n < 2; ++n) _Pragma("unroll") for (int k = 0; k < 2; ++k) \
;         acc[ai][bj][m][n] = __builtin_amdgcn_mfma_f32_16x16x32_bf16(Bt[n][k], At[m][k], acc[ai][bj][m][n], 0, 0, 0); __builtin_amdgcn_s_setprio(0); } while (0)
; #define PG8_WAIT_V(n) asm volatile("s_waitcnt vmcnt(" #n ")" ::: "memory")
; #define PG8_WAIT_L(n) asm volatile("s_waitcnt lgkmcnt(" #n ")" ::: "memory")
; #define PG8_BAR __builtin_amdgcn_s_barrier()
; #define PG8_SCHED __builtin_amdgcn_sched_barrier(0)
; template <class Epi, class Sched, bool ALIGN_EPI = false, bool SP2 = false>
; __device__ __forceinline__ void gemm_phase(PG8_LAS unsigned char* lds, const Gemm g, const Sched& S, const Epi& E, const int wid  ) {
;     ...
;             PG8_LDB(B0, 1, 0); PG8_LDB(B1, 1, 1); PG8_SCHED; PG8_LDA(At, 1, 0); PG8_STAGE(PG8_SA(0, 1), a2 + hstep, voffA);
;             PG8_WAIT_V(8); PG8_WAIT_L(0); PG8_BAR; PG8_MMA(0, 0, At, B0); PG8_MMA(0, 1, At, B1); PG8_BAR; PG8_SCHED;
;             PG8_LDA(At, 1, 1); PG8_STAGE(PG8_SB(1, 0), b3, voffB); PG8_STAGE(PG8_SB(1, 1), b3 + hstep, voffB); PG8_STAGE(PG8_SA(1, 0), a3, voffA);
;             PG8_WAIT_V(8); PG8_WAIT_L(0); PG8_BAR; PG8_MMA(1, 0, At, B0); PG8_MMA(1, 1, At, B1); PG8_BAR; PG8_SCHED;
;     ...
;         if constexpr (ALIGN_EPI) { if (wr == 0) PG8_BAR; }
	s_setprio 1
	s_waitcnt lgkmcnt(0)
	v_mfma_f32_16x16x32_bf16 v[124:127], v[144:147], v[184:187], v[124:127]
	v_mfma_f32_16x16x32_bf16 v[120:123], v[160:163], v[184:187], v[120:123]
	v_mfma_f32_16x16x32_bf16 v[112:115], v[144:147], v[192:195], v[112:115]
	v_mfma_f32_16x16x32_bf16 v[104:107], v[160:163], v[192:195], v[104:107]
	v_mfma_f32_16x16x32_bf16 v[96:99], v[144:147], v[200:203], v[96:99]
	v_mfma_f32_16x16x32_bf16 v[88:91], v[160:163], v[200:203], v[88:91]
	v_mfma_f32_16x16x32_bf16 v[80:83], v[144:147], v[208:211], v[80:83]
	v_mfma_f32_16x16x32_bf16 v[72:75], v[160:163], v[208:211], v[72:75]
	v_mfma_f32_16x16x32_bf16 v[124:127], v[156:159], v[188:191], v[124:127]
	v_mfma_f32_16x16x32_bf16 v[120:123], v[164:167], v[188:191], v[120:123]
	v_mfma_f32_16x16x32_bf16 v[112:115], v[156:159], v[196:199], v[112:115]
	v_mfma_f32_16x16x32_bf16 v[104:107], v[164:167], v[196:199], v[104:107]
	v_mfma_f32_16x16x32_bf16 v[96:99], v[156:159], v[204:207], v[96:99]
	v_mfma_f32_16x16x32_bf16 v[88:91], v[164:167], v[204:207], v[88:91]
	v_mfma_f32_16x16x32_bf16 v[80:83], v[156:159], v[212:215], v[80:83]
	v_mfma_f32_16x16x32_bf16 v[72:75], v[164:167], v[212:215], v[72:75]
	s_setprio 0
	s_setprio 1
	v_mfma_f32_16x16x32_bf16 v[116:119], v[168:171], v[184:187], v[116:119]
	v_mfma_f32_16x16x32_bf16 v[108:111], v[176:179], v[184:187], v[108:111]
	v_mfma_f32_16x16x32_bf16 v[100:103], v[168:171], v[192:195], v[100:103]
	v_mfma_f32_16x16x32_bf16 v[92:95], v[176:179], v[192:195], v[92:95]
	v_mfma_f32_16x16x32_bf16 v[84:87], v[168:171], v[200:203], v[84:87]
	v_mfma_f32_16x16x32_bf16 v[76:79], v[176:179], v[200:203], v[76:79]
	v_mfma_f32_16x16x32_bf16 v[68:71], v[168:171], v[208:211], v[68:71]
	v_mfma_f32_16x16x32_bf16 v[64:67], v[176:179], v[208:211], v[64:67]
	v_mfma_f32_16x16x32_bf16 v[116:119], v[172:175], v[188:191], v[116:119]
	v_mfma_f32_16x16x32_bf16 v[108:111], v[180:183], v[188:191], v[108:111]
	v_mfma_f32_16x16x32_bf16 v[100:103], v[172:175], v[196:199], v[100:103]
	v_mfma_f32_16x16x32_bf16 v[92:95], v[180:183], v[196:199], v[92:95]
	v_mfma_f32_16x16x32_bf16 v[84:87], v[172:175], v[204:207], v[84:87]
	v_mfma_f32_16x16x32_bf16 v[76:79], v[180:183], v[204:207], v[76:79]
	v_mfma_f32_16x16x32_bf16 v[68:71], v[172:175], v[212:215], v[68:71]
	v_mfma_f32_16x16x32_bf16 v[64:67], v[180:183], v[212:215], v[64:67]
	s_setprio 0
	s_barrier
	s_add_i32 s18, s50, s31
	v_lshl_add_u64 v[148:149], v[148:149], 0, s[12:13]
	s_mov_b32 m0, s18
	ds_read_b128 v[184:187], v155 offset:49152
	ds_read_b128 v[188:191], v155 offset:50176
	ds_read_b128 v[192:195], v155 offset:51200
	ds_read_b128 v[196:199], v155 offset:52224
	ds_read_b128 v[200:203], v155 offset:53248
	ds_read_b128 v[204:207], v155 offset:54272
	ds_read_b128 v[208:211], v155 offset:55296
	ds_read_b128 v[212:215], v155 offset:56320
	global_load_lds_dwordx4 v[148:149], off
	s_add_i32 m0, s18, 0x2000
	s_add_u32 s18, s22, 0x160080
	v_lshl_add_u64 v[148:149], v[216:217], 0, s[12:13]
	s_addc_u32 s19, s23, 0
	s_add_i32 s22, s51, s31
	global_load_lds_dwordx4 v[148:149], off
	v_lshl_add_u64 v[148:149], s[18:19], 0, v[130:131]
	s_mov_b32 m0, s22
	s_nop 0
	global_load_lds_dwordx4 v[148:149], off
	v_lshl_add_u64 v[148:149], s[18:19], 0, v[134:135]
	s_add_i32 m0, s22, 0x2000
	s_nop 0
	global_load_lds_dwordx4 v[148:149], off
	s_waitcnt vmcnt(6)
	s_waitcnt lgkmcnt(0)
	s_barrier
	s_setprio 1
	s_waitcnt lgkmcnt(0)
	v_mfma_f32_16x16x32_bf16 v[60:63], v[144:147], v[184:187], v[60:63]
	v_mfma_f32_16x16x32_bf16 v[56:59], v[160:163], v[184:187], v[56:59]
	v_mfma_f32_16x16x32_bf16 v[48:51], v[144:147], v[192:195], v[48:51]
	v_mfma_f32_16x16x32_bf16 v[40:43], v[160:163], v[192:195], v[40:43]
	v_mfma_f32_16x16x32_bf16 v[32:35], v[144:147], v[200:203], v[32:35]
	v_mfma_f32_16x16x32_bf16 v[24:27], v[160:163], v[200:203], v[24:27]
	v_mfma_f32_16x16x32_bf16 v[16:19], v[144:147], v[208:211], v[16:19]
	v_mfma_f32_16x16x32_bf16 v[8:11], v[160:163], v[208:211], v[8:11]
	v_mfma_f32_16x16x32_bf16 v[60:63], v[156:159], v[188:191], v[60:63]
	v_mfma_f32_16x16x32_bf16 v[56:59], v[164:167], v[188:191], v[56:59]
	v_mfma_f32_16x16x32_bf16 v[48:51], v[156:159], v[196:199], v[48:51]
	v_mfma_f32_16x16x32_bf16 v[40:43], v[164:167], v[196:199], v[40:43]
	v_mfma_f32_16x16x32_bf16 v[32:35], v[156:159], v[204:207], v[32:35]
	v_mfma_f32_16x16x32_bf16 v[24:27], v[164:167], v[204:207], v[24:27]
	v_mfma_f32_16x16x32_bf16 v[16:19], v[156:159], v[212:215], v[16:19]
	v_mfma_f32_16x16x32_bf16 v[8:11], v[164:167], v[212:215], v[8:11]
	s_setprio 0
	s_setprio 1
	v_mfma_f32_16x16x32_bf16 v[52:55], v[168:171], v[184:187], v[52:55]
	v_mfma_f32_16x16x32_bf16 v[44:47], v[176:179], v[184:187], v[44:47]
	v_mfma_f32_16x16x32_bf16 v[36:39], v[168:171], v[192:195], v[36:39]
	v_mfma_f32_16x16x32_bf16 v[28:31], v[176:179], v[192:195], v[28:31]
	v_mfma_f32_16x16x32_bf16 v[20:23], v[168:171], v[200:203], v[20:23]
	v_mfma_f32_16x16x32_bf16 v[12:15], v[176:179], v[200:203], v[12:15]
	v_mfma_f32_16x16x32_bf16 v[4:7], v[168:171], v[208:211], v[4:7]
	v_mfma_f32_16x16x32_bf16 v[0:3], v[176:179], v[208:211], v[0:3]
	v_mfma_f32_16x16x32_bf16 v[52:55], v[172:175], v[188:191], v[52:55]
	v_mfma_f32_16x16x32_bf16 v[44:47], v[180:183], v[188:191], v[44:47]
	v_mfma_f32_16x16x32_bf16 v[36:39], v[172:175], v[196:199], v[36:39]
	v_mfma_f32_16x16x32_bf16 v[28:31], v[180:183], v[196:199], v[28:31]
	v_mfma_f32_16x16x32_bf16 v[20:23], v[172:175], v[204:207], v[20:23]
	v_mfma_f32_16x16x32_bf16 v[12:15], v[180:183], v[204:207], v[12:15]
	v_mfma_f32_16x16x32_bf16 v[4:7], v[172:175], v[212:215], v[4:7]
	v_mfma_f32_16x16x32_bf16 v[0:3], v[180:183], v[212:215], v[0:3]
	s_setprio 0
	s_add_i32 s49, s49, 2
	s_add_u32 s47, s47, 0x100
	s_addc_u32 s48, s48, 0
	s_cmpk_gt_u32 s49, 0x55
	s_mov_b64 s[18:19], s[20:21]
	s_barrier
	s_cbranch_scc0 .LBB0_5850
	s_and_b64 vcc, exec, s[14:15]
	s_cbranch_vccz .LBB0_5853
	s_barrier
